# v12 + MFMA accumulator-pair order with weight-fragment reuse between consecutive pairs
# speedup vs baseline: 1.0149x; 1.0149x over previous
; #define PG8_STAGE(bufoff, gbase, voff) do { _Pragma("unroll") for (int _i = 0; _i < 2; ++_i) \
;         __builtin_amdgcn_global_load_lds((const unsigned*)((const char*)(gbase) + (voff)[_i]), (PG8_LAS unsigned*)(lds + (bufoff) + ldsw + _i * 8192), 16, 0, 0); } while (0)
; #define PG8_LDA(dst, b, h) do { _Pragma("unroll") for (int m = 0; m < 4; ++m) _Pragma("unroll") for (int k = 0; k < 2; ++k) dst[m][k] = *(const PG8_LAS bf16x8*)(lds + PG8_SA(b, h) + aoff + m * 2048 + k * 1024); } while (0)
; #define PG8_LDB(dst, b, h) do { _Pragma("unroll") for (int n = 0; n < 2; ++n) _Pragma("unroll") for (int k = 0; k < 2; ++k) dst[n][k] = *(const PG8_LAS bf16x8*)(lds + PG8_SB(b, h) + boff + n * 2048 + k * 1024); } while (0)
; #define PG8_MMA(ai, bj, At, Bt) do { __builtin_amdgcn_s_setprio(1); _Pragma("unroll") for (int m = 0; m < 4; ++m) _Pragma("unroll") for (int n = 0; n < 2; ++n) _Pragma("unroll") for (int k = 0; k < 2; ++k) \
;         acc[ai][bj][m][n] = __builtin_amdgcn_mfma_f32_16x16x32_bf16(Bt[n][k], At[m][k], acc[ai][bj][m][n], 0, 0, 0); __builtin_amdgcn_s_setprio(0); } while (0)
; #define PG8_WAIT_V(n) asm volatile("s_waitcnt vmcnt(" #n ")" ::: "memory")
; #define PG8_WAIT_L(n) asm volatile("s_waitcnt lgkmcnt(" #n ")" ::: "memory")
; template <class Epi, class Sched, bool ALIGN_EPI = false, bool SP2 = false>
; __device__ __forceinline__ void gemm_phase(PG8_LAS unsigned char* lds, const Gemm g, const Sched& S, const Epi& E) {
;     ...
;             const bool last = (t == nt - 2);
;             const char* a1 = cA + (size_t)(t + 1) * kstep;
;             const char* a2 = last ? nA : cA + (size_t)(t + 2) * kstep; const char* b2 = last ? nB : cB + (size_t)(t + 2) * kstep;
;             const char* a3 = a2 + kstep; const char* b3 = b2 + kstep;
;             if (last && has_next) S.a_ready(nxt);
;             if constexpr (SP2) {
;             PG8_LDB(B0, 0, 0); PG8_LDB(B1, 0, 1); PG8_SCHED; PG8_LDA(At, 0, 0); PG8_STAGE(PG8_SA(1, 1), a1 + hstep, voffA);
;             PG8_WAIT_V(8); PG8_WAIT_L(0); PG8_BAR; PG8_MMA(0, 0, At, B0); PG8_MMA(0, 1, At, B1); PG8_BAR; PG8_SCHED;
;             PG8_LDA(At, 0, 1); PG8_STAGE(PG8_SB(0, 0), b2, voffB); PG8_STAGE(PG8_SB(0, 1), b2 + hstep, voffB); PG8_STAGE(PG8_SA(0, 0), a2, voffA);
;             PG8_WAIT_V(8); PG8_WAIT_L(0); PG8_BAR; PG8_MMA(1, 0, At, B0); PG8_MMA(1, 1, At, B1); PG8_BAR; PG8_SCHED;
.LBB0_202:
	s_add_i32 s78, s38, 2
	s_add_u32 s79, s22, 0x80
	s_addc_u32 s39, s23, 0
	s_cmp_eq_u32 s33, s38
	s_cselect_b32 s39, s7, s39
	s_cselect_b32 s38, s6, s79
	v_add_u32_e32 v0, s19, v150
	s_cselect_b32 s81, s17, s77
	s_cselect_b32 s80, s16, s76
	s_add_i32 s79, 0, 0x14000
	ds_read_b128 v[152:155], v0
	ds_read_b128 v[156:159], v0 offset:1024
	ds_read_b128 v[160:163], v0 offset:2048
	ds_read_b128 v[164:167], v0 offset:3072
	v_add_u32_e32 v0, s79, v150
	ds_read_b128 v[168:171], v0
	ds_read_b128 v[172:175], v0 offset:1024
	ds_read_b128 v[176:179], v0 offset:2048
	ds_read_b128 v[184:187], v0 offset:3072
	v_lshl_add_u64 v[2:3], s[22:23], 0, v[144:145]
	s_add_i32 m0, s42, 0xc000
	ds_read_b128 v[188:191], v151
	ds_read_b128 v[192:195], v151 offset:1024
	ds_read_b128 v[196:199], v151 offset:2048
	ds_read_b128 v[200:203], v151 offset:3072
	ds_read_b128 v[204:207], v151 offset:4096
	ds_read_b128 v[230:233], v151 offset:5120
	ds_read_b128 v[234:237], v151 offset:6144
	ds_read_b128 v[238:241], v151 offset:7168
	global_load_lds_dwordx4 v[2:3], off
	v_lshl_add_u64 v[2:3], s[22:23], 0, v[146:147]
	s_add_i32 m0, s42, 0xe000
	s_nop 0
	global_load_lds_dwordx4 v[2:3], off
	s_waitcnt vmcnt(8)
	s_waitcnt lgkmcnt(0)
	s_barrier
	s_setprio 1
	s_waitcnt lgkmcnt(0)
	v_mfma_f32_16x16x32_bf16 v[132:135], v[152:155], v[188:191], v[132:135]
	v_mfma_f32_16x16x32_bf16 v[132:135], v[156:159], v[192:195], v[132:135]
	v_mfma_f32_16x16x32_bf16 v[116:119], v[152:155], v[196:199], v[116:119]
	v_mfma_f32_16x16x32_bf16 v[116:119], v[156:159], v[200:203], v[116:119]
	v_mfma_f32_16x16x32_bf16 v[100:103], v[152:155], v[204:207], v[100:103]
	v_mfma_f32_16x16x32_bf16 v[100:103], v[156:159], v[230:233], v[100:103]
	v_mfma_f32_16x16x32_bf16 v[84:87], v[152:155], v[234:237], v[84:87]
	v_mfma_f32_16x16x32_bf16 v[84:87], v[156:159], v[238:241], v[84:87]
	v_mfma_f32_16x16x32_bf16 v[80:83], v[160:163], v[234:237], v[80:83]
	v_mfma_f32_16x16x32_bf16 v[80:83], v[164:167], v[238:241], v[80:83]
	v_mfma_f32_16x16x32_bf16 v[96:99], v[160:163], v[204:207], v[96:99]
	v_mfma_f32_16x16x32_bf16 v[96:99], v[164:167], v[230:233], v[96:99]
	v_mfma_f32_16x16x32_bf16 v[112:115], v[160:163], v[196:199], v[112:115]
	v_mfma_f32_16x16x32_bf16 v[112:115], v[164:167], v[200:203], v[112:115]
	v_mfma_f32_16x16x32_bf16 v[128:131], v[160:163], v[188:191], v[128:131]
	v_mfma_f32_16x16x32_bf16 v[128:131], v[164:167], v[192:195], v[128:131]
	s_setprio 0
	s_setprio 1
	v_mfma_f32_16x16x32_bf16 v[124:127], v[168:171], v[188:191], v[124:127]
	v_mfma_f32_16x16x32_bf16 v[124:127], v[172:175], v[192:195], v[124:127]
	v_mfma_f32_16x16x32_bf16 v[108:111], v[168:171], v[196:199], v[108:111]
	v_mfma_f32_16x16x32_bf16 v[108:111], v[172:175], v[200:203], v[108:111]
	v_mfma_f32_16x16x32_bf16 v[92:95], v[168:171], v[204:207], v[92:95]
	v_mfma_f32_16x16x32_bf16 v[92:95], v[172:175], v[230:233], v[92:95]
	v_mfma_f32_16x16x32_bf16 v[76:79], v[168:171], v[234:237], v[76:79]
	v_mfma_f32_16x16x32_bf16 v[76:79], v[172:175], v[238:241], v[76:79]
	v_mfma_f32_16x16x32_bf16 v[72:75], v[176:179], v[234:237], v[72:75]
	v_mfma_f32_16x16x32_bf16 v[72:75], v[184:187], v[238:241], v[72:75]
	v_mfma_f32_16x16x32_bf16 v[88:91], v[176:179], v[204:207], v[88:91]
	v_mfma_f32_16x16x32_bf16 v[88:91], v[184:187], v[230:233], v[88:91]
	v_mfma_f32_16x16x32_bf16 v[104:107], v[176:179], v[196:199], v[104:107]
	v_mfma_f32_16x16x32_bf16 v[104:107], v[184:187], v[200:203], v[104:107]
	v_mfma_f32_16x16x32_bf16 v[120:123], v[176:179], v[188:191], v[120:123]
	v_mfma_f32_16x16x32_bf16 v[120:123], v[184:187], v[192:195], v[120:123]
	s_setprio 0
	s_barrier
	s_add_i32 s82, s19, s20
	v_lshl_add_u64 v[2:3], s[80:81], 0, v[140:141]
	s_mov_b32 m0, s82
	ds_read_b128 v[188:191], v151 offset:16384
	ds_read_b128 v[192:195], v151 offset:17408
	ds_read_b128 v[196:199], v151 offset:18432
	ds_read_b128 v[200:203], v151 offset:19456
	ds_read_b128 v[204:207], v151 offset:20480
	ds_read_b128 v[230:233], v151 offset:21504
	ds_read_b128 v[234:237], v151 offset:22528
	ds_read_b128 v[238:241], v151 offset:23552
	global_load_lds_dwordx4 v[2:3], off
	s_add_i32 m0, s82, 0x2000
	v_lshl_add_u64 v[180:181], s[80:81], 0, v[136:137]
	s_add_u32 s80, s80, s48
	s_addc_u32 s81, s81, s49
	s_add_i32 s79, s79, s20
	global_load_lds_dwordx4 v[180:181], off
	v_lshl_add_u64 v[208:209], s[80:81], 0, v[140:141]
	s_mov_b32 m0, s79
	v_lshl_add_u64 v[216:217], s[80:81], 0, v[136:137]
	global_load_lds_dwordx4 v[208:209], off
	s_add_i32 m0, s79, 0x2000
	v_lshl_add_u64 v[224:225], s[38:39], 0, v[142:143]
	global_load_lds_dwordx4 v[216:217], off
	s_mov_b32 m0, s42
	v_lshl_add_u64 v[226:227], s[38:39], 0, v[138:139]
	global_load_lds_dwordx4 v[224:225], off
	s_mov_b32 m0, s45
	s_nop 0
	global_load_lds_dwordx4 v[226:227], off
	s_waitcnt vmcnt(8)
	s_waitcnt lgkmcnt(0)
	s_barrier
; #define PG8_STAGE(bufoff, gbase, voff) do { _Pragma("unroll") for (int _i = 0; _i < 2; ++_i) \
;         __builtin_amdgcn_global_load_lds((const unsigned*)((const char*)(gbase) + (voff)[_i]), (PG8_LAS unsigned*)(lds + (bufoff) + ldsw + _i * 8192), 16, 0, 0); } while (0)
; #define PG8_LDA(dst, b, h) do { _Pragma("unroll") for (int m = 0; m < 4; ++m) _Pragma("unroll") for (int k = 0; k < 2; ++k) dst[m][k] = *(const PG8_LAS bf16x8*)(lds + PG8_SA(b, h) + aoff + m * 2048 + k * 1024); } while (0)
; #define PG8_LDB(dst, b, h) do { _Pragma("unroll") for (int n = 0; n < 2; ++n) _Pragma("unroll") for (int k = 0; k < 2; ++k) dst[n][k] = *(const PG8_LAS bf16x8*)(lds + PG8_SB(b, h) + boff + n * 2048 + k * 1024); } while (0)
; #define PG8_MMA(ai, bj, At, Bt) do { __builtin_amdgcn_s_setprio(1); _Pragma("unroll") for (int m = 0; m < 4; ++m) _Pragma("unroll") for (int n = 0; n < 2; ++n) _Pragma("unroll") for (int k = 0; k < 2; ++k) \
;         acc[ai][bj][m][n] = __builtin_amdgcn_mfma_f32_16x16x32_bf16(Bt[n][k], At[m][k], acc[ai][bj][m][n], 0, 0, 0); __builtin_amdgcn_s_setprio(0); } while (0)
; #define PG8_WAIT_V(n) asm volatile("s_waitcnt vmcnt(" #n ")" ::: "memory")
; #define PG8_WAIT_L(n) asm volatile("s_waitcnt lgkmcnt(" #n ")" ::: "memory")
; #define PG8_BAR __builtin_amdgcn_s_barrier()
; #define PG8_SCHED __builtin_amdgcn_sched_barrier(0)
; template <class Epi, class Sched, bool ALIGN_EPI = false, bool SP2 = false>
; __device__ __forceinline__ void gemm_phase(PG8_LAS unsigned char* lds, const Gemm g, const Sched& S, const Epi& E) {
;     ...
;             PG8_WAIT_V(8); PG8_WAIT_L(0); PG8_BAR; PG8_MMA(1, 0, At, B0); PG8_MMA(1, 1, At, B1); PG8_BAR; PG8_SCHED;
;             PG8_LDB(B0, 1, 0); PG8_LDB(B1, 1, 1); PG8_SCHED; PG8_LDA(At, 1, 0); PG8_STAGE(PG8_SA(0, 1), a2 + hstep, voffA);
;             PG8_WAIT_V(8); PG8_WAIT_L(0); PG8_BAR; PG8_MMA(0, 0, At, B0); PG8_MMA(0, 1, At, B1); PG8_BAR; PG8_SCHED;
	s_setprio 1
	s_waitcnt lgkmcnt(0)
	v_mfma_f32_16x16x32_bf16 v[68:71], v[152:155], v[188:191], v[68:71]
	v_mfma_f32_16x16x32_bf16 v[68:71], v[156:159], v[192:195], v[68:71]
	v_mfma_f32_16x16x32_bf16 v[52:55], v[152:155], v[196:199], v[52:55]
	v_mfma_f32_16x16x32_bf16 v[52:55], v[156:159], v[200:203], v[52:55]
	v_mfma_f32_16x16x32_bf16 v[36:39], v[152:155], v[204:207], v[36:39]
	v_mfma_f32_16x16x32_bf16 v[36:39], v[156:159], v[230:233], v[36:39]
	v_mfma_f32_16x16x32_bf16 v[20:23], v[152:155], v[234:237], v[20:23]
	v_mfma_f32_16x16x32_bf16 v[20:23], v[156:159], v[238:241], v[20:23]
	v_mfma_f32_16x16x32_bf16 v[16:19], v[160:163], v[234:237], v[16:19]
	v_mfma_f32_16x16x32_bf16 v[16:19], v[164:167], v[238:241], v[16:19]
	v_mfma_f32_16x16x32_bf16 v[32:35], v[160:163], v[204:207], v[32:35]
	v_mfma_f32_16x16x32_bf16 v[32:35], v[164:167], v[230:233], v[32:35]
	v_mfma_f32_16x16x32_bf16 v[48:51], v[160:163], v[196:199], v[48:51]
	v_mfma_f32_16x16x32_bf16 v[48:51], v[164:167], v[200:203], v[48:51]
	v_mfma_f32_16x16x32_bf16 v[64:67], v[160:163], v[188:191], v[64:67]
	v_mfma_f32_16x16x32_bf16 v[64:67], v[164:167], v[192:195], v[64:67]
	s_setprio 0
	s_setprio 1
	v_mfma_f32_16x16x32_bf16 v[60:63], v[168:171], v[188:191], v[60:63]
	v_mfma_f32_16x16x32_bf16 v[60:63], v[172:175], v[192:195], v[60:63]
	v_mfma_f32_16x16x32_bf16 v[44:47], v[168:171], v[196:199], v[44:47]
	v_mfma_f32_16x16x32_bf16 v[44:47], v[172:175], v[200:203], v[44:47]
	v_mfma_f32_16x16x32_bf16 v[28:31], v[168:171], v[204:207], v[28:31]
	v_mfma_f32_16x16x32_bf16 v[28:31], v[172:175], v[230:233], v[28:31]
	v_mfma_f32_16x16x32_bf16 v[12:15], v[168:171], v[234:237], v[12:15]
	v_mfma_f32_16x16x32_bf16 v[12:15], v[172:175], v[238:241], v[12:15]
	v_mfma_f32_16x16x32_bf16 v[8:11], v[176:179], v[234:237], v[8:11]
	v_mfma_f32_16x16x32_bf16 v[8:11], v[184:187], v[238:241], v[8:11]
	v_mfma_f32_16x16x32_bf16 v[24:27], v[176:179], v[204:207], v[24:27]
	v_mfma_f32_16x16x32_bf16 v[24:27], v[184:187], v[230:233], v[24:27]
	v_mfma_f32_16x16x32_bf16 v[40:43], v[176:179], v[196:199], v[40:43]
	v_mfma_f32_16x16x32_bf16 v[40:43], v[184:187], v[200:203], v[40:43]
	v_mfma_f32_16x16x32_bf16 v[56:59], v[176:179], v[188:191], v[56:59]
	v_mfma_f32_16x16x32_bf16 v[56:59], v[184:187], v[192:195], v[56:59]
	s_setprio 0
	s_barrier
	v_add_u32_e32 v0, s91, v150
	s_add_i32 s79, 0, 0x1c000
	ds_read_b128 v[152:155], v0
	ds_read_b128 v[156:159], v0 offset:1024
	ds_read_b128 v[160:163], v0 offset:2048
	ds_read_b128 v[164:167], v0 offset:3072
	v_add_u32_e32 v0, s79, v150
	ds_read_b128 v[168:171], v0
	ds_read_b128 v[172:175], v0 offset:1024
	ds_read_b128 v[176:179], v0 offset:2048
	ds_read_b128 v[184:187], v0 offset:3072
	s_add_u32 s38, s38, s48
	s_addc_u32 s39, s39, s49
	s_mov_b32 m0, s46
	v_lshl_add_u64 v[228:229], s[38:39], 0, v[142:143]
	ds_read_b128 v[188:191], v151 offset:32768
	ds_read_b128 v[192:195], v151 offset:33792
	ds_read_b128 v[196:199], v151 offset:34816
	ds_read_b128 v[200:203], v151 offset:35840
	ds_read_b128 v[204:207], v151 offset:36864
	ds_read_b128 v[230:233], v151 offset:37888
	ds_read_b128 v[234:237], v151 offset:38912
	ds_read_b128 v[238:241], v151 offset:39936
	global_load_lds_dwordx4 v[228:229], off
	v_lshl_add_u64 v[228:229], s[38:39], 0, v[138:139]
	s_mov_b32 m0, s47
	s_nop 0
	global_load_lds_dwordx4 v[228:229], off
	s_waitcnt vmcnt(8)
	s_waitcnt lgkmcnt(0)
	s_barrier
	s_setprio 1
	s_waitcnt lgkmcnt(0)
	v_mfma_f32_16x16x32_bf16 v[132:135], v[152:155], v[188:191], v[132:135]
	v_mfma_f32_16x16x32_bf16 v[132:135], v[156:159], v[192:195], v[132:135]
	v_mfma_f32_16x16x32_bf16 v[116:119], v[152:155], v[196:199], v[116:119]
	v_mfma_f32_16x16x32_bf16 v[116:119], v[156:159], v[200:203], v[116:119]
	v_mfma_f32_16x16x32_bf16 v[100:103], v[152:155], v[204:207], v[100:103]
	v_mfma_f32_16x16x32_bf16 v[100:103], v[156:159], v[230:233], v[100:103]
	v_mfma_f32_16x16x32_bf16 v[84:87], v[152:155], v[234:237], v[84:87]
	v_mfma_f32_16x16x32_bf16 v[84:87], v[156:159], v[238:241], v[84:87]
	v_mfma_f32_16x16x32_bf16 v[80:83], v[160:163], v[234:237], v[80:83]
	v_mfma_f32_16x16x32_bf16 v[80:83], v[164:167], v[238:241], v[80:83]
	v_mfma_f32_16x16x32_bf16 v[96:99], v[160:163], v[204:207], v[96:99]
	v_mfma_f32_16x16x32_bf16 v[96:99], v[164:167], v[230:233], v[96:99]
	v_mfma_f32_16x16x32_bf16 v[112:115], v[160:163], v[196:199], v[112:115]
	v_mfma_f32_16x16x32_bf16 v[112:115], v[164:167], v[200:203], v[112:115]
	v_mfma_f32_16x16x32_bf16 v[128:131], v[160:163], v[188:191], v[128:131]
	v_mfma_f32_16x16x32_bf16 v[128:131], v[164:167], v[192:195], v[128:131]
	s_setprio 0
	s_setprio 1
	v_mfma_f32_16x16x32_bf16 v[124:127], v[168:171], v[188:191], v[124:127]
	v_mfma_f32_16x16x32_bf16 v[124:127], v[172:175], v[192:195], v[124:127]
	v_mfma_f32_16x16x32_bf16 v[108:111], v[168:171], v[196:199], v[108:111]
	v_mfma_f32_16x16x32_bf16 v[108:111], v[172:175], v[200:203], v[108:111]
	v_mfma_f32_16x16x32_bf16 v[92:95], v[168:171], v[204:207], v[92:95]
	v_mfma_f32_16x16x32_bf16 v[92:95], v[172:175], v[230:233], v[92:95]
	v_mfma_f32_16x16x32_bf16 v[76:79], v[168:171], v[234:237], v[76:79]
	v_mfma_f32_16x16x32_bf16 v[76:79], v[172:175], v[238:241], v[76:79]
	v_mfma_f32_16x16x32_bf16 v[72:75], v[176:179], v[234:237], v[72:75]
	v_mfma_f32_16x16x32_bf16 v[72:75], v[184:187], v[238:241], v[72:75]
	v_mfma_f32_16x16x32_bf16 v[88:91], v[176:179], v[204:207], v[88:91]
	v_mfma_f32_16x16x32_bf16 v[88:91], v[184:187], v[230:233], v[88:91]
	v_mfma_f32_16x16x32_bf16 v[104:107], v[176:179], v[196:199], v[104:107]
	v_mfma_f32_16x16x32_bf16 v[104:107], v[184:187], v[200:203], v[104:107]
	v_mfma_f32_16x16x32_bf16 v[120:123], v[176:179], v[188:191], v[120:123]
	v_mfma_f32_16x16x32_bf16 v[120:123], v[184:187], v[192:195], v[120:123]
	s_setprio 0
	s_barrier
; #define PG8_STAGE(bufoff, gbase, voff) do { _Pragma("unroll") for (int _i = 0; _i < 2; ++_i) \
;         __builtin_amdgcn_global_load_lds((const unsigned*)((const char*)(gbase) + (voff)[_i]), (PG8_LAS unsigned*)(lds + (bufoff) + ldsw + _i * 8192), 16, 0, 0); } while (0)
; #define PG8_LDA(dst, b, h) do { _Pragma("unroll") for (int m = 0; m < 4; ++m) _Pragma("unroll") for (int k = 0; k < 2; ++k) dst[m][k] = *(const PG8_LAS bf16x8*)(lds + PG8_SA(b, h) + aoff + m * 2048 + k * 1024); } while (0)
; #define PG8_MMA(ai, bj, At, Bt) do { __builtin_amdgcn_s_setprio(1); _Pragma("unroll") for (int m = 0; m < 4; ++m) _Pragma("unroll") for (int n = 0; n < 2; ++n) _Pragma("unroll") for (int k = 0; k < 2; ++k) \
;         acc[ai][bj][m][n] = __builtin_amdgcn_mfma_f32_16x16x32_bf16(Bt[n][k], At[m][k], acc[ai][bj][m][n], 0, 0, 0); __builtin_amdgcn_s_setprio(0); } while (0)
; #define PG8_WAIT_V(n) asm volatile("s_waitcnt vmcnt(" #n ")" ::: "memory")
; #define PG8_WAIT_L(n) asm volatile("s_waitcnt lgkmcnt(" #n ")" ::: "memory")
; #define PG8_BAR __builtin_amdgcn_s_barrier()
; #define PG8_SCHED __builtin_amdgcn_sched_barrier(0)
; template <class Epi, class Sched, bool ALIGN_EPI = false, bool SP2 = false>
; __device__ __forceinline__ void gemm_phase(PG8_LAS unsigned char* lds, const Gemm g, const Sched& S, const Epi& E) {
;     ...
;             PG8_LDA(At, 1, 1); PG8_STAGE(PG8_SB(1, 0), b3, voffB); PG8_STAGE(PG8_SB(1, 1), b3 + hstep, voffB); PG8_STAGE(PG8_SA(1, 0), a3, voffA);
;             PG8_WAIT_V(8); PG8_WAIT_L(0); PG8_BAR; PG8_MMA(1, 0, At, B0); PG8_MMA(1, 1, At, B1); PG8_BAR; PG8_SCHED;
	s_add_i32 s38, s91, s20
	v_lshl_add_u64 v[2:3], v[2:3], 0, s[24:25]
	s_mov_b32 m0, s38
	ds_read_b128 v[188:191], v151 offset:49152
	ds_read_b128 v[192:195], v151 offset:50176
	ds_read_b128 v[196:199], v151 offset:51200
	ds_read_b128 v[200:203], v151 offset:52224
	ds_read_b128 v[204:207], v151 offset:53248
	ds_read_b128 v[230:233], v151 offset:54272
	ds_read_b128 v[234:237], v151 offset:55296
	ds_read_b128 v[238:241], v151 offset:56320
	global_load_lds_dwordx4 v[2:3], off
	v_lshl_add_u64 v[2:3], v[180:181], 0, s[24:25]
	s_add_i32 m0, s38, 0x2000
	s_add_i32 s38, s79, s20
	global_load_lds_dwordx4 v[2:3], off
	v_lshl_add_u64 v[2:3], v[208:209], 0, s[24:25]
	s_mov_b32 m0, s38
	s_nop 0
	global_load_lds_dwordx4 v[2:3], off
	v_lshl_add_u64 v[2:3], v[216:217], 0, s[24:25]
	s_add_i32 m0, s38, 0x2000
	s_nop 0
	global_load_lds_dwordx4 v[2:3], off
	v_lshl_add_u64 v[2:3], v[224:225], 0, s[24:25]
	s_mov_b32 m0, s52
	s_nop 0
	global_load_lds_dwordx4 v[2:3], off
	v_lshl_add_u64 v[2:3], v[226:227], 0, s[24:25]
	s_mov_b32 m0, s53
	s_nop 0
	global_load_lds_dwordx4 v[2:3], off
	s_waitcnt vmcnt(8)
	s_waitcnt lgkmcnt(0)
	s_barrier
	s_setprio 1
	s_waitcnt lgkmcnt(0)
	v_mfma_f32_16x16x32_bf16 v[68:71], v[152:155], v[188:191], v[68:71]
	v_mfma_f32_16x16x32_bf16 v[68:71], v[156:159], v[192:195], v[68:71]
	v_mfma_f32_16x16x32_bf16 v[52:55], v[152:155], v[196:199], v[52:55]
	v_mfma_f32_16x16x32_bf16 v[52:55], v[156:159], v[200:203], v[52:55]
	v_mfma_f32_16x16x32_bf16 v[36:39], v[152:155], v[204:207], v[36:39]
	v_mfma_f32_16x16x32_bf16 v[36:39], v[156:159], v[230:233], v[36:39]
	v_mfma_f32_16x16x32_bf16 v[20:23], v[152:155], v[234:237], v[20:23]
	v_mfma_f32_16x16x32_bf16 v[20:23], v[156:159], v[238:241], v[20:23]
	v_mfma_f32_16x16x32_bf16 v[16:19], v[160:163], v[234:237], v[16:19]
	v_mfma_f32_16x16x32_bf16 v[16:19], v[164:167], v[238:241], v[16:19]
	v_mfma_f32_16x16x32_bf16 v[32:35], v[160:163], v[204:207], v[32:35]
	v_mfma_f32_16x16x32_bf16 v[32:35], v[164:167], v[230:233], v[32:35]
	v_mfma_f32_16x16x32_bf16 v[48:51], v[160:163], v[196:199], v[48:51]
	v_mfma_f32_16x16x32_bf16 v[48:51], v[164:167], v[200:203], v[48:51]
	v_mfma_f32_16x16x32_bf16 v[64:67], v[160:163], v[188:191], v[64:67]
	v_mfma_f32_16x16x32_bf16 v[64:67], v[164:167], v[192:195], v[64:67]
	s_setprio 0
	s_setprio 1
	v_mfma_f32_16x16x32_bf16 v[60:63], v[168:171], v[188:191], v[60:63]
	v_mfma_f32_16x16x32_bf16 v[60:63], v[172:175], v[192:195], v[60:63]
	v_mfma_f32_16x16x32_bf16 v[44:47], v[168:171], v[196:199], v[44:47]
	v_mfma_f32_16x16x32_bf16 v[44:47], v[172:175], v[200:203], v[44:47]
	v_mfma_f32_16x16x32_bf16 v[28:31], v[168:171], v[204:207], v[28:31]
	v_mfma_f32_16x16x32_bf16 v[28:31], v[172:175], v[230:233], v[28:31]
	v_mfma_f32_16x16x32_bf16 v[12:15], v[168:171], v[234:237], v[12:15]
	v_mfma_f32_16x16x32_bf16 v[12:15], v[172:175], v[238:241], v[12:15]
	v_mfma_f32_16x16x32_bf16 v[8:11], v[176:179], v[234:237], v[8:11]
	v_mfma_f32_16x16x32_bf16 v[8:11], v[184:187], v[238:241], v[8:11]
	v_mfma_f32_16x16x32_bf16 v[24:27], v[176:179], v[204:207], v[24:27]
	v_mfma_f32_16x16x32_bf16 v[24:27], v[184:187], v[230:233], v[24:27]
	v_mfma_f32_16x16x32_bf16 v[40:43], v[176:179], v[196:199], v[40:43]
	v_mfma_f32_16x16x32_bf16 v[40:43], v[184:187], v[200:203], v[40:43]
	v_mfma_f32_16x16x32_bf16 v[56:59], v[176:179], v[188:191], v[56:59]
	v_mfma_f32_16x16x32_bf16 v[56:59], v[184:187], v[192:195], v[56:59]
	s_setprio 0
	s_barrier
	s_add_u32 s22, s22, 0x100
	s_addc_u32 s23, s23, 0
	s_add_u32 s76, s76, 0x100
	s_addc_u32 s77, s77, 0
	s_cmp_ge_u32 s78, s9
	s_mov_b32 s38, s78
	s_cbranch_scc0 .LBB0_202

; #define PG8_STAGE(bufoff, gbase, voff) do { _Pragma("unroll") for (int _i = 0; _i < 2; ++_i) \
;         __builtin_amdgcn_global_load_lds((const unsigned*)((const char*)(gbase) + (voff)[_i]), (PG8_LAS unsigned*)(lds + (bufoff) + ldsw + _i * 8192), 16, 0, 0); } while (0)
; #define PG8_LDA(dst, b, h) do { _Pragma("unroll") for (int m = 0; m < 4; ++m) _Pragma("unroll") for (int k = 0; k < 2; ++k) dst[m][k] = *(const PG8_LAS bf16x8*)(lds + PG8_SA(b, h) + aoff + m * 2048 + k * 1024); } while (0)
; #define PG8_LDB(dst, b, h) do { _Pragma("unroll") for (int n = 0; n < 2; ++n) _Pragma("unroll") for (int k = 0; k < 2; ++k) dst[n][k] = *(const PG8_LAS bf16x8*)(lds + PG8_SB(b, h) + boff + n * 2048 + k * 1024); } while (0)
; #define PG8_MMA(ai, bj, At, Bt) do { __builtin_amdgcn_s_setprio(1); _Pragma("unroll") for (int m = 0; m < 4; ++m) _Pragma("unroll") for (int n = 0; n < 2; ++n) _Pragma("unroll") for (int k = 0; k < 2; ++k) \
;         acc[ai][bj][m][n] = __builtin_amdgcn_mfma_f32_16x16x32_bf16(Bt[n][k], At[m][k], acc[ai][bj][m][n], 0, 0, 0); __builtin_amdgcn_s_setprio(0); } while (0)
; #define PG8_WAIT_V(n) asm volatile("s_waitcnt vmcnt(" #n ")" ::: "memory")
; template <class Epi, class Sched, bool ALIGN_EPI = false, bool SP2 = false>
; __device__ __forceinline__ void gemm_phase(PG8_LAS unsigned char* lds, const Gemm g, const Sched& S, const Epi& E) {
;     ...
;             if constexpr (Epi::KHOOK) { if ((t & 7) == 0 && t != 0) E.khook(acc, t >> 3, wr, fr, lds); }
;             const bool last = (t == nt - 2);
;             const char* a1 = cA + (size_t)(t + 1) * kstep;
;             const char* a2 = last ? nA : cA + (size_t)(t + 2) * kstep; const char* b2 = last ? nB : cB + (size_t)(t + 2) * kstep;
;             const char* a3 = a2 + kstep; const char* b3 = b2 + kstep;
;             if (last && has_next) S.a_ready(nxt);
;             if constexpr (SP2) {
;             PG8_LDB(B0, 0, 0); PG8_LDB(B1, 0, 1); PG8_SCHED; PG8_LDA(At, 0, 0); PG8_STAGE(PG8_SA(1, 1), a1 + hstep, voffA);
;             PG8_WAIT_V(8); PG8_WAIT_L(0); PG8_BAR; PG8_MMA(0, 0, At, B0); PG8_MMA(0, 1, At, B1); PG8_BAR; PG8_SCHED;
;             PG8_LDA(At, 0, 1); PG8_STAGE(PG8_SB(0, 0), b2, voffB); PG8_STAGE(PG8_SB(0, 1), b2 + hstep, voffB); PG8_STAGE(PG8_SA(0, 0), a2, voffA);
;             PG8_WAIT_V(8); PG8_WAIT_L(0); PG8_BAR; PG8_MMA(1, 0, At, B0); PG8_MMA(1, 1, At, B1); PG8_BAR; PG8_SCHED;
.LBB0_245:
	v_readlane_b32 s22, v252, 59
	v_readlane_b32 s23, v252, 60
	s_andn2_b64 vcc, exec, s[22:23]
	s_cbranch_vccnz .LBB0_252
	s_add_u32 s40, s6, s48
	s_addc_u32 s41, s7, s49
	s_add_u32 s37, s6, 0x100
	s_addc_u32 s80, s7, 0
	s_and_b64 s[22:23], s[12:13], exec
	s_cselect_b32 s23, s5, s80
	s_cselect_b32 s22, s4, s37
	s_add_u32 s37, s10, 0x100
	s_addc_u32 s82, s11, 0
	s_and_b64 s[80:81], s[12:13], exec
	s_cselect_b32 s85, s17, s82
	s_cselect_b32 s84, s16, s37
	s_add_i32 s83, 0, 0x14000
	v_add_u32_e32 v150, s19, v147
	v_add_u32_e32 v151, s83, v147
	ds_read_b128 v[152:155], v150
	ds_read_b128 v[156:159], v150 offset:1024
	ds_read_b128 v[160:163], v150 offset:2048
	ds_read_b128 v[164:167], v150 offset:3072
	ds_read_b128 v[168:171], v151
	ds_read_b128 v[172:175], v151 offset:1024
	ds_read_b128 v[176:179], v151 offset:2048
	ds_read_b128 v[184:187], v151 offset:3072
	v_lshl_add_u64 v[180:181], s[40:41], 0, v[2:3]
	s_add_i32 s37, s47, 0xc000
	v_lshl_add_u64 v[180:181], v[180:181], 0, s[24:25]
	s_mov_b32 m0, s37
	ds_read_b128 v[188:191], v149
	ds_read_b128 v[192:195], v149 offset:1024
	ds_read_b128 v[196:199], v149 offset:2048
	ds_read_b128 v[200:203], v149 offset:3072
	ds_read_b128 v[204:207], v149 offset:4096
	ds_read_b128 v[230:233], v149 offset:5120
	ds_read_b128 v[234:237], v149 offset:6144
	ds_read_b128 v[238:241], v149 offset:7168
	global_load_lds_dwordx4 v[180:181], off
	v_lshl_add_u64 v[180:181], s[40:41], 0, v[136:137]
	s_add_i32 s80, s47, 0xe000
	v_lshl_add_u64 v[180:181], v[180:181], 0, s[24:25]
	s_mov_b32 m0, s80
	s_nop 0
	global_load_lds_dwordx4 v[180:181], off
	s_waitcnt vmcnt(8)
	s_waitcnt lgkmcnt(0)
	s_barrier
	s_setprio 1
	s_waitcnt lgkmcnt(0)
	v_mfma_f32_16x16x32_bf16 v[132:135], v[152:155], v[188:191], v[132:135]
	v_mfma_f32_16x16x32_bf16 v[132:135], v[156:159], v[192:195], v[132:135]
	v_mfma_f32_16x16x32_bf16 v[116:119], v[152:155], v[196:199], v[116:119]
	v_mfma_f32_16x16x32_bf16 v[116:119], v[156:159], v[200:203], v[116:119]
	v_mfma_f32_16x16x32_bf16 v[100:103], v[152:155], v[204:207], v[100:103]
	v_mfma_f32_16x16x32_bf16 v[100:103], v[156:159], v[230:233], v[100:103]
	v_mfma_f32_16x16x32_bf16 v[84:87], v[152:155], v[234:237], v[84:87]
	v_mfma_f32_16x16x32_bf16 v[84:87], v[156:159], v[238:241], v[84:87]
	v_mfma_f32_16x16x32_bf16 v[80:83], v[160:163], v[234:237], v[80:83]
	v_mfma_f32_16x16x32_bf16 v[80:83], v[164:167], v[238:241], v[80:83]
	v_mfma_f32_16x16x32_bf16 v[96:99], v[160:163], v[204:207], v[96:99]
	v_mfma_f32_16x16x32_bf16 v[96:99], v[164:167], v[230:233], v[96:99]
	v_mfma_f32_16x16x32_bf16 v[112:115], v[160:163], v[196:199], v[112:115]
	v_mfma_f32_16x16x32_bf16 v[112:115], v[164:167], v[200:203], v[112:115]
	v_mfma_f32_16x16x32_bf16 v[128:131], v[160:163], v[188:191], v[128:131]
	v_mfma_f32_16x16x32_bf16 v[128:131], v[164:167], v[192:195], v[128:131]
	s_setprio 0
	s_setprio 1
	v_mfma_f32_16x16x32_bf16 v[124:127], v[168:171], v[188:191], v[124:127]
	v_mfma_f32_16x16x32_bf16 v[124:127], v[172:175], v[192:195], v[124:127]
	v_mfma_f32_16x16x32_bf16 v[108:111], v[168:171], v[196:199], v[108:111]
	v_mfma_f32_16x16x32_bf16 v[108:111], v[172:175], v[200:203], v[108:111]
	v_mfma_f32_16x16x32_bf16 v[92:95], v[168:171], v[204:207], v[92:95]
	v_mfma_f32_16x16x32_bf16 v[92:95], v[172:175], v[230:233], v[92:95]
	v_mfma_f32_16x16x32_bf16 v[76:79], v[168:171], v[234:237], v[76:79]
	v_mfma_f32_16x16x32_bf16 v[76:79], v[172:175], v[238:241], v[76:79]
	v_mfma_f32_16x16x32_bf16 v[72:75], v[176:179], v[234:237], v[72:75]
	v_mfma_f32_16x16x32_bf16 v[72:75], v[184:187], v[238:241], v[72:75]
	v_mfma_f32_16x16x32_bf16 v[88:91], v[176:179], v[204:207], v[88:91]
	v_mfma_f32_16x16x32_bf16 v[88:91], v[184:187], v[230:233], v[88:91]
	v_mfma_f32_16x16x32_bf16 v[104:107], v[176:179], v[196:199], v[104:107]
	v_mfma_f32_16x16x32_bf16 v[104:107], v[184:187], v[200:203], v[104:107]
	v_mfma_f32_16x16x32_bf16 v[120:123], v[176:179], v[188:191], v[120:123]
	v_mfma_f32_16x16x32_bf16 v[120:123], v[184:187], v[192:195], v[120:123]
	s_setprio 0
	s_barrier
	s_add_i32 s81, s19, s46
	s_add_i32 s82, s81, 0x2000
	v_lshl_add_u64 v[208:209], s[84:85], 0, v[0:1]
	s_mov_b32 m0, s81
	s_add_u32 s40, s84, s48
	ds_read_b128 v[188:191], v149 offset:16384
	ds_read_b128 v[192:195], v149 offset:17408
	ds_read_b128 v[196:199], v149 offset:18432
	ds_read_b128 v[200:203], v149 offset:19456
	ds_read_b128 v[204:207], v149 offset:20480
	ds_read_b128 v[230:233], v149 offset:21504
	ds_read_b128 v[234:237], v149 offset:22528
	ds_read_b128 v[238:241], v149 offset:23552
	global_load_lds_dwordx4 v[208:209], off
	v_lshl_add_u64 v[216:217], s[84:85], 0, v[138:139]
	s_mov_b32 m0, s82
	s_addc_u32 s41, s85, s49
	s_add_i32 s83, s83, s46
	global_load_lds_dwordx4 v[216:217], off
	v_lshl_add_u64 v[224:225], s[40:41], 0, v[0:1]
	s_mov_b32 m0, s83
	s_add_i32 s84, s83, 0x2000
	global_load_lds_dwordx4 v[224:225], off
	v_lshl_add_u64 v[226:227], s[40:41], 0, v[138:139]
	s_mov_b32 m0, s84
	v_lshl_add_u64 v[228:229], s[22:23], 0, v[2:3]
	global_load_lds_dwordx4 v[226:227], off
	s_mov_b32 m0, s47
	v_lshl_add_u64 v[242:243], s[22:23], 0, v[136:137]
	global_load_lds_dwordx4 v[228:229], off
	s_mov_b32 m0, s52
	s_nop 0
	global_load_lds_dwordx4 v[242:243], off
	s_waitcnt vmcnt(8)
	s_waitcnt lgkmcnt(0)
	s_barrier
; #define PG8_STAGE(bufoff, gbase, voff) do { _Pragma("unroll") for (int _i = 0; _i < 2; ++_i) \
;         __builtin_amdgcn_global_load_lds((const unsigned*)((const char*)(gbase) + (voff)[_i]), (PG8_LAS unsigned*)(lds + (bufoff) + ldsw + _i * 8192), 16, 0, 0); } while (0)
; #define PG8_LDA(dst, b, h) do { _Pragma("unroll") for (int m = 0; m < 4; ++m) _Pragma("unroll") for (int k = 0; k < 2; ++k) dst[m][k] = *(const PG8_LAS bf16x8*)(lds + PG8_SA(b, h) + aoff + m * 2048 + k * 1024); } while (0)
; #define PG8_LDB(dst, b, h) do { _Pragma("unroll") for (int n = 0; n < 2; ++n) _Pragma("unroll") for (int k = 0; k < 2; ++k) dst[n][k] = *(const PG8_LAS bf16x8*)(lds + PG8_SB(b, h) + boff + n * 2048 + k * 1024); } while (0)
; #define PG8_MMA(ai, bj, At, Bt) do { __builtin_amdgcn_s_setprio(1); _Pragma("unroll") for (int m = 0; m < 4; ++m) _Pragma("unroll") for (int n = 0; n < 2; ++n) _Pragma("unroll") for (int k = 0; k < 2; ++k) \
;         acc[ai][bj][m][n] = __builtin_amdgcn_mfma_f32_16x16x32_bf16(Bt[n][k], At[m][k], acc[ai][bj][m][n], 0, 0, 0); __builtin_amdgcn_s_setprio(0); } while (0)
; #define PG8_WAIT_V(n) asm volatile("s_waitcnt vmcnt(" #n ")" ::: "memory")
; #define PG8_WAIT_L(n) asm volatile("s_waitcnt lgkmcnt(" #n ")" ::: "memory")
; #define PG8_BAR __builtin_amdgcn_s_barrier()
; #define PG8_SCHED __builtin_amdgcn_sched_barrier(0)
; template <class Epi, class Sched, bool ALIGN_EPI = false, bool SP2 = false>
; __device__ __forceinline__ void gemm_phase(PG8_LAS unsigned char* lds, const Gemm g, const Sched& S, const Epi& E) {
;     ...
;             PG8_WAIT_V(8); PG8_WAIT_L(0); PG8_BAR; PG8_MMA(1, 0, At, B0); PG8_MMA(1, 1, At, B1); PG8_BAR; PG8_SCHED;
;             PG8_LDB(B0, 1, 0); PG8_LDB(B1, 1, 1); PG8_SCHED; PG8_LDA(At, 1, 0); PG8_STAGE(PG8_SA(0, 1), a2 + hstep, voffA);
;             PG8_WAIT_V(8); PG8_WAIT_L(0); PG8_BAR; PG8_MMA(0, 0, At, B0); PG8_MMA(0, 1, At, B1); PG8_BAR; PG8_SCHED;
	s_setprio 1
	s_waitcnt lgkmcnt(0)
	v_mfma_f32_16x16x32_bf16 v[68:71], v[152:155], v[188:191], v[68:71]
	v_mfma_f32_16x16x32_bf16 v[68:71], v[156:159], v[192:195], v[68:71]
	v_mfma_f32_16x16x32_bf16 v[52:55], v[152:155], v[196:199], v[52:55]
	v_mfma_f32_16x16x32_bf16 v[52:55], v[156:159], v[200:203], v[52:55]
	v_mfma_f32_16x16x32_bf16 v[36:39], v[152:155], v[204:207], v[36:39]
	v_mfma_f32_16x16x32_bf16 v[36:39], v[156:159], v[230:233], v[36:39]
	v_mfma_f32_16x16x32_bf16 v[20:23], v[152:155], v[234:237], v[20:23]
	v_mfma_f32_16x16x32_bf16 v[20:23], v[156:159], v[238:241], v[20:23]
	v_mfma_f32_16x16x32_bf16 v[16:19], v[160:163], v[234:237], v[16:19]
	v_mfma_f32_16x16x32_bf16 v[16:19], v[164:167], v[238:241], v[16:19]
	v_mfma_f32_16x16x32_bf16 v[32:35], v[160:163], v[204:207], v[32:35]
	v_mfma_f32_16x16x32_bf16 v[32:35], v[164:167], v[230:233], v[32:35]
	v_mfma_f32_16x16x32_bf16 v[48:51], v[160:163], v[196:199], v[48:51]
	v_mfma_f32_16x16x32_bf16 v[48:51], v[164:167], v[200:203], v[48:51]
	v_mfma_f32_16x16x32_bf16 v[64:67], v[160:163], v[188:191], v[64:67]
	v_mfma_f32_16x16x32_bf16 v[64:67], v[164:167], v[192:195], v[64:67]
	s_setprio 0
	s_setprio 1
	v_mfma_f32_16x16x32_bf16 v[60:63], v[168:171], v[188:191], v[60:63]
	v_mfma_f32_16x16x32_bf16 v[60:63], v[172:175], v[192:195], v[60:63]
	v_mfma_f32_16x16x32_bf16 v[44:47], v[168:171], v[196:199], v[44:47]
	v_mfma_f32_16x16x32_bf16 v[44:47], v[172:175], v[200:203], v[44:47]
	v_mfma_f32_16x16x32_bf16 v[28:31], v[168:171], v[204:207], v[28:31]
	v_mfma_f32_16x16x32_bf16 v[28:31], v[172:175], v[230:233], v[28:31]
	v_mfma_f32_16x16x32_bf16 v[12:15], v[168:171], v[234:237], v[12:15]
	v_mfma_f32_16x16x32_bf16 v[12:15], v[172:175], v[238:241], v[12:15]
	v_mfma_f32_16x16x32_bf16 v[8:11], v[176:179], v[234:237], v[8:11]
	v_mfma_f32_16x16x32_bf16 v[8:11], v[184:187], v[238:241], v[8:11]
	v_mfma_f32_16x16x32_bf16 v[24:27], v[176:179], v[204:207], v[24:27]
	v_mfma_f32_16x16x32_bf16 v[24:27], v[184:187], v[230:233], v[24:27]
	v_mfma_f32_16x16x32_bf16 v[40:43], v[176:179], v[196:199], v[40:43]
	v_mfma_f32_16x16x32_bf16 v[40:43], v[184:187], v[200:203], v[40:43]
	v_mfma_f32_16x16x32_bf16 v[56:59], v[176:179], v[188:191], v[56:59]
	v_mfma_f32_16x16x32_bf16 v[56:59], v[184:187], v[192:195], v[56:59]
	s_setprio 0
	s_barrier
	s_add_i32 s87, 0, 0x1c000
	v_add_u32_e32 v152, s91, v147
	v_add_u32_e32 v153, s87, v147
	ds_read_b128 v[154:157], v152
	ds_read_b128 v[158:161], v152 offset:1024
	ds_read_b128 v[162:165], v152 offset:2048
	ds_read_b128 v[166:169], v152 offset:3072
	ds_read_b128 v[170:173], v153
	ds_read_b128 v[174:177], v153 offset:1024
	ds_read_b128 v[178:181], v153 offset:2048
	ds_read_b128 v[184:187], v153 offset:3072
	s_add_u32 s22, s22, s48
	s_addc_u32 s23, s23, s49
	s_mov_b32 m0, s53
	v_lshl_add_u64 v[244:245], s[22:23], 0, v[2:3]
	ds_read_b128 v[188:191], v149 offset:32768
	ds_read_b128 v[192:195], v149 offset:33792
	ds_read_b128 v[196:199], v149 offset:34816
	ds_read_b128 v[200:203], v149 offset:35840
	ds_read_b128 v[204:207], v149 offset:36864
	ds_read_b128 v[230:233], v149 offset:37888
	ds_read_b128 v[234:237], v149 offset:38912
	ds_read_b128 v[238:241], v149 offset:39936
	global_load_lds_dwordx4 v[244:245], off
	v_lshl_add_u64 v[244:245], s[22:23], 0, v[136:137]
	s_mov_b32 m0, s72
	s_nop 0
	global_load_lds_dwordx4 v[244:245], off
	s_waitcnt vmcnt(8)
	s_waitcnt lgkmcnt(0)
	s_barrier
	s_setprio 1
	s_waitcnt lgkmcnt(0)
	v_mfma_f32_16x16x32_bf16 v[132:135], v[154:157], v[188:191], v[132:135]
	v_mfma_f32_16x16x32_bf16 v[132:135], v[158:161], v[192:195], v[132:135]
	v_mfma_f32_16x16x32_bf16 v[116:119], v[154:157], v[196:199], v[116:119]
	v_mfma_f32_16x16x32_bf16 v[116:119], v[158:161], v[200:203], v[116:119]
	v_mfma_f32_16x16x32_bf16 v[100:103], v[154:157], v[204:207], v[100:103]
	v_mfma_f32_16x16x32_bf16 v[100:103], v[158:161], v[230:233], v[100:103]
	v_mfma_f32_16x16x32_bf16 v[84:87], v[154:157], v[234:237], v[84:87]
	v_mfma_f32_16x16x32_bf16 v[84:87], v[158:161], v[238:241], v[84:87]
	v_mfma_f32_16x16x32_bf16 v[80:83], v[162:165], v[234:237], v[80:83]
	v_mfma_f32_16x16x32_bf16 v[80:83], v[166:169], v[238:241], v[80:83]
	v_mfma_f32_16x16x32_bf16 v[96:99], v[162:165], v[204:207], v[96:99]
	v_mfma_f32_16x16x32_bf16 v[96:99], v[166:169], v[230:233], v[96:99]
	v_mfma_f32_16x16x32_bf16 v[112:115], v[162:165], v[196:199], v[112:115]
	v_mfma_f32_16x16x32_bf16 v[112:115], v[166:169], v[200:203], v[112:115]
	v_mfma_f32_16x16x32_bf16 v[128:131], v[162:165], v[188:191], v[128:131]
	v_mfma_f32_16x16x32_bf16 v[128:131], v[166:169], v[192:195], v[128:131]
	s_setprio 0
	s_setprio 1
	v_mfma_f32_16x16x32_bf16 v[124:127], v[170:173], v[188:191], v[124:127]
	v_mfma_f32_16x16x32_bf16 v[124:127], v[174:177], v[192:195], v[124:127]
	v_mfma_f32_16x16x32_bf16 v[108:111], v[170:173], v[196:199], v[108:111]
	v_mfma_f32_16x16x32_bf16 v[108:111], v[174:177], v[200:203], v[108:111]
	v_mfma_f32_16x16x32_bf16 v[92:95], v[170:173], v[204:207], v[92:95]
	v_mfma_f32_16x16x32_bf16 v[92:95], v[174:177], v[230:233], v[92:95]
	v_mfma_f32_16x16x32_bf16 v[76:79], v[170:173], v[234:237], v[76:79]
	v_mfma_f32_16x16x32_bf16 v[76:79], v[174:177], v[238:241], v[76:79]
	v_mfma_f32_16x16x32_bf16 v[72:75], v[178:181], v[234:237], v[72:75]
	v_mfma_f32_16x16x32_bf16 v[72:75], v[184:187], v[238:241], v[72:75]
	v_mfma_f32_16x16x32_bf16 v[88:91], v[178:181], v[204:207], v[88:91]
	v_mfma_f32_16x16x32_bf16 v[88:91], v[184:187], v[230:233], v[88:91]
	v_mfma_f32_16x16x32_bf16 v[104:107], v[178:181], v[196:199], v[104:107]
	v_mfma_f32_16x16x32_bf16 v[104:107], v[184:187], v[200:203], v[104:107]
	v_mfma_f32_16x16x32_bf16 v[120:123], v[178:181], v[188:191], v[120:123]
	v_mfma_f32_16x16x32_bf16 v[120:123], v[184:187], v[192:195], v[120:123]
	s_setprio 0
	s_barrier
; #define PG8_STAGE(bufoff, gbase, voff) do { _Pragma("unroll") for (int _i = 0; _i < 2; ++_i) \
;         __builtin_amdgcn_global_load_lds((const unsigned*)((const char*)(gbase) + (voff)[_i]), (PG8_LAS unsigned*)(lds + (bufoff) + ldsw + _i * 8192), 16, 0, 0); } while (0)
; #define PG8_LDA(dst, b, h) do { _Pragma("unroll") for (int m = 0; m < 4; ++m) _Pragma("unroll") for (int k = 0; k < 2; ++k) dst[m][k] = *(const PG8_LAS bf16x8*)(lds + PG8_SA(b, h) + aoff + m * 2048 + k * 1024); } while (0)
; #define PG8_MMA(ai, bj, At, Bt) do { __builtin_amdgcn_s_setprio(1); _Pragma("unroll") for (int m = 0; m < 4; ++m) _Pragma("unroll") for (int n = 0; n < 2; ++n) _Pragma("unroll") for (int k = 0; k < 2; ++k) \
;         acc[ai][bj][m][n] = __builtin_amdgcn_mfma_f32_16x16x32_bf16(Bt[n][k], At[m][k], acc[ai][bj][m][n], 0, 0, 0); __builtin_amdgcn_s_setprio(0); } while (0)
; #define PG8_WAIT_V(n) asm volatile("s_waitcnt vmcnt(" #n ")" ::: "memory")
; #define PG8_WAIT_L(n) asm volatile("s_waitcnt lgkmcnt(" #n ")" ::: "memory")
; #define PG8_BAR __builtin_amdgcn_s_barrier()
; #define PG8_SCHED __builtin_amdgcn_sched_barrier(0)
; template <class Epi, class Sched, bool ALIGN_EPI = false, bool SP2 = false>
; __device__ __forceinline__ void gemm_phase(PG8_LAS unsigned char* lds, const Gemm g, const Sched& S, const Epi& E) {
;     ...
;             if constexpr (Epi::KHOOK) { if ((t & 7) == 0 && t != 0) E.khook(acc, t >> 3, wr, fr, lds); }
;     ...
;             PG8_LDA(At, 1, 1); PG8_STAGE(PG8_SB(1, 0), b3, voffB); PG8_STAGE(PG8_SB(1, 1), b3 + hstep, voffB); PG8_STAGE(PG8_SA(1, 0), a3, voffA);
;             PG8_WAIT_V(8); PG8_WAIT_L(0); PG8_BAR; PG8_MMA(1, 0, At, B0); PG8_MMA(1, 1, At, B1); PG8_BAR; PG8_SCHED;
	s_add_i32 s85, s91, s46
	v_lshl_add_u64 v[208:209], v[208:209], 0, s[24:25]
	s_mov_b32 m0, s85
	s_add_i32 s86, s85, 0x2000
	ds_read_b128 v[188:191], v149 offset:49152
	ds_read_b128 v[192:195], v149 offset:50176
	ds_read_b128 v[196:199], v149 offset:51200
	ds_read_b128 v[200:203], v149 offset:52224
	ds_read_b128 v[204:207], v149 offset:53248
	ds_read_b128 v[230:233], v149 offset:54272
	ds_read_b128 v[234:237], v149 offset:55296
	ds_read_b128 v[238:241], v149 offset:56320
	global_load_lds_dwordx4 v[208:209], off
	v_lshl_add_u64 v[208:209], v[216:217], 0, s[24:25]
	s_mov_b32 m0, s86
	s_add_i32 s87, s87, s46
	global_load_lds_dwordx4 v[208:209], off
	v_lshl_add_u64 v[208:209], v[224:225], 0, s[24:25]
	s_mov_b32 m0, s87
	s_add_i32 s88, s87, 0x2000
	global_load_lds_dwordx4 v[208:209], off
	v_lshl_add_u64 v[208:209], v[226:227], 0, s[24:25]
	s_mov_b32 m0, s88
	s_nop 0
	global_load_lds_dwordx4 v[208:209], off
	v_lshl_add_u64 v[208:209], v[228:229], 0, s[24:25]
	s_mov_b32 m0, s75
	s_nop 0
	global_load_lds_dwordx4 v[208:209], off
	v_lshl_add_u64 v[208:209], v[242:243], 0, s[24:25]
	s_mov_b32 m0, s76
	s_nop 0
	global_load_lds_dwordx4 v[208:209], off
	s_waitcnt vmcnt(8)
	s_waitcnt lgkmcnt(0)
	s_barrier
	s_setprio 1
	s_waitcnt lgkmcnt(0)
	v_mfma_f32_16x16x32_bf16 v[68:71], v[154:157], v[188:191], v[68:71]
	v_mfma_f32_16x16x32_bf16 v[68:71], v[158:161], v[192:195], v[68:71]
	v_mfma_f32_16x16x32_bf16 v[52:55], v[154:157], v[196:199], v[52:55]
	v_mfma_f32_16x16x32_bf16 v[52:55], v[158:161], v[200:203], v[52:55]
	v_mfma_f32_16x16x32_bf16 v[36:39], v[154:157], v[204:207], v[36:39]
	v_mfma_f32_16x16x32_bf16 v[36:39], v[158:161], v[230:233], v[36:39]
	v_mfma_f32_16x16x32_bf16 v[20:23], v[154:157], v[234:237], v[20:23]
	v_mfma_f32_16x16x32_bf16 v[20:23], v[158:161], v[238:241], v[20:23]
	v_mfma_f32_16x16x32_bf16 v[16:19], v[162:165], v[234:237], v[16:19]
	v_mfma_f32_16x16x32_bf16 v[16:19], v[166:169], v[238:241], v[16:19]
	v_mfma_f32_16x16x32_bf16 v[32:35], v[162:165], v[204:207], v[32:35]
	v_mfma_f32_16x16x32_bf16 v[32:35], v[166:169], v[230:233], v[32:35]
	v_mfma_f32_16x16x32_bf16 v[48:51], v[162:165], v[196:199], v[48:51]
	v_mfma_f32_16x16x32_bf16 v[48:51], v[166:169], v[200:203], v[48:51]
	v_mfma_f32_16x16x32_bf16 v[64:67], v[162:165], v[188:191], v[64:67]
	v_mfma_f32_16x16x32_bf16 v[64:67], v[166:169], v[192:195], v[64:67]
	s_setprio 0
	s_setprio 1
	v_mfma_f32_16x16x32_bf16 v[60:63], v[170:173], v[188:191], v[60:63]
	v_mfma_f32_16x16x32_bf16 v[60:63], v[174:177], v[192:195], v[60:63]
	v_mfma_f32_16x16x32_bf16 v[44:47], v[170:173], v[196:199], v[44:47]
	v_mfma_f32_16x16x32_bf16 v[44:47], v[174:177], v[200:203], v[44:47]
	v_mfma_f32_16x16x32_bf16 v[28:31], v[170:173], v[204:207], v[28:31]
	v_mfma_f32_16x16x32_bf16 v[28:31], v[174:177], v[230:233], v[28:31]
	v_mfma_f32_16x16x32_bf16 v[12:15], v[170:173], v[234:237], v[12:15]
	v_mfma_f32_16x16x32_bf16 v[12:15], v[174:177], v[238:241], v[12:15]
	v_mfma_f32_16x16x32_bf16 v[8:11], v[178:181], v[234:237], v[8:11]
	v_mfma_f32_16x16x32_bf16 v[8:11], v[184:187], v[238:241], v[8:11]
	v_mfma_f32_16x16x32_bf16 v[24:27], v[178:181], v[204:207], v[24:27]
	v_mfma_f32_16x16x32_bf16 v[24:27], v[184:187], v[230:233], v[24:27]
	v_mfma_f32_16x16x32_bf16 v[40:43], v[178:181], v[196:199], v[40:43]
	v_mfma_f32_16x16x32_bf16 v[40:43], v[184:187], v[200:203], v[40:43]
	v_mfma_f32_16x16x32_bf16 v[56:59], v[178:181], v[188:191], v[56:59]
	v_mfma_f32_16x16x32_bf16 v[56:59], v[184:187], v[192:195], v[56:59]
	s_setprio 0
	s_barrier
	v_readlane_b32 s22, v252, 42
	v_readlane_b32 s23, v252, 43
	s_andn2_b64 vcc, exec, s[22:23]
	s_cbranch_vccnz .LBB0_251
	s_add_u32 s22, s6, 0x180
	s_addc_u32 s23, s7, 0
	s_add_u32 s89, s10, 0x200
	s_addc_u32 s92, s11, 0
	s_mov_b32 s93, 4
	v_mov_b32_e32 v154, v148
	s_add_i32 s40, s93, -2
	s_and_b32 s40, s40, 6
	s_cmp_lg_u32 s40, 0
	s_cbranch_scc1 .LBB0_250
	s_branch .LBB0_249

; #define PG8_STAGE(bufoff, gbase, voff) do { _Pragma("unroll") for (int _i = 0; _i < 2; ++_i) \
;         __builtin_amdgcn_global_load_lds((const unsigned*)((const char*)(gbase) + (voff)[_i]), (PG8_LAS unsigned*)(lds + (bufoff) + ldsw + _i * 8192), 16, 0, 0); } while (0)
; #define PG8_LDA(dst, b, h) do { _Pragma("unroll") for (int m = 0; m < 4; ++m) _Pragma("unroll") for (int k = 0; k < 2; ++k) dst[m][k] = *(const PG8_LAS bf16x8*)(lds + PG8_SA(b, h) + aoff + m * 2048 + k * 1024); } while (0)
; #define PG8_LDB(dst, b, h) do { _Pragma("unroll") for (int n = 0; n < 2; ++n) _Pragma("unroll") for (int k = 0; k < 2; ++k) dst[n][k] = *(const PG8_LAS bf16x8*)(lds + PG8_SB(b, h) + boff + n * 2048 + k * 1024); } while (0)
; #define PG8_MMA(ai, bj, At, Bt) do { __builtin_amdgcn_s_setprio(1); _Pragma("unroll") for (int m = 0; m < 4; ++m) _Pragma("unroll") for (int n = 0; n < 2; ++n) _Pragma("unroll") for (int k = 0; k < 2; ++k) \
;         acc[ai][bj][m][n] = __builtin_amdgcn_mfma_f32_16x16x32_bf16(Bt[n][k], At[m][k], acc[ai][bj][m][n], 0, 0, 0); __builtin_amdgcn_s_setprio(0); } while (0)
; #define PG8_WAIT_V(n) asm volatile("s_waitcnt vmcnt(" #n ")" ::: "memory")
; #define PG8_WAIT_L(n) asm volatile("s_waitcnt lgkmcnt(" #n ")" ::: "memory")
; template <class Epi, class Sched, bool ALIGN_EPI = false, bool SP2 = false>
; __device__ __forceinline__ void gemm_phase(PG8_LAS unsigned char* lds, const Gemm g, const Sched& S, const Epi& E) {
;     ...
;             const bool last = (t == nt - 2);
;             const char* a1 = cA + (size_t)(t + 1) * kstep;
;             const char* a2 = last ? nA : cA + (size_t)(t + 2) * kstep; const char* b2 = last ? nB : cB + (size_t)(t + 2) * kstep;
;             const char* a3 = a2 + kstep; const char* b3 = b2 + kstep;
;             if (last && has_next) S.a_ready(nxt);
;             if constexpr (SP2) {
;             PG8_LDB(B0, 0, 0); PG8_LDB(B1, 0, 1); PG8_SCHED; PG8_LDA(At, 0, 0); PG8_STAGE(PG8_SA(1, 1), a1 + hstep, voffA);
;             PG8_WAIT_V(8); PG8_WAIT_L(0); PG8_BAR; PG8_MMA(0, 0, At, B0); PG8_MMA(0, 1, At, B1); PG8_BAR; PG8_SCHED;
;             PG8_LDA(At, 0, 1); PG8_STAGE(PG8_SB(0, 0), b2, voffB); PG8_STAGE(PG8_SB(0, 1), b2 + hstep, voffB); PG8_STAGE(PG8_SA(0, 0), a2, voffA);
;             PG8_WAIT_V(8); PG8_WAIT_L(0); PG8_BAR; PG8_MMA(1, 0, At, B0); PG8_MMA(1, 1, At, B1); PG8_BAR; PG8_SCHED;
.LBB0_250:
	ds_read_b128 v[156:159], v150
	ds_read_b128 v[160:163], v150 offset:1024
	ds_read_b128 v[164:167], v150 offset:2048
	ds_read_b128 v[168:171], v150 offset:3072
	ds_read_b128 v[172:175], v151
	ds_read_b128 v[176:179], v151 offset:1024
	ds_read_b128 v[184:187], v151 offset:2048
	ds_read_b128 v[188:191], v151 offset:3072
	s_add_u32 s40, s22, 0x80
	s_addc_u32 s41, s23, 0
	s_cmp_eq_u32 s9, s93
	s_cselect_b32 s40, s4, s40
	s_cselect_b32 s41, s5, s41
	s_cselect_b32 s95, s17, s92
	s_cselect_b32 s94, s16, s89
	s_mov_b32 m0, s37
	v_lshl_add_u64 v[180:181], s[22:23], 0, v[140:141]
	ds_read_b128 v[192:195], v149
	ds_read_b128 v[196:199], v149 offset:1024
	ds_read_b128 v[200:203], v149 offset:2048
	ds_read_b128 v[204:207], v149 offset:3072
	ds_read_b128 v[230:233], v149 offset:4096
	ds_read_b128 v[234:237], v149 offset:5120
	ds_read_b128 v[238:241], v149 offset:6144
	ds_read_b128 v[242:245], v149 offset:7168
	global_load_lds_dwordx4 v[180:181], off
	v_lshl_add_u64 v[180:181], s[22:23], 0, v[142:143]
	s_mov_b32 m0, s80
	s_nop 0
	global_load_lds_dwordx4 v[180:181], off
	s_waitcnt vmcnt(8)
	s_waitcnt lgkmcnt(0)
	s_barrier
	s_setprio 1
	s_waitcnt lgkmcnt(0)
	v_mfma_f32_16x16x32_bf16 v[132:135], v[156:159], v[192:195], v[132:135]
	v_mfma_f32_16x16x32_bf16 v[132:135], v[160:163], v[196:199], v[132:135]
	v_mfma_f32_16x16x32_bf16 v[116:119], v[156:159], v[200:203], v[116:119]
	v_mfma_f32_16x16x32_bf16 v[116:119], v[160:163], v[204:207], v[116:119]
	v_mfma_f32_16x16x32_bf16 v[100:103], v[156:159], v[230:233], v[100:103]
	v_mfma_f32_16x16x32_bf16 v[100:103], v[160:163], v[234:237], v[100:103]
	v_mfma_f32_16x16x32_bf16 v[84:87], v[156:159], v[238:241], v[84:87]
	v_mfma_f32_16x16x32_bf16 v[84:87], v[160:163], v[242:245], v[84:87]
	v_mfma_f32_16x16x32_bf16 v[80:83], v[164:167], v[238:241], v[80:83]
	v_mfma_f32_16x16x32_bf16 v[80:83], v[168:171], v[242:245], v[80:83]
	v_mfma_f32_16x16x32_bf16 v[96:99], v[164:167], v[230:233], v[96:99]
	v_mfma_f32_16x16x32_bf16 v[96:99], v[168:171], v[234:237], v[96:99]
	v_mfma_f32_16x16x32_bf16 v[112:115], v[164:167], v[200:203], v[112:115]
	v_mfma_f32_16x16x32_bf16 v[112:115], v[168:171], v[204:207], v[112:115]
	v_mfma_f32_16x16x32_bf16 v[128:131], v[164:167], v[192:195], v[128:131]
	v_mfma_f32_16x16x32_bf16 v[128:131], v[168:171], v[196:199], v[128:131]
	s_setprio 0
	s_setprio 1
	v_mfma_f32_16x16x32_bf16 v[124:127], v[172:175], v[192:195], v[124:127]
	v_mfma_f32_16x16x32_bf16 v[124:127], v[176:179], v[196:199], v[124:127]
	v_mfma_f32_16x16x32_bf16 v[108:111], v[172:175], v[200:203], v[108:111]
	v_mfma_f32_16x16x32_bf16 v[108:111], v[176:179], v[204:207], v[108:111]
	v_mfma_f32_16x16x32_bf16 v[92:95], v[172:175], v[230:233], v[92:95]
	v_mfma_f32_16x16x32_bf16 v[92:95], v[176:179], v[234:237], v[92:95]
	v_mfma_f32_16x16x32_bf16 v[76:79], v[172:175], v[238:241], v[76:79]
	v_mfma_f32_16x16x32_bf16 v[76:79], v[176:179], v[242:245], v[76:79]
	v_mfma_f32_16x16x32_bf16 v[72:75], v[184:187], v[238:241], v[72:75]
	v_mfma_f32_16x16x32_bf16 v[72:75], v[188:191], v[242:245], v[72:75]
	v_mfma_f32_16x16x32_bf16 v[88:91], v[184:187], v[230:233], v[88:91]
	v_mfma_f32_16x16x32_bf16 v[88:91], v[188:191], v[234:237], v[88:91]
	v_mfma_f32_16x16x32_bf16 v[104:107], v[184:187], v[200:203], v[104:107]
	v_mfma_f32_16x16x32_bf16 v[104:107], v[188:191], v[204:207], v[104:107]
	v_mfma_f32_16x16x32_bf16 v[120:123], v[184:187], v[192:195], v[120:123]
	v_mfma_f32_16x16x32_bf16 v[120:123], v[188:191], v[196:199], v[120:123]
	s_setprio 0
	s_barrier
	s_mov_b32 m0, s81
	v_lshl_add_u64 v[180:181], s[94:95], 0, v[0:1]
	v_lshl_add_u64 v[208:209], s[94:95], 0, v[138:139]
	s_add_u32 s94, s94, s48
	ds_read_b128 v[192:195], v149 offset:16384
	ds_read_b128 v[196:199], v149 offset:17408
	ds_read_b128 v[200:203], v149 offset:18432
	ds_read_b128 v[204:207], v149 offset:19456
	ds_read_b128 v[230:233], v149 offset:20480
	ds_read_b128 v[234:237], v149 offset:21504
	ds_read_b128 v[238:241], v149 offset:22528
	ds_read_b128 v[242:245], v149 offset:23552
	global_load_lds_dwordx4 v[180:181], off
	s_mov_b32 m0, s82
	s_addc_u32 s95, s95, s49
	global_load_lds_dwordx4 v[208:209], off
	v_lshl_add_u64 v[216:217], s[94:95], 0, v[0:1]
	s_mov_b32 m0, s83
	v_lshl_add_u64 v[224:225], s[94:95], 0, v[138:139]
	global_load_lds_dwordx4 v[216:217], off
	s_mov_b32 m0, s84
	v_lshl_add_u64 v[226:227], s[40:41], 0, v[2:3]
	global_load_lds_dwordx4 v[224:225], off
	s_mov_b32 m0, s47
	v_lshl_add_u64 v[228:229], s[40:41], 0, v[136:137]
	global_load_lds_dwordx4 v[226:227], off
	s_mov_b32 m0, s52
	s_nop 0
	global_load_lds_dwordx4 v[228:229], off
	s_waitcnt vmcnt(8)
	s_waitcnt lgkmcnt(0)
	s_barrier
; #define PG8_STAGE(bufoff, gbase, voff) do { _Pragma("unroll") for (int _i = 0; _i < 2; ++_i) \
;         __builtin_amdgcn_global_load_lds((const unsigned*)((const char*)(gbase) + (voff)[_i]), (PG8_LAS unsigned*)(lds + (bufoff) + ldsw + _i * 8192), 16, 0, 0); } while (0)
; #define PG8_LDA(dst, b, h) do { _Pragma("unroll") for (int m = 0; m < 4; ++m) _Pragma("unroll") for (int k = 0; k < 2; ++k) dst[m][k] = *(const PG8_LAS bf16x8*)(lds + PG8_SA(b, h) + aoff + m * 2048 + k * 1024); } while (0)
; #define PG8_LDB(dst, b, h) do { _Pragma("unroll") for (int n = 0; n < 2; ++n) _Pragma("unroll") for (int k = 0; k < 2; ++k) dst[n][k] = *(const PG8_LAS bf16x8*)(lds + PG8_SB(b, h) + boff + n * 2048 + k * 1024); } while (0)
; #define PG8_MMA(ai, bj, At, Bt) do { __builtin_amdgcn_s_setprio(1); _Pragma("unroll") for (int m = 0; m < 4; ++m) _Pragma("unroll") for (int n = 0; n < 2; ++n) _Pragma("unroll") for (int k = 0; k < 2; ++k) \
;         acc[ai][bj][m][n] = __builtin_amdgcn_mfma_f32_16x16x32_bf16(Bt[n][k], At[m][k], acc[ai][bj][m][n], 0, 0, 0); __builtin_amdgcn_s_setprio(0); } while (0)
; #define PG8_WAIT_V(n) asm volatile("s_waitcnt vmcnt(" #n ")" ::: "memory")
; #define PG8_WAIT_L(n) asm volatile("s_waitcnt lgkmcnt(" #n ")" ::: "memory")
; #define PG8_BAR __builtin_amdgcn_s_barrier()
; #define PG8_SCHED __builtin_amdgcn_sched_barrier(0)
; template <class Epi, class Sched, bool ALIGN_EPI = false, bool SP2 = false>
; __device__ __forceinline__ void gemm_phase(PG8_LAS unsigned char* lds, const Gemm g, const Sched& S, const Epi& E) {
;     ...
;             PG8_WAIT_V(8); PG8_WAIT_L(0); PG8_BAR; PG8_MMA(1, 0, At, B0); PG8_MMA(1, 1, At, B1); PG8_BAR; PG8_SCHED;
;             PG8_LDB(B0, 1, 0); PG8_LDB(B1, 1, 1); PG8_SCHED; PG8_LDA(At, 1, 0); PG8_STAGE(PG8_SA(0, 1), a2 + hstep, voffA);
;             PG8_WAIT_V(8); PG8_WAIT_L(0); PG8_BAR; PG8_MMA(0, 0, At, B0); PG8_MMA(0, 1, At, B1); PG8_BAR; PG8_SCHED;
	s_setprio 1
	s_waitcnt lgkmcnt(0)
	v_mfma_f32_16x16x32_bf16 v[68:71], v[156:159], v[192:195], v[68:71]
	v_mfma_f32_16x16x32_bf16 v[68:71], v[160:163], v[196:199], v[68:71]
	v_mfma_f32_16x16x32_bf16 v[52:55], v[156:159], v[200:203], v[52:55]
	v_mfma_f32_16x16x32_bf16 v[52:55], v[160:163], v[204:207], v[52:55]
	v_mfma_f32_16x16x32_bf16 v[36:39], v[156:159], v[230:233], v[36:39]
	v_mfma_f32_16x16x32_bf16 v[36:39], v[160:163], v[234:237], v[36:39]
	v_mfma_f32_16x16x32_bf16 v[20:23], v[156:159], v[238:241], v[20:23]
	v_mfma_f32_16x16x32_bf16 v[20:23], v[160:163], v[242:245], v[20:23]
	v_mfma_f32_16x16x32_bf16 v[16:19], v[164:167], v[238:241], v[16:19]
	v_mfma_f32_16x16x32_bf16 v[16:19], v[168:171], v[242:245], v[16:19]
	v_mfma_f32_16x16x32_bf16 v[32:35], v[164:167], v[230:233], v[32:35]
	v_mfma_f32_16x16x32_bf16 v[32:35], v[168:171], v[234:237], v[32:35]
	v_mfma_f32_16x16x32_bf16 v[48:51], v[164:167], v[200:203], v[48:51]
	v_mfma_f32_16x16x32_bf16 v[48:51], v[168:171], v[204:207], v[48:51]
	v_mfma_f32_16x16x32_bf16 v[64:67], v[164:167], v[192:195], v[64:67]
	v_mfma_f32_16x16x32_bf16 v[64:67], v[168:171], v[196:199], v[64:67]
	s_setprio 0
	s_setprio 1
	v_mfma_f32_16x16x32_bf16 v[60:63], v[172:175], v[192:195], v[60:63]
	v_mfma_f32_16x16x32_bf16 v[60:63], v[176:179], v[196:199], v[60:63]
	v_mfma_f32_16x16x32_bf16 v[44:47], v[172:175], v[200:203], v[44:47]
	v_mfma_f32_16x16x32_bf16 v[44:47], v[176:179], v[204:207], v[44:47]
	v_mfma_f32_16x16x32_bf16 v[28:31], v[172:175], v[230:233], v[28:31]
	v_mfma_f32_16x16x32_bf16 v[28:31], v[176:179], v[234:237], v[28:31]
	v_mfma_f32_16x16x32_bf16 v[12:15], v[172:175], v[238:241], v[12:15]
	v_mfma_f32_16x16x32_bf16 v[12:15], v[176:179], v[242:245], v[12:15]
	v_mfma_f32_16x16x32_bf16 v[8:11], v[184:187], v[238:241], v[8:11]
	v_mfma_f32_16x16x32_bf16 v[8:11], v[188:191], v[242:245], v[8:11]
	v_mfma_f32_16x16x32_bf16 v[24:27], v[184:187], v[230:233], v[24:27]
	v_mfma_f32_16x16x32_bf16 v[24:27], v[188:191], v[234:237], v[24:27]
	v_mfma_f32_16x16x32_bf16 v[40:43], v[184:187], v[200:203], v[40:43]
	v_mfma_f32_16x16x32_bf16 v[40:43], v[188:191], v[204:207], v[40:43]
	v_mfma_f32_16x16x32_bf16 v[56:59], v[184:187], v[192:195], v[56:59]
	v_mfma_f32_16x16x32_bf16 v[56:59], v[188:191], v[196:199], v[56:59]
	s_setprio 0
	s_barrier
	ds_read_b128 v[156:159], v152
	ds_read_b128 v[160:163], v152 offset:1024
	ds_read_b128 v[164:167], v152 offset:2048
	ds_read_b128 v[168:171], v152 offset:3072
	ds_read_b128 v[172:175], v153
	ds_read_b128 v[176:179], v153 offset:1024
	ds_read_b128 v[184:187], v153 offset:2048
	ds_read_b128 v[188:191], v153 offset:3072
	s_add_u32 s40, s40, s48
	s_addc_u32 s41, s41, s49
	s_mov_b32 m0, s53
	v_lshl_add_u64 v[246:247], s[40:41], 0, v[2:3]
	ds_read_b128 v[192:195], v149 offset:32768
	ds_read_b128 v[196:199], v149 offset:33792
	ds_read_b128 v[200:203], v149 offset:34816
	ds_read_b128 v[204:207], v149 offset:35840
	ds_read_b128 v[230:233], v149 offset:36864
	ds_read_b128 v[234:237], v149 offset:37888
	ds_read_b128 v[238:241], v149 offset:38912
	ds_read_b128 v[242:245], v149 offset:39936
	global_load_lds_dwordx4 v[246:247], off
	v_lshl_add_u64 v[246:247], s[40:41], 0, v[136:137]
	s_mov_b32 m0, s72
	s_nop 0
	global_load_lds_dwordx4 v[246:247], off
	s_waitcnt vmcnt(8)
	s_waitcnt lgkmcnt(0)
	s_barrier
	s_setprio 1
	s_waitcnt lgkmcnt(0)
	v_mfma_f32_16x16x32_bf16 v[132:135], v[156:159], v[192:195], v[132:135]
	v_mfma_f32_16x16x32_bf16 v[132:135], v[160:163], v[196:199], v[132:135]
	v_mfma_f32_16x16x32_bf16 v[116:119], v[156:159], v[200:203], v[116:119]
	v_mfma_f32_16x16x32_bf16 v[116:119], v[160:163], v[204:207], v[116:119]
	v_mfma_f32_16x16x32_bf16 v[100:103], v[156:159], v[230:233], v[100:103]
	v_mfma_f32_16x16x32_bf16 v[100:103], v[160:163], v[234:237], v[100:103]
	v_mfma_f32_16x16x32_bf16 v[84:87], v[156:159], v[238:241], v[84:87]
	v_mfma_f32_16x16x32_bf16 v[84:87], v[160:163], v[242:245], v[84:87]
	v_mfma_f32_16x16x32_bf16 v[80:83], v[164:167], v[238:241], v[80:83]
	v_mfma_f32_16x16x32_bf16 v[80:83], v[168:171], v[242:245], v[80:83]
	v_mfma_f32_16x16x32_bf16 v[96:99], v[164:167], v[230:233], v[96:99]
	v_mfma_f32_16x16x32_bf16 v[96:99], v[168:171], v[234:237], v[96:99]
	v_mfma_f32_16x16x32_bf16 v[112:115], v[164:167], v[200:203], v[112:115]
	v_mfma_f32_16x16x32_bf16 v[112:115], v[168:171], v[204:207], v[112:115]
	v_mfma_f32_16x16x32_bf16 v[128:131], v[164:167], v[192:195], v[128:131]
	v_mfma_f32_16x16x32_bf16 v[128:131], v[168:171], v[196:199], v[128:131]
	s_setprio 0
	s_setprio 1
	v_mfma_f32_16x16x32_bf16 v[124:127], v[172:175], v[192:195], v[124:127]
	v_mfma_f32_16x16x32_bf16 v[124:127], v[176:179], v[196:199], v[124:127]
	v_mfma_f32_16x16x32_bf16 v[108:111], v[172:175], v[200:203], v[108:111]
	v_mfma_f32_16x16x32_bf16 v[108:111], v[176:179], v[204:207], v[108:111]
	v_mfma_f32_16x16x32_bf16 v[92:95], v[172:175], v[230:233], v[92:95]
	v_mfma_f32_16x16x32_bf16 v[92:95], v[176:179], v[234:237], v[92:95]
	v_mfma_f32_16x16x32_bf16 v[76:79], v[172:175], v[238:241], v[76:79]
	v_mfma_f32_16x16x32_bf16 v[76:79], v[176:179], v[242:245], v[76:79]
	v_mfma_f32_16x16x32_bf16 v[72:75], v[184:187], v[238:241], v[72:75]
	v_mfma_f32_16x16x32_bf16 v[72:75], v[188:191], v[242:245], v[72:75]
	v_mfma_f32_16x16x32_bf16 v[88:91], v[184:187], v[230:233], v[88:91]
	v_mfma_f32_16x16x32_bf16 v[88:91], v[188:191], v[234:237], v[88:91]
	v_mfma_f32_16x16x32_bf16 v[104:107], v[184:187], v[200:203], v[104:107]
	v_mfma_f32_16x16x32_bf16 v[104:107], v[188:191], v[204:207], v[104:107]
	v_mfma_f32_16x16x32_bf16 v[120:123], v[184:187], v[192:195], v[120:123]
	v_mfma_f32_16x16x32_bf16 v[120:123], v[188:191], v[196:199], v[120:123]
	s_setprio 0
	s_barrier
; #define PG8_STAGE(bufoff, gbase, voff) do { _Pragma("unroll") for (int _i = 0; _i < 2; ++_i) \
;         __builtin_amdgcn_global_load_lds((const unsigned*)((const char*)(gbase) + (voff)[_i]), (PG8_LAS unsigned*)(lds + (bufoff) + ldsw + _i * 8192), 16, 0, 0); } while (0)
; #define PG8_LDA(dst, b, h) do { _Pragma("unroll") for (int m = 0; m < 4; ++m) _Pragma("unroll") for (int k = 0; k < 2; ++k) dst[m][k] = *(const PG8_LAS bf16x8*)(lds + PG8_SA(b, h) + aoff + m * 2048 + k * 1024); } while (0)
; #define PG8_MMA(ai, bj, At, Bt) do { __builtin_amdgcn_s_setprio(1); _Pragma("unroll") for (int m = 0; m < 4; ++m) _Pragma("unroll") for (int n = 0; n < 2; ++n) _Pragma("unroll") for (int k = 0; k < 2; ++k) \
;         acc[ai][bj][m][n] = __builtin_amdgcn_mfma_f32_16x16x32_bf16(Bt[n][k], At[m][k], acc[ai][bj][m][n], 0, 0, 0); __builtin_amdgcn_s_setprio(0); } while (0)
; #define PG8_WAIT_V(n) asm volatile("s_waitcnt vmcnt(" #n ")" ::: "memory")
; #define PG8_WAIT_L(n) asm volatile("s_waitcnt lgkmcnt(" #n ")" ::: "memory")
; #define PG8_BAR __builtin_amdgcn_s_barrier()
; #define PG8_SCHED __builtin_amdgcn_sched_barrier(0)
; template <class Epi, class Sched, bool ALIGN_EPI = false, bool SP2 = false>
; __device__ __forceinline__ void gemm_phase(PG8_LAS unsigned char* lds, const Gemm g, const Sched& S, const Epi& E) {
;     ...
;         for (int t = 0; t < nt; t += 2) {
;     ...
;             PG8_LDA(At, 1, 1); PG8_STAGE(PG8_SB(1, 0), b3, voffB); PG8_STAGE(PG8_SB(1, 1), b3 + hstep, voffB); PG8_STAGE(PG8_SA(1, 0), a3, voffA);
;             PG8_WAIT_V(8); PG8_WAIT_L(0); PG8_BAR; PG8_MMA(1, 0, At, B0); PG8_MMA(1, 1, At, B1); PG8_BAR; PG8_SCHED;
	s_mov_b32 m0, s85
	v_lshl_add_u64 v[180:181], v[180:181], 0, s[24:25]
	ds_read_b128 v[192:195], v149 offset:49152
	ds_read_b128 v[196:199], v149 offset:50176
	ds_read_b128 v[200:203], v149 offset:51200
	ds_read_b128 v[204:207], v149 offset:52224
	ds_read_b128 v[230:233], v149 offset:53248
	ds_read_b128 v[234:237], v149 offset:54272
	ds_read_b128 v[238:241], v149 offset:55296
	ds_read_b128 v[242:245], v149 offset:56320
	global_load_lds_dwordx4 v[180:181], off
	v_lshl_add_u64 v[180:181], v[208:209], 0, s[24:25]
	s_mov_b32 m0, s86
	s_nop 0
	global_load_lds_dwordx4 v[180:181], off
	v_lshl_add_u64 v[180:181], v[216:217], 0, s[24:25]
	s_mov_b32 m0, s87
	s_nop 0
	global_load_lds_dwordx4 v[180:181], off
	v_lshl_add_u64 v[180:181], v[224:225], 0, s[24:25]
	s_mov_b32 m0, s88
	s_nop 0
	global_load_lds_dwordx4 v[180:181], off
	v_lshl_add_u64 v[180:181], v[226:227], 0, s[24:25]
	s_mov_b32 m0, s75
	s_nop 0
	global_load_lds_dwordx4 v[180:181], off
	v_lshl_add_u64 v[180:181], v[228:229], 0, s[24:25]
	s_mov_b32 m0, s76
	s_nop 0
	global_load_lds_dwordx4 v[180:181], off
	s_waitcnt vmcnt(8)
	s_waitcnt lgkmcnt(0)
	s_barrier
	s_setprio 1
	s_waitcnt lgkmcnt(0)
	v_mfma_f32_16x16x32_bf16 v[68:71], v[156:159], v[192:195], v[68:71]
	v_mfma_f32_16x16x32_bf16 v[68:71], v[160:163], v[196:199], v[68:71]
	v_mfma_f32_16x16x32_bf16 v[52:55], v[156:159], v[200:203], v[52:55]
	v_mfma_f32_16x16x32_bf16 v[52:55], v[160:163], v[204:207], v[52:55]
	v_mfma_f32_16x16x32_bf16 v[36:39], v[156:159], v[230:233], v[36:39]
	v_mfma_f32_16x16x32_bf16 v[36:39], v[160:163], v[234:237], v[36:39]
	v_mfma_f32_16x16x32_bf16 v[20:23], v[156:159], v[238:241], v[20:23]
	v_mfma_f32_16x16x32_bf16 v[20:23], v[160:163], v[242:245], v[20:23]
	v_mfma_f32_16x16x32_bf16 v[16:19], v[164:167], v[238:241], v[16:19]
	v_mfma_f32_16x16x32_bf16 v[16:19], v[168:171], v[242:245], v[16:19]
	v_mfma_f32_16x16x32_bf16 v[32:35], v[164:167], v[230:233], v[32:35]
	v_mfma_f32_16x16x32_bf16 v[32:35], v[168:171], v[234:237], v[32:35]
	v_mfma_f32_16x16x32_bf16 v[48:51], v[164:167], v[200:203], v[48:51]
	v_mfma_f32_16x16x32_bf16 v[48:51], v[168:171], v[204:207], v[48:51]
	v_mfma_f32_16x16x32_bf16 v[64:67], v[164:167], v[192:195], v[64:67]
	v_mfma_f32_16x16x32_bf16 v[64:67], v[168:171], v[196:199], v[64:67]
	s_setprio 0
	s_setprio 1
	v_mfma_f32_16x16x32_bf16 v[60:63], v[172:175], v[192:195], v[60:63]
	v_mfma_f32_16x16x32_bf16 v[60:63], v[176:179], v[196:199], v[60:63]
	v_mfma_f32_16x16x32_bf16 v[44:47], v[172:175], v[200:203], v[44:47]
	v_mfma_f32_16x16x32_bf16 v[44:47], v[176:179], v[204:207], v[44:47]
	v_mfma_f32_16x16x32_bf16 v[28:31], v[172:175], v[230:233], v[28:31]
	v_mfma_f32_16x16x32_bf16 v[28:31], v[176:179], v[234:237], v[28:31]
	v_mfma_f32_16x16x32_bf16 v[12:15], v[172:175], v[238:241], v[12:15]
	v_mfma_f32_16x16x32_bf16 v[12:15], v[176:179], v[242:245], v[12:15]
	v_mfma_f32_16x16x32_bf16 v[8:11], v[184:187], v[238:241], v[8:11]
	v_mfma_f32_16x16x32_bf16 v[8:11], v[188:191], v[242:245], v[8:11]
	v_mfma_f32_16x16x32_bf16 v[24:27], v[184:187], v[230:233], v[24:27]
	v_mfma_f32_16x16x32_bf16 v[24:27], v[188:191], v[234:237], v[24:27]
	v_mfma_f32_16x16x32_bf16 v[40:43], v[184:187], v[200:203], v[40:43]
	v_mfma_f32_16x16x32_bf16 v[40:43], v[188:191], v[204:207], v[40:43]
	v_mfma_f32_16x16x32_bf16 v[56:59], v[184:187], v[192:195], v[56:59]
	v_mfma_f32_16x16x32_bf16 v[56:59], v[188:191], v[196:199], v[56:59]
	s_setprio 0
	s_barrier
	s_add_i32 s40, s93, 2
	s_add_u32 s22, s22, 0x100
	s_addc_u32 s23, s23, 0
	s_add_u32 s89, s89, 0x100
	s_addc_u32 s92, s92, 0
	s_cmp_ge_u32 s93, s9
	v_add_u32_e32 v154, 0x100, v154
	s_cbranch_scc0 .LBB0_248

; #define PG8_STAGE(bufoff, gbase, voff) do { _Pragma("unroll") for (int _i = 0; _i < 2; ++_i) \
;         __builtin_amdgcn_global_load_lds((const unsigned*)((const char*)(gbase) + (voff)[_i]), (PG8_LAS unsigned*)(lds + (bufoff) + ldsw + _i * 8192), 16, 0, 0); } while (0)
; #define PG8_LDA(dst, b, h) do { _Pragma("unroll") for (int m = 0; m < 4; ++m) _Pragma("unroll") for (int k = 0; k < 2; ++k) dst[m][k] = *(const PG8_LAS bf16x8*)(lds + PG8_SA(b, h) + aoff + m * 2048 + k * 1024); } while (0)
; #define PG8_LDB(dst, b, h) do { _Pragma("unroll") for (int n = 0; n < 2; ++n) _Pragma("unroll") for (int k = 0; k < 2; ++k) dst[n][k] = *(const PG8_LAS bf16x8*)(lds + PG8_SB(b, h) + boff + n * 2048 + k * 1024); } while (0)
; #define PG8_MMA(ai, bj, At, Bt) do { __builtin_amdgcn_s_setprio(1); _Pragma("unroll") for (int m = 0; m < 4; ++m) _Pragma("unroll") for (int n = 0; n < 2; ++n) _Pragma("unroll") for (int k = 0; k < 2; ++k) \
;         acc[ai][bj][m][n] = __builtin_amdgcn_mfma_f32_16x16x32_bf16(Bt[n][k], At[m][k], acc[ai][bj][m][n], 0, 0, 0); __builtin_amdgcn_s_setprio(0); } while (0)
; #define PG8_WAIT_V(n) asm volatile("s_waitcnt vmcnt(" #n ")" ::: "memory")
; #define PG8_WAIT_L(n) asm volatile("s_waitcnt lgkmcnt(" #n ")" ::: "memory")
; template <class Epi, class Sched, bool ALIGN_EPI = false, bool SP2 = false>
; __device__ __forceinline__ void gemm_phase(PG8_LAS unsigned char* lds, const Gemm g, const Sched& S, const Epi& E) {
;     ...
;             const bool last = (t == nt - 2);
;             const char* a1 = cA + (size_t)(t + 1) * kstep;
;             const char* a2 = last ? nA : cA + (size_t)(t + 2) * kstep; const char* b2 = last ? nB : cB + (size_t)(t + 2) * kstep;
;             const char* a3 = a2 + kstep; const char* b3 = b2 + kstep;
;             if (last && has_next) S.a_ready(nxt);
;             if constexpr (SP2) {
;             PG8_LDB(B0, 0, 0); PG8_LDB(B1, 0, 1); PG8_SCHED; PG8_LDA(At, 0, 0); PG8_STAGE(PG8_SA(1, 1), a1 + hstep, voffA);
;             PG8_WAIT_V(8); PG8_WAIT_L(0); PG8_BAR; PG8_MMA(0, 0, At, B0); PG8_MMA(0, 1, At, B1); PG8_BAR; PG8_SCHED;
;             PG8_LDA(At, 0, 1); PG8_STAGE(PG8_SB(0, 0), b2, voffB); PG8_STAGE(PG8_SB(0, 1), b2 + hstep, voffB); PG8_STAGE(PG8_SA(0, 0), a2, voffA);
;             PG8_WAIT_V(8); PG8_WAIT_L(0); PG8_BAR; PG8_MMA(1, 0, At, B0); PG8_MMA(1, 1, At, B1); PG8_BAR; PG8_SCHED;
.LBB0_294:
	s_add_i32 s81, s40, 2
	s_add_u32 s82, s38, 0x80
	s_addc_u32 s41, s39, 0
	s_cmp_eq_u32 s33, s40
	s_cselect_b32 s41, s7, s41
	s_cselect_b32 s40, s6, s82
	v_add_u32_e32 v0, s19, v151
	s_cselect_b32 s83, s23, s80
	s_cselect_b32 s82, s22, s79
	s_add_i32 s84, 0, 0x14000
	ds_read_b128 v[154:157], v0
	ds_read_b128 v[158:161], v0 offset:1024
	ds_read_b128 v[162:165], v0 offset:2048
	ds_read_b128 v[166:169], v0 offset:3072
	v_add_u32_e32 v0, s84, v151
	ds_read_b128 v[170:173], v0
	ds_read_b128 v[174:177], v0 offset:1024
	ds_read_b128 v[178:181], v0 offset:2048
	ds_read_b128 v[184:187], v0 offset:3072
	v_lshl_add_u64 v[2:3], s[38:39], 0, v[144:145]
	s_add_i32 m0, s46, 0xc000
	ds_read_b128 v[188:191], v152
	ds_read_b128 v[192:195], v152 offset:1024
	ds_read_b128 v[196:199], v152 offset:2048
	ds_read_b128 v[200:203], v152 offset:3072
	ds_read_b128 v[204:207], v152 offset:4096
	ds_read_b128 v[230:233], v152 offset:5120
	ds_read_b128 v[234:237], v152 offset:6144
	ds_read_b128 v[238:241], v152 offset:7168
	global_load_lds_dwordx4 v[2:3], off
	v_lshl_add_u64 v[2:3], s[38:39], 0, v[146:147]
	s_add_i32 m0, s46, 0xe000
	s_nop 0
	global_load_lds_dwordx4 v[2:3], off
	s_waitcnt vmcnt(8)
	s_waitcnt lgkmcnt(0)
	s_barrier
	s_setprio 1
	s_waitcnt lgkmcnt(0)
	v_mfma_f32_16x16x32_bf16 v[8:11], v[154:157], v[188:191], v[8:11]
	v_mfma_f32_16x16x32_bf16 v[8:11], v[158:161], v[192:195], v[8:11]
	v_mfma_f32_16x16x32_bf16 v[48:51], v[154:157], v[196:199], v[48:51]
	v_mfma_f32_16x16x32_bf16 v[48:51], v[158:161], v[200:203], v[48:51]
	v_mfma_f32_16x16x32_bf16 v[96:99], v[154:157], v[204:207], v[96:99]
	v_mfma_f32_16x16x32_bf16 v[96:99], v[158:161], v[230:233], v[96:99]
	v_mfma_f32_16x16x32_bf16 v[120:123], v[154:157], v[234:237], v[120:123]
	v_mfma_f32_16x16x32_bf16 v[120:123], v[158:161], v[238:241], v[120:123]
	v_mfma_f32_16x16x32_bf16 v[124:127], v[162:165], v[234:237], v[124:127]
	v_mfma_f32_16x16x32_bf16 v[124:127], v[166:169], v[238:241], v[124:127]
	v_mfma_f32_16x16x32_bf16 v[100:103], v[162:165], v[204:207], v[100:103]
	v_mfma_f32_16x16x32_bf16 v[100:103], v[166:169], v[230:233], v[100:103]
	v_mfma_f32_16x16x32_bf16 v[52:55], v[162:165], v[196:199], v[52:55]
	v_mfma_f32_16x16x32_bf16 v[52:55], v[166:169], v[200:203], v[52:55]
	v_mfma_f32_16x16x32_bf16 v[12:15], v[162:165], v[188:191], v[12:15]
	v_mfma_f32_16x16x32_bf16 v[12:15], v[166:169], v[192:195], v[12:15]
	s_setprio 0
	s_setprio 1
	v_mfma_f32_16x16x32_bf16 v[24:27], v[170:173], v[188:191], v[24:27]
	v_mfma_f32_16x16x32_bf16 v[24:27], v[174:177], v[192:195], v[24:27]
	v_mfma_f32_16x16x32_bf16 v[72:75], v[170:173], v[196:199], v[72:75]
	v_mfma_f32_16x16x32_bf16 v[72:75], v[174:177], v[200:203], v[72:75]
	v_mfma_f32_16x16x32_bf16 v[112:115], v[170:173], v[204:207], v[112:115]
	v_mfma_f32_16x16x32_bf16 v[112:115], v[174:177], v[230:233], v[112:115]
	v_mfma_f32_16x16x32_bf16 v[128:131], v[170:173], v[234:237], v[128:131]
	v_mfma_f32_16x16x32_bf16 v[128:131], v[174:177], v[238:241], v[128:131]
	v_mfma_f32_16x16x32_bf16 v[132:135], v[178:181], v[234:237], v[132:135]
	v_mfma_f32_16x16x32_bf16 v[132:135], v[184:187], v[238:241], v[132:135]
	v_mfma_f32_16x16x32_bf16 v[116:119], v[178:181], v[204:207], v[116:119]
	v_mfma_f32_16x16x32_bf16 v[116:119], v[184:187], v[230:233], v[116:119]
	v_mfma_f32_16x16x32_bf16 v[76:79], v[178:181], v[196:199], v[76:79]
	v_mfma_f32_16x16x32_bf16 v[76:79], v[184:187], v[200:203], v[76:79]
	v_mfma_f32_16x16x32_bf16 v[28:31], v[178:181], v[188:191], v[28:31]
	v_mfma_f32_16x16x32_bf16 v[28:31], v[184:187], v[192:195], v[28:31]
	s_setprio 0
	s_barrier
	s_add_i32 s85, s19, s37
	v_lshl_add_u64 v[2:3], s[82:83], 0, v[140:141]
	s_mov_b32 m0, s85
	ds_read_b128 v[188:191], v152 offset:16384
	ds_read_b128 v[192:195], v152 offset:17408
	ds_read_b128 v[196:199], v152 offset:18432
	ds_read_b128 v[200:203], v152 offset:19456
	ds_read_b128 v[204:207], v152 offset:20480
	ds_read_b128 v[230:233], v152 offset:21504
	ds_read_b128 v[234:237], v152 offset:22528
	ds_read_b128 v[238:241], v152 offset:23552
	global_load_lds_dwordx4 v[2:3], off
	s_add_i32 m0, s85, 0x2000
	v_lshl_add_u64 v[208:209], s[82:83], 0, v[136:137]
	s_add_u32 s82, s82, s48
	s_addc_u32 s83, s83, s49
	s_add_i32 s84, s84, s37
	global_load_lds_dwordx4 v[208:209], off
	v_lshl_add_u64 v[216:217], s[82:83], 0, v[140:141]
	s_mov_b32 m0, s84
	v_lshl_add_u64 v[224:225], s[82:83], 0, v[136:137]
	global_load_lds_dwordx4 v[216:217], off
	s_add_i32 m0, s84, 0x2000
	v_lshl_add_u64 v[226:227], s[40:41], 0, v[142:143]
	global_load_lds_dwordx4 v[224:225], off
	s_mov_b32 m0, s46
	v_lshl_add_u64 v[228:229], s[40:41], 0, v[138:139]
	global_load_lds_dwordx4 v[226:227], off
	s_mov_b32 m0, s47
	s_nop 0
	global_load_lds_dwordx4 v[228:229], off
	s_waitcnt vmcnt(8)
	s_waitcnt lgkmcnt(0)
	s_barrier
; #define PG8_STAGE(bufoff, gbase, voff) do { _Pragma("unroll") for (int _i = 0; _i < 2; ++_i) \
;         __builtin_amdgcn_global_load_lds((const unsigned*)((const char*)(gbase) + (voff)[_i]), (PG8_LAS unsigned*)(lds + (bufoff) + ldsw + _i * 8192), 16, 0, 0); } while (0)
; #define PG8_LDA(dst, b, h) do { _Pragma("unroll") for (int m = 0; m < 4; ++m) _Pragma("unroll") for (int k = 0; k < 2; ++k) dst[m][k] = *(const PG8_LAS bf16x8*)(lds + PG8_SA(b, h) + aoff + m * 2048 + k * 1024); } while (0)
; #define PG8_LDB(dst, b, h) do { _Pragma("unroll") for (int n = 0; n < 2; ++n) _Pragma("unroll") for (int k = 0; k < 2; ++k) dst[n][k] = *(const PG8_LAS bf16x8*)(lds + PG8_SB(b, h) + boff + n * 2048 + k * 1024); } while (0)
; #define PG8_MMA(ai, bj, At, Bt) do { __builtin_amdgcn_s_setprio(1); _Pragma("unroll") for (int m = 0; m < 4; ++m) _Pragma("unroll") for (int n = 0; n < 2; ++n) _Pragma("unroll") for (int k = 0; k < 2; ++k) \
;         acc[ai][bj][m][n] = __builtin_amdgcn_mfma_f32_16x16x32_bf16(Bt[n][k], At[m][k], acc[ai][bj][m][n], 0, 0, 0); __builtin_amdgcn_s_setprio(0); } while (0)
; #define PG8_WAIT_V(n) asm volatile("s_waitcnt vmcnt(" #n ")" ::: "memory")
; #define PG8_WAIT_L(n) asm volatile("s_waitcnt lgkmcnt(" #n ")" ::: "memory")
; #define PG8_BAR __builtin_amdgcn_s_barrier()
; #define PG8_SCHED __builtin_amdgcn_sched_barrier(0)
; template <class Epi, class Sched, bool ALIGN_EPI = false, bool SP2 = false>
; __device__ __forceinline__ void gemm_phase(PG8_LAS unsigned char* lds, const Gemm g, const Sched& S, const Epi& E) {
;     ...
;             PG8_WAIT_V(8); PG8_WAIT_L(0); PG8_BAR; PG8_MMA(1, 0, At, B0); PG8_MMA(1, 1, At, B1); PG8_BAR; PG8_SCHED;
;             PG8_LDB(B0, 1, 0); PG8_LDB(B1, 1, 1); PG8_SCHED; PG8_LDA(At, 1, 0); PG8_STAGE(PG8_SA(0, 1), a2 + hstep, voffA);
;             PG8_WAIT_V(8); PG8_WAIT_L(0); PG8_BAR; PG8_MMA(0, 0, At, B0); PG8_MMA(0, 1, At, B1); PG8_BAR; PG8_SCHED;
	s_setprio 1
	s_waitcnt lgkmcnt(0)
	v_mfma_f32_16x16x32_bf16 v[16:19], v[154:157], v[188:191], v[16:19]
	v_mfma_f32_16x16x32_bf16 v[16:19], v[158:161], v[192:195], v[16:19]
	v_mfma_f32_16x16x32_bf16 v[56:59], v[154:157], v[196:199], v[56:59]
	v_mfma_f32_16x16x32_bf16 v[56:59], v[158:161], v[200:203], v[56:59]
	v_mfma_f32_16x16x32_bf16 v[104:107], v[154:157], v[204:207], v[104:107]
	v_mfma_f32_16x16x32_bf16 v[104:107], v[158:161], v[230:233], v[104:107]
	v_mfma_f32_16x16x32_bf16 v[68:71], v[154:157], v[234:237], v[68:71]
	v_mfma_f32_16x16x32_bf16 v[68:71], v[158:161], v[238:241], v[68:71]
	v_mfma_f32_16x16x32_bf16 v[64:67], v[162:165], v[234:237], v[64:67]
	v_mfma_f32_16x16x32_bf16 v[64:67], v[166:169], v[238:241], v[64:67]
	v_mfma_f32_16x16x32_bf16 v[108:111], v[162:165], v[204:207], v[108:111]
	v_mfma_f32_16x16x32_bf16 v[108:111], v[166:169], v[230:233], v[108:111]
	v_mfma_f32_16x16x32_bf16 v[60:63], v[162:165], v[196:199], v[60:63]
	v_mfma_f32_16x16x32_bf16 v[60:63], v[166:169], v[200:203], v[60:63]
	v_mfma_f32_16x16x32_bf16 v[20:23], v[162:165], v[188:191], v[20:23]
	v_mfma_f32_16x16x32_bf16 v[20:23], v[166:169], v[192:195], v[20:23]
	s_setprio 0
	s_setprio 1
	v_mfma_f32_16x16x32_bf16 v[40:43], v[170:173], v[188:191], v[40:43]
	v_mfma_f32_16x16x32_bf16 v[40:43], v[174:177], v[192:195], v[40:43]
	v_mfma_f32_16x16x32_bf16 v[88:91], v[170:173], v[196:199], v[88:91]
	v_mfma_f32_16x16x32_bf16 v[88:91], v[174:177], v[200:203], v[88:91]
	v_mfma_f32_16x16x32_bf16 v[84:87], v[170:173], v[204:207], v[84:87]
	v_mfma_f32_16x16x32_bf16 v[84:87], v[174:177], v[230:233], v[84:87]
	v_mfma_f32_16x16x32_bf16 v[36:39], v[170:173], v[234:237], v[36:39]
	v_mfma_f32_16x16x32_bf16 v[36:39], v[174:177], v[238:241], v[36:39]
	v_mfma_f32_16x16x32_bf16 v[32:35], v[178:181], v[234:237], v[32:35]
	v_mfma_f32_16x16x32_bf16 v[32:35], v[184:187], v[238:241], v[32:35]
	v_mfma_f32_16x16x32_bf16 v[80:83], v[178:181], v[204:207], v[80:83]
	v_mfma_f32_16x16x32_bf16 v[80:83], v[184:187], v[230:233], v[80:83]
	v_mfma_f32_16x16x32_bf16 v[92:95], v[178:181], v[196:199], v[92:95]
	v_mfma_f32_16x16x32_bf16 v[92:95], v[184:187], v[200:203], v[92:95]
	v_mfma_f32_16x16x32_bf16 v[44:47], v[178:181], v[188:191], v[44:47]
	v_mfma_f32_16x16x32_bf16 v[44:47], v[184:187], v[192:195], v[44:47]
	s_setprio 0
	s_barrier
	v_add_u32_e32 v0, s91, v151
	s_add_i32 s82, 0, 0x1c000
	ds_read_b128 v[154:157], v0
	ds_read_b128 v[158:161], v0 offset:1024
	ds_read_b128 v[162:165], v0 offset:2048
	ds_read_b128 v[166:169], v0 offset:3072
	v_add_u32_e32 v0, s82, v151
	ds_read_b128 v[170:173], v0
	ds_read_b128 v[174:177], v0 offset:1024
	ds_read_b128 v[178:181], v0 offset:2048
	ds_read_b128 v[184:187], v0 offset:3072
	s_add_u32 s40, s40, s48
	s_addc_u32 s41, s41, s49
	s_mov_b32 m0, s52
	v_lshl_add_u64 v[242:243], s[40:41], 0, v[142:143]
	ds_read_b128 v[188:191], v152 offset:32768
	ds_read_b128 v[192:195], v152 offset:33792
	ds_read_b128 v[196:199], v152 offset:34816
	ds_read_b128 v[200:203], v152 offset:35840
	ds_read_b128 v[204:207], v152 offset:36864
	ds_read_b128 v[230:233], v152 offset:37888
	ds_read_b128 v[234:237], v152 offset:38912
	ds_read_b128 v[238:241], v152 offset:39936
	global_load_lds_dwordx4 v[242:243], off
	v_lshl_add_u64 v[242:243], s[40:41], 0, v[138:139]
	s_mov_b32 m0, s53
	s_nop 0
	global_load_lds_dwordx4 v[242:243], off
	s_waitcnt vmcnt(8)
	s_waitcnt lgkmcnt(0)
	s_barrier
	s_setprio 1
	s_waitcnt lgkmcnt(0)
	v_mfma_f32_16x16x32_bf16 v[8:11], v[154:157], v[188:191], v[8:11]
	v_mfma_f32_16x16x32_bf16 v[8:11], v[158:161], v[192:195], v[8:11]
	v_mfma_f32_16x16x32_bf16 v[48:51], v[154:157], v[196:199], v[48:51]
	v_mfma_f32_16x16x32_bf16 v[48:51], v[158:161], v[200:203], v[48:51]
	v_mfma_f32_16x16x32_bf16 v[96:99], v[154:157], v[204:207], v[96:99]
	v_mfma_f32_16x16x32_bf16 v[96:99], v[158:161], v[230:233], v[96:99]
	v_mfma_f32_16x16x32_bf16 v[120:123], v[154:157], v[234:237], v[120:123]
	v_mfma_f32_16x16x32_bf16 v[120:123], v[158:161], v[238:241], v[120:123]
	v_mfma_f32_16x16x32_bf16 v[124:127], v[162:165], v[234:237], v[124:127]
	v_mfma_f32_16x16x32_bf16 v[124:127], v[166:169], v[238:241], v[124:127]
	v_mfma_f32_16x16x32_bf16 v[100:103], v[162:165], v[204:207], v[100:103]
	v_mfma_f32_16x16x32_bf16 v[100:103], v[166:169], v[230:233], v[100:103]
	v_mfma_f32_16x16x32_bf16 v[52:55], v[162:165], v[196:199], v[52:55]
	v_mfma_f32_16x16x32_bf16 v[52:55], v[166:169], v[200:203], v[52:55]
	v_mfma_f32_16x16x32_bf16 v[12:15], v[162:165], v[188:191], v[12:15]
	v_mfma_f32_16x16x32_bf16 v[12:15], v[166:169], v[192:195], v[12:15]
	s_setprio 0
	s_setprio 1
	v_mfma_f32_16x16x32_bf16 v[24:27], v[170:173], v[188:191], v[24:27]
	v_mfma_f32_16x16x32_bf16 v[24:27], v[174:177], v[192:195], v[24:27]
	v_mfma_f32_16x16x32_bf16 v[72:75], v[170:173], v[196:199], v[72:75]
	v_mfma_f32_16x16x32_bf16 v[72:75], v[174:177], v[200:203], v[72:75]
	v_mfma_f32_16x16x32_bf16 v[112:115], v[170:173], v[204:207], v[112:115]
	v_mfma_f32_16x16x32_bf16 v[112:115], v[174:177], v[230:233], v[112:115]
	v_mfma_f32_16x16x32_bf16 v[128:131], v[170:173], v[234:237], v[128:131]
	v_mfma_f32_16x16x32_bf16 v[128:131], v[174:177], v[238:241], v[128:131]
	v_mfma_f32_16x16x32_bf16 v[132:135], v[178:181], v[234:237], v[132:135]
	v_mfma_f32_16x16x32_bf16 v[132:135], v[184:187], v[238:241], v[132:135]
	v_mfma_f32_16x16x32_bf16 v[116:119], v[178:181], v[204:207], v[116:119]
	v_mfma_f32_16x16x32_bf16 v[116:119], v[184:187], v[230:233], v[116:119]
	v_mfma_f32_16x16x32_bf16 v[76:79], v[178:181], v[196:199], v[76:79]
	v_mfma_f32_16x16x32_bf16 v[76:79], v[184:187], v[200:203], v[76:79]
	v_mfma_f32_16x16x32_bf16 v[28:31], v[178:181], v[188:191], v[28:31]
	v_mfma_f32_16x16x32_bf16 v[28:31], v[184:187], v[192:195], v[28:31]
	s_setprio 0
	s_barrier
; #define PG8_STAGE(bufoff, gbase, voff) do { _Pragma("unroll") for (int _i = 0; _i < 2; ++_i) \
;         __builtin_amdgcn_global_load_lds((const unsigned*)((const char*)(gbase) + (voff)[_i]), (PG8_LAS unsigned*)(lds + (bufoff) + ldsw + _i * 8192), 16, 0, 0); } while (0)
; #define PG8_LDA(dst, b, h) do { _Pragma("unroll") for (int m = 0; m < 4; ++m) _Pragma("unroll") for (int k = 0; k < 2; ++k) dst[m][k] = *(const PG8_LAS bf16x8*)(lds + PG8_SA(b, h) + aoff + m * 2048 + k * 1024); } while (0)
; #define PG8_MMA(ai, bj, At, Bt) do { __builtin_amdgcn_s_setprio(1); _Pragma("unroll") for (int m = 0; m < 4; ++m) _Pragma("unroll") for (int n = 0; n < 2; ++n) _Pragma("unroll") for (int k = 0; k < 2; ++k) \
;         acc[ai][bj][m][n] = __builtin_amdgcn_mfma_f32_16x16x32_bf16(Bt[n][k], At[m][k], acc[ai][bj][m][n], 0, 0, 0); __builtin_amdgcn_s_setprio(0); } while (0)
; #define PG8_WAIT_V(n) asm volatile("s_waitcnt vmcnt(" #n ")" ::: "memory")
; #define PG8_WAIT_L(n) asm volatile("s_waitcnt lgkmcnt(" #n ")" ::: "memory")
; #define PG8_BAR __builtin_amdgcn_s_barrier()
; #define PG8_SCHED __builtin_amdgcn_sched_barrier(0)
; template <class Epi, class Sched, bool ALIGN_EPI = false, bool SP2 = false>
; __device__ __forceinline__ void gemm_phase(PG8_LAS unsigned char* lds, const Gemm g, const Sched& S, const Epi& E) {
;     ...
;             PG8_LDA(At, 1, 1); PG8_STAGE(PG8_SB(1, 0), b3, voffB); PG8_STAGE(PG8_SB(1, 1), b3 + hstep, voffB); PG8_STAGE(PG8_SA(1, 0), a3, voffA);
;             PG8_WAIT_V(8); PG8_WAIT_L(0); PG8_BAR; PG8_MMA(1, 0, At, B0); PG8_MMA(1, 1, At, B1); PG8_BAR; PG8_SCHED;
	s_add_i32 s40, s91, s37
	v_lshl_add_u64 v[2:3], v[2:3], 0, s[24:25]
	s_mov_b32 m0, s40
	ds_read_b128 v[188:191], v152 offset:49152
	ds_read_b128 v[192:195], v152 offset:50176
	ds_read_b128 v[196:199], v152 offset:51200
	ds_read_b128 v[200:203], v152 offset:52224
	ds_read_b128 v[204:207], v152 offset:53248
	ds_read_b128 v[230:233], v152 offset:54272
	ds_read_b128 v[234:237], v152 offset:55296
	ds_read_b128 v[238:241], v152 offset:56320
	global_load_lds_dwordx4 v[2:3], off
	v_lshl_add_u64 v[2:3], v[208:209], 0, s[24:25]
	s_add_i32 m0, s40, 0x2000
	s_add_i32 s40, s82, s37
	global_load_lds_dwordx4 v[2:3], off
	v_lshl_add_u64 v[2:3], v[216:217], 0, s[24:25]
	s_mov_b32 m0, s40
	s_nop 0
	global_load_lds_dwordx4 v[2:3], off
	v_lshl_add_u64 v[2:3], v[224:225], 0, s[24:25]
	s_add_i32 m0, s40, 0x2000
	s_nop 0
	global_load_lds_dwordx4 v[2:3], off
	v_lshl_add_u64 v[2:3], v[226:227], 0, s[24:25]
	s_mov_b32 m0, s73
	s_nop 0
	global_load_lds_dwordx4 v[2:3], off
	v_lshl_add_u64 v[2:3], v[228:229], 0, s[24:25]
	s_mov_b32 m0, s74
	s_nop 0
	global_load_lds_dwordx4 v[2:3], off
	s_waitcnt vmcnt(8)
	s_waitcnt lgkmcnt(0)
	s_barrier
	s_setprio 1
	s_waitcnt lgkmcnt(0)
	v_mfma_f32_16x16x32_bf16 v[16:19], v[154:157], v[188:191], v[16:19]
	v_mfma_f32_16x16x32_bf16 v[16:19], v[158:161], v[192:195], v[16:19]
	v_mfma_f32_16x16x32_bf16 v[56:59], v[154:157], v[196:199], v[56:59]
	v_mfma_f32_16x16x32_bf16 v[56:59], v[158:161], v[200:203], v[56:59]
	v_mfma_f32_16x16x32_bf16 v[104:107], v[154:157], v[204:207], v[104:107]
	v_mfma_f32_16x16x32_bf16 v[104:107], v[158:161], v[230:233], v[104:107]
	v_mfma_f32_16x16x32_bf16 v[68:71], v[154:157], v[234:237], v[68:71]
	v_mfma_f32_16x16x32_bf16 v[68:71], v[158:161], v[238:241], v[68:71]
	v_mfma_f32_16x16x32_bf16 v[64:67], v[162:165], v[234:237], v[64:67]
	v_mfma_f32_16x16x32_bf16 v[64:67], v[166:169], v[238:241], v[64:67]
	v_mfma_f32_16x16x32_bf16 v[108:111], v[162:165], v[204:207], v[108:111]
	v_mfma_f32_16x16x32_bf16 v[108:111], v[166:169], v[230:233], v[108:111]
	v_mfma_f32_16x16x32_bf16 v[60:63], v[162:165], v[196:199], v[60:63]
	v_mfma_f32_16x16x32_bf16 v[60:63], v[166:169], v[200:203], v[60:63]
	v_mfma_f32_16x16x32_bf16 v[20:23], v[162:165], v[188:191], v[20:23]
	v_mfma_f32_16x16x32_bf16 v[20:23], v[166:169], v[192:195], v[20:23]
	s_setprio 0
	s_setprio 1
	v_mfma_f32_16x16x32_bf16 v[40:43], v[170:173], v[188:191], v[40:43]
	v_mfma_f32_16x16x32_bf16 v[40:43], v[174:177], v[192:195], v[40:43]
	v_mfma_f32_16x16x32_bf16 v[88:91], v[170:173], v[196:199], v[88:91]
	v_mfma_f32_16x16x32_bf16 v[88:91], v[174:177], v[200:203], v[88:91]
	v_mfma_f32_16x16x32_bf16 v[84:87], v[170:173], v[204:207], v[84:87]
	v_mfma_f32_16x16x32_bf16 v[84:87], v[174:177], v[230:233], v[84:87]
	v_mfma_f32_16x16x32_bf16 v[36:39], v[170:173], v[234:237], v[36:39]
	v_mfma_f32_16x16x32_bf16 v[36:39], v[174:177], v[238:241], v[36:39]
	v_mfma_f32_16x16x32_bf16 v[32:35], v[178:181], v[234:237], v[32:35]
	v_mfma_f32_16x16x32_bf16 v[32:35], v[184:187], v[238:241], v[32:35]
	v_mfma_f32_16x16x32_bf16 v[80:83], v[178:181], v[204:207], v[80:83]
	v_mfma_f32_16x16x32_bf16 v[80:83], v[184:187], v[230:233], v[80:83]
	v_mfma_f32_16x16x32_bf16 v[92:95], v[178:181], v[196:199], v[92:95]
	v_mfma_f32_16x16x32_bf16 v[92:95], v[184:187], v[200:203], v[92:95]
	v_mfma_f32_16x16x32_bf16 v[44:47], v[178:181], v[188:191], v[44:47]
	v_mfma_f32_16x16x32_bf16 v[44:47], v[184:187], v[192:195], v[44:47]
	s_setprio 0
	s_barrier
	s_add_u32 s38, s38, 0x100
	s_addc_u32 s39, s39, 0
	s_add_u32 s79, s79, 0x100
	s_addc_u32 s80, s80, 0
	s_cmp_ge_u32 s81, s9
	s_mov_b32 s40, s81
	s_cbranch_scc0 .LBB0_294

; #define PG8_STAGE(bufoff, gbase, voff) do { _Pragma("unroll") for (int _i = 0; _i < 2; ++_i) \
;         __builtin_amdgcn_global_load_lds((const unsigned*)((const char*)(gbase) + (voff)[_i]), (PG8_LAS unsigned*)(lds + (bufoff) + ldsw + _i * 8192), 16, 0, 0); } while (0)
; #define PG8_LDA(dst, b, h) do { _Pragma("unroll") for (int m = 0; m < 4; ++m) _Pragma("unroll") for (int k = 0; k < 2; ++k) dst[m][k] = *(const PG8_LAS bf16x8*)(lds + PG8_SA(b, h) + aoff + m * 2048 + k * 1024); } while (0)
; #define PG8_LDB(dst, b, h) do { _Pragma("unroll") for (int n = 0; n < 2; ++n) _Pragma("unroll") for (int k = 0; k < 2; ++k) dst[n][k] = *(const PG8_LAS bf16x8*)(lds + PG8_SB(b, h) + boff + n * 2048 + k * 1024); } while (0)
; #define PG8_MMA(ai, bj, At, Bt) do { __builtin_amdgcn_s_setprio(1); _Pragma("unroll") for (int m = 0; m < 4; ++m) _Pragma("unroll") for (int n = 0; n < 2; ++n) _Pragma("unroll") for (int k = 0; k < 2; ++k) \
;         acc[ai][bj][m][n] = __builtin_amdgcn_mfma_f32_16x16x32_bf16(Bt[n][k], At[m][k], acc[ai][bj][m][n], 0, 0, 0); __builtin_amdgcn_s_setprio(0); } while (0)
; #define PG8_WAIT_V(n) asm volatile("s_waitcnt vmcnt(" #n ")" ::: "memory")
; #define PG8_WAIT_L(n) asm volatile("s_waitcnt lgkmcnt(" #n ")" ::: "memory")
; template <class Epi, class Sched, bool ALIGN_EPI = false, bool SP2 = false>
; __device__ __forceinline__ void gemm_phase(PG8_LAS unsigned char* lds, const Gemm g, const Sched& S, const Epi& E) {
;     ...
;             const bool last = (t == nt - 2);
;             const char* a1 = cA + (size_t)(t + 1) * kstep;
;             const char* a2 = last ? nA : cA + (size_t)(t + 2) * kstep; const char* b2 = last ? nB : cB + (size_t)(t + 2) * kstep;
;             const char* a3 = a2 + kstep; const char* b3 = b2 + kstep;
;             if (last && has_next) S.a_ready(nxt);
;             if constexpr (SP2) {
;             PG8_LDB(B0, 0, 0); PG8_LDB(B1, 0, 1); PG8_SCHED; PG8_LDA(At, 0, 0); PG8_STAGE(PG8_SA(1, 1), a1 + hstep, voffA);
;             PG8_WAIT_V(8); PG8_WAIT_L(0); PG8_BAR; PG8_MMA(0, 0, At, B0); PG8_MMA(0, 1, At, B1); PG8_BAR; PG8_SCHED;
;             PG8_LDA(At, 0, 1); PG8_STAGE(PG8_SB(0, 0), b2, voffB); PG8_STAGE(PG8_SB(0, 1), b2 + hstep, voffB); PG8_STAGE(PG8_SA(0, 0), a2, voffA);
;             PG8_WAIT_V(8); PG8_WAIT_L(0); PG8_BAR; PG8_MMA(1, 0, At, B0); PG8_MMA(1, 1, At, B1); PG8_BAR; PG8_SCHED;
.LBB0_365:
	s_add_i32 s88, s86, 2
	s_add_u32 s89, s0, 0x80
	s_addc_u32 s87, s1, 0
	s_cmp_eq_u32 s33, s86
	s_cselect_b32 s87, s3, s87
	s_cselect_b32 s86, s2, s89
	v_add_u32_e32 v0, s19, v230
	s_cselect_b32 vcc_hi, s85, s73
	s_cselect_b32 vcc_lo, s84, s72
	s_add_i32 s89, 0, 0x14000
	ds_read_b128 v[120:123], v0
	ds_read_b128 v[124:127], v0 offset:1024
	ds_read_b128 v[128:131], v0 offset:2048
	ds_read_b128 v[132:135], v0 offset:3072
	v_add_u32_e32 v0, s89, v230
	ds_read_b128 v[136:139], v0
	ds_read_b128 v[140:143], v0 offset:1024
	ds_read_b128 v[162:165], v0 offset:2048
	ds_read_b128 v[166:169], v0 offset:3072
	v_lshl_add_u64 v[144:145], s[0:1], 0, v[184:185]
	s_add_i32 m0, s93, 0xc000
	ds_read_b128 v[170:173], v238
	ds_read_b128 v[188:191], v238 offset:1024
	ds_read_b128 v[192:195], v238 offset:2048
	ds_read_b128 v[196:199], v238 offset:3072
	ds_read_b128 v[200:203], v238 offset:4096
	ds_read_b128 v[204:207], v238 offset:5120
	ds_read_b128 v[242:245], v238 offset:6144
	ds_read_b128 v[246:249], v238 offset:7168
	global_load_lds_dwordx4 v[144:145], off
	v_lshl_add_u64 v[144:145], s[0:1], 0, v[186:187]
	s_add_i32 m0, s93, 0xe000
	s_nop 0
	global_load_lds_dwordx4 v[144:145], off
	s_waitcnt vmcnt(8)
	s_waitcnt lgkmcnt(0)
	s_barrier
	s_setprio 1
	s_waitcnt lgkmcnt(0)
	v_mfma_f32_16x16x32_bf16 v[158:161], v[120:123], v[170:173], v[158:161]
	v_mfma_f32_16x16x32_bf16 v[158:161], v[124:127], v[188:191], v[158:161]
	v_mfma_f32_16x16x32_bf16 v[150:153], v[120:123], v[192:195], v[150:153]
	v_mfma_f32_16x16x32_bf16 v[150:153], v[124:127], v[196:199], v[150:153]
	v_mfma_f32_16x16x32_bf16 v[100:103], v[120:123], v[200:203], v[100:103]
	v_mfma_f32_16x16x32_bf16 v[100:103], v[124:127], v[204:207], v[100:103]
	v_mfma_f32_16x16x32_bf16 v[116:119], v[120:123], v[242:245], v[116:119]
	v_mfma_f32_16x16x32_bf16 v[116:119], v[124:127], v[246:249], v[116:119]
	v_mfma_f32_16x16x32_bf16 v[68:71], v[128:131], v[242:245], v[68:71]
	v_mfma_f32_16x16x32_bf16 v[68:71], v[132:135], v[246:249], v[68:71]
	v_mfma_f32_16x16x32_bf16 v[36:39], v[128:131], v[200:203], v[36:39]
	v_mfma_f32_16x16x32_bf16 v[36:39], v[132:135], v[204:207], v[36:39]
	v_mfma_f32_16x16x32_bf16 v[52:55], v[128:131], v[192:195], v[52:55]
	v_mfma_f32_16x16x32_bf16 v[52:55], v[132:135], v[196:199], v[52:55]
	v_mfma_f32_16x16x32_bf16 v[60:63], v[128:131], v[170:173], v[60:63]
	v_mfma_f32_16x16x32_bf16 v[60:63], v[132:135], v[188:191], v[60:63]
	s_setprio 0
	s_setprio 1
	v_mfma_f32_16x16x32_bf16 v[154:157], v[136:139], v[170:173], v[154:157]
	v_mfma_f32_16x16x32_bf16 v[154:157], v[140:143], v[188:191], v[154:157]
	v_mfma_f32_16x16x32_bf16 v[144:147], v[136:139], v[192:195], v[146:149]
	v_mfma_f32_16x16x32_bf16 v[144:147], v[140:143], v[196:199], v[144:147]
	v_mfma_f32_16x16x32_bf16 v[96:99], v[136:139], v[200:203], v[96:99]
	v_mfma_f32_16x16x32_bf16 v[96:99], v[140:143], v[204:207], v[96:99]
	v_mfma_f32_16x16x32_bf16 v[112:115], v[136:139], v[242:245], v[112:115]
	v_mfma_f32_16x16x32_bf16 v[112:115], v[140:143], v[246:249], v[112:115]
	v_mfma_f32_16x16x32_bf16 v[64:67], v[162:165], v[242:245], v[64:67]
	v_mfma_f32_16x16x32_bf16 v[64:67], v[166:169], v[246:249], v[64:67]
	v_mfma_f32_16x16x32_bf16 v[32:35], v[162:165], v[200:203], v[32:35]
	v_mfma_f32_16x16x32_bf16 v[32:35], v[166:169], v[204:207], v[32:35]
	v_mfma_f32_16x16x32_bf16 v[48:51], v[162:165], v[192:195], v[48:51]
	v_mfma_f32_16x16x32_bf16 v[48:51], v[166:169], v[196:199], v[48:51]
	v_mfma_f32_16x16x32_bf16 v[56:59], v[162:165], v[170:173], v[56:59]
	v_mfma_f32_16x16x32_bf16 v[56:59], v[166:169], v[188:191], v[56:59]
	s_setprio 0
	s_barrier
	s_add_i32 s38, s19, s92
	v_lshl_add_u64 v[174:175], vcc, 0, v[176:177]
	s_mov_b32 m0, s38
	ds_read_b128 v[170:173], v238 offset:16384
	ds_read_b128 v[188:191], v238 offset:17408
	ds_read_b128 v[192:195], v238 offset:18432
	ds_read_b128 v[196:199], v238 offset:19456
	ds_read_b128 v[200:203], v238 offset:20480
	ds_read_b128 v[204:207], v238 offset:21504
	ds_read_b128 v[242:245], v238 offset:22528
	ds_read_b128 v[246:249], v238 offset:23552
	global_load_lds_dwordx4 v[174:175], off
	s_add_i32 m0, s38, 0x2000
	v_lshl_add_u64 v[208:209], vcc, 0, v[180:181]
	s_add_u32 vcc_lo, vcc_lo, s48
	s_addc_u32 vcc_hi, vcc_hi, s49
	s_add_i32 s38, s89, s92
	global_load_lds_dwordx4 v[208:209], off
	v_lshl_add_u64 v[216:217], vcc, 0, v[176:177]
	s_mov_b32 m0, s38
	v_lshl_add_u64 v[224:225], vcc, 0, v[180:181]
	global_load_lds_dwordx4 v[216:217], off
	s_add_i32 m0, s38, 0x2000
	v_lshl_add_u64 v[226:227], s[86:87], 0, v[2:3]
	global_load_lds_dwordx4 v[224:225], off
	s_mov_b32 m0, s93
	v_lshl_add_u64 v[228:229], s[86:87], 0, v[178:179]
	global_load_lds_dwordx4 v[226:227], off
	s_mov_b32 m0, s94
	s_nop 0
	global_load_lds_dwordx4 v[228:229], off
	s_waitcnt vmcnt(8)
	s_waitcnt lgkmcnt(0)
	s_barrier
; #define PG8_STAGE(bufoff, gbase, voff) do { _Pragma("unroll") for (int _i = 0; _i < 2; ++_i) \
;         __builtin_amdgcn_global_load_lds((const unsigned*)((const char*)(gbase) + (voff)[_i]), (PG8_LAS unsigned*)(lds + (bufoff) + ldsw + _i * 8192), 16, 0, 0); } while (0)
; #define PG8_LDA(dst, b, h) do { _Pragma("unroll") for (int m = 0; m < 4; ++m) _Pragma("unroll") for (int k = 0; k < 2; ++k) dst[m][k] = *(const PG8_LAS bf16x8*)(lds + PG8_SA(b, h) + aoff + m * 2048 + k * 1024); } while (0)
; #define PG8_LDB(dst, b, h) do { _Pragma("unroll") for (int n = 0; n < 2; ++n) _Pragma("unroll") for (int k = 0; k < 2; ++k) dst[n][k] = *(const PG8_LAS bf16x8*)(lds + PG8_SB(b, h) + boff + n * 2048 + k * 1024); } while (0)
; #define PG8_MMA(ai, bj, At, Bt) do { __builtin_amdgcn_s_setprio(1); _Pragma("unroll") for (int m = 0; m < 4; ++m) _Pragma("unroll") for (int n = 0; n < 2; ++n) _Pragma("unroll") for (int k = 0; k < 2; ++k) \
;         acc[ai][bj][m][n] = __builtin_amdgcn_mfma_f32_16x16x32_bf16(Bt[n][k], At[m][k], acc[ai][bj][m][n], 0, 0, 0); __builtin_amdgcn_s_setprio(0); } while (0)
; #define PG8_WAIT_V(n) asm volatile("s_waitcnt vmcnt(" #n ")" ::: "memory")
; #define PG8_WAIT_L(n) asm volatile("s_waitcnt lgkmcnt(" #n ")" ::: "memory")
; #define PG8_BAR __builtin_amdgcn_s_barrier()
; #define PG8_SCHED __builtin_amdgcn_sched_barrier(0)
; template <class Epi, class Sched, bool ALIGN_EPI = false, bool SP2 = false>
; __device__ __forceinline__ void gemm_phase(PG8_LAS unsigned char* lds, const Gemm g, const Sched& S, const Epi& E) {
;     ...
;             PG8_WAIT_V(8); PG8_WAIT_L(0); PG8_BAR; PG8_MMA(1, 0, At, B0); PG8_MMA(1, 1, At, B1); PG8_BAR; PG8_SCHED;
;             PG8_LDB(B0, 1, 0); PG8_LDB(B1, 1, 1); PG8_SCHED; PG8_LDA(At, 1, 0); PG8_STAGE(PG8_SA(0, 1), a2 + hstep, voffA);
;             PG8_WAIT_V(8); PG8_WAIT_L(0); PG8_BAR; PG8_MMA(0, 0, At, B0); PG8_MMA(0, 1, At, B1); PG8_BAR; PG8_SCHED;
	s_setprio 1
	s_waitcnt lgkmcnt(0)
	v_mfma_f32_16x16x32_bf16 v[92:95], v[120:123], v[170:173], v[92:95]
	v_mfma_f32_16x16x32_bf16 v[92:95], v[124:127], v[188:191], v[92:95]
	v_mfma_f32_16x16x32_bf16 v[84:87], v[120:123], v[192:195], v[84:87]
	v_mfma_f32_16x16x32_bf16 v[84:87], v[124:127], v[196:199], v[84:87]
	v_mfma_f32_16x16x32_bf16 v[76:79], v[120:123], v[200:203], v[76:79]
	v_mfma_f32_16x16x32_bf16 v[76:79], v[124:127], v[204:207], v[76:79]
	v_mfma_f32_16x16x32_bf16 v[108:111], v[120:123], v[242:245], v[108:111]
	v_mfma_f32_16x16x32_bf16 v[108:111], v[124:127], v[246:249], v[108:111]
	v_mfma_f32_16x16x32_bf16 v[44:47], v[128:131], v[242:245], v[44:47]
	v_mfma_f32_16x16x32_bf16 v[44:47], v[132:135], v[246:249], v[44:47]
	v_mfma_f32_16x16x32_bf16 v[12:15], v[128:131], v[200:203], v[12:15]
	v_mfma_f32_16x16x32_bf16 v[12:15], v[132:135], v[204:207], v[12:15]
	v_mfma_f32_16x16x32_bf16 v[20:23], v[128:131], v[192:195], v[20:23]
	v_mfma_f32_16x16x32_bf16 v[20:23], v[132:135], v[196:199], v[20:23]
	v_mfma_f32_16x16x32_bf16 v[28:31], v[128:131], v[170:173], v[28:31]
	v_mfma_f32_16x16x32_bf16 v[28:31], v[132:135], v[188:191], v[28:31]
	s_setprio 0
	s_setprio 1
	v_mfma_f32_16x16x32_bf16 v[88:91], v[136:139], v[170:173], v[88:91]
	v_mfma_f32_16x16x32_bf16 v[88:91], v[140:143], v[188:191], v[88:91]
	v_mfma_f32_16x16x32_bf16 v[80:83], v[136:139], v[192:195], v[80:83]
	v_mfma_f32_16x16x32_bf16 v[80:83], v[140:143], v[196:199], v[80:83]
	v_mfma_f32_16x16x32_bf16 v[72:75], v[136:139], v[200:203], v[72:75]
	v_mfma_f32_16x16x32_bf16 v[72:75], v[140:143], v[204:207], v[72:75]
	v_mfma_f32_16x16x32_bf16 v[104:107], v[136:139], v[242:245], v[104:107]
	v_mfma_f32_16x16x32_bf16 v[104:107], v[140:143], v[246:249], v[104:107]
	v_mfma_f32_16x16x32_bf16 v[40:43], v[162:165], v[242:245], v[40:43]
	v_mfma_f32_16x16x32_bf16 v[40:43], v[166:169], v[246:249], v[40:43]
	v_mfma_f32_16x16x32_bf16 v[8:11], v[162:165], v[200:203], v[8:11]
	v_mfma_f32_16x16x32_bf16 v[8:11], v[166:169], v[204:207], v[8:11]
	v_mfma_f32_16x16x32_bf16 v[16:19], v[162:165], v[192:195], v[16:19]
	v_mfma_f32_16x16x32_bf16 v[16:19], v[166:169], v[196:199], v[16:19]
	v_mfma_f32_16x16x32_bf16 v[24:27], v[162:165], v[170:173], v[24:27]
	v_mfma_f32_16x16x32_bf16 v[24:27], v[166:169], v[188:191], v[24:27]
	s_setprio 0
	s_barrier
	v_add_u32_e32 v0, s91, v230
	s_add_i32 s38, 0, 0x1c000
	ds_read_b128 v[120:123], v0
	ds_read_b128 v[124:127], v0 offset:1024
	ds_read_b128 v[128:131], v0 offset:2048
	ds_read_b128 v[132:135], v0 offset:3072
	v_add_u32_e32 v0, s38, v230
	ds_read_b128 v[136:139], v0
	ds_read_b128 v[140:143], v0 offset:1024
	ds_read_b128 v[162:165], v0 offset:2048
	ds_read_b128 v[166:169], v0 offset:3072
	s_add_u32 s86, s86, s48
	s_addc_u32 s87, s87, s49
	s_mov_b32 m0, s95
	v_lshl_add_u64 v[148:149], s[86:87], 0, v[2:3]
	ds_read_b128 v[170:173], v238 offset:32768
	ds_read_b128 v[188:191], v238 offset:33792
	ds_read_b128 v[192:195], v238 offset:34816
	ds_read_b128 v[196:199], v238 offset:35840
	ds_read_b128 v[200:203], v238 offset:36864
	ds_read_b128 v[204:207], v238 offset:37888
	ds_read_b128 v[242:245], v238 offset:38912
	ds_read_b128 v[246:249], v238 offset:39936
	global_load_lds_dwordx4 v[148:149], off
	v_lshl_add_u64 v[148:149], s[86:87], 0, v[178:179]
	s_mov_b32 m0, s96
	s_nop 0
	global_load_lds_dwordx4 v[148:149], off
	s_waitcnt vmcnt(8)
	s_waitcnt lgkmcnt(0)
	s_barrier
	s_setprio 1
	s_waitcnt lgkmcnt(0)
	v_mfma_f32_16x16x32_bf16 v[158:161], v[120:123], v[170:173], v[158:161]
	v_mfma_f32_16x16x32_bf16 v[158:161], v[124:127], v[188:191], v[158:161]
	v_mfma_f32_16x16x32_bf16 v[148:151], v[120:123], v[192:195], v[150:153]
	v_mfma_f32_16x16x32_bf16 v[150:153], v[124:127], v[196:199], v[148:151]
	v_mfma_f32_16x16x32_bf16 v[100:103], v[120:123], v[200:203], v[100:103]
	v_mfma_f32_16x16x32_bf16 v[100:103], v[124:127], v[204:207], v[100:103]
	v_mfma_f32_16x16x32_bf16 v[116:119], v[120:123], v[242:245], v[116:119]
	v_mfma_f32_16x16x32_bf16 v[116:119], v[124:127], v[246:249], v[116:119]
	v_mfma_f32_16x16x32_bf16 v[68:71], v[128:131], v[242:245], v[68:71]
	v_mfma_f32_16x16x32_bf16 v[68:71], v[132:135], v[246:249], v[68:71]
	v_mfma_f32_16x16x32_bf16 v[36:39], v[128:131], v[200:203], v[36:39]
	v_mfma_f32_16x16x32_bf16 v[36:39], v[132:135], v[204:207], v[36:39]
	v_mfma_f32_16x16x32_bf16 v[52:55], v[128:131], v[192:195], v[52:55]
	v_mfma_f32_16x16x32_bf16 v[52:55], v[132:135], v[196:199], v[52:55]
	v_mfma_f32_16x16x32_bf16 v[60:63], v[128:131], v[170:173], v[60:63]
	v_mfma_f32_16x16x32_bf16 v[60:63], v[132:135], v[188:191], v[60:63]
	s_setprio 0
	s_setprio 1
	v_mfma_f32_16x16x32_bf16 v[154:157], v[136:139], v[170:173], v[154:157]
	v_mfma_f32_16x16x32_bf16 v[154:157], v[140:143], v[188:191], v[154:157]
	v_mfma_f32_16x16x32_bf16 v[144:147], v[136:139], v[192:195], v[144:147]
	v_mfma_f32_16x16x32_bf16 v[146:149], v[140:143], v[196:199], v[144:147]
	v_mfma_f32_16x16x32_bf16 v[96:99], v[136:139], v[200:203], v[96:99]
	v_mfma_f32_16x16x32_bf16 v[96:99], v[140:143], v[204:207], v[96:99]
	v_mfma_f32_16x16x32_bf16 v[112:115], v[136:139], v[242:245], v[112:115]
	v_mfma_f32_16x16x32_bf16 v[112:115], v[140:143], v[246:249], v[112:115]
	v_mfma_f32_16x16x32_bf16 v[64:67], v[162:165], v[242:245], v[64:67]
	v_mfma_f32_16x16x32_bf16 v[64:67], v[166:169], v[246:249], v[64:67]
	v_mfma_f32_16x16x32_bf16 v[32:35], v[162:165], v[200:203], v[32:35]
	v_mfma_f32_16x16x32_bf16 v[32:35], v[166:169], v[204:207], v[32:35]
	v_mfma_f32_16x16x32_bf16 v[48:51], v[162:165], v[192:195], v[48:51]
	v_mfma_f32_16x16x32_bf16 v[48:51], v[166:169], v[196:199], v[48:51]
	v_mfma_f32_16x16x32_bf16 v[56:59], v[162:165], v[170:173], v[56:59]
	v_mfma_f32_16x16x32_bf16 v[56:59], v[166:169], v[188:191], v[56:59]
	s_setprio 0
	s_barrier
; #define PG8_STAGE(bufoff, gbase, voff) do { _Pragma("unroll") for (int _i = 0; _i < 2; ++_i) \
;         __builtin_amdgcn_global_load_lds((const unsigned*)((const char*)(gbase) + (voff)[_i]), (PG8_LAS unsigned*)(lds + (bufoff) + ldsw + _i * 8192), 16, 0, 0); } while (0)
; #define PG8_LDA(dst, b, h) do { _Pragma("unroll") for (int m = 0; m < 4; ++m) _Pragma("unroll") for (int k = 0; k < 2; ++k) dst[m][k] = *(const PG8_LAS bf16x8*)(lds + PG8_SA(b, h) + aoff + m * 2048 + k * 1024); } while (0)
; #define PG8_MMA(ai, bj, At, Bt) do { __builtin_amdgcn_s_setprio(1); _Pragma("unroll") for (int m = 0; m < 4; ++m) _Pragma("unroll") for (int n = 0; n < 2; ++n) _Pragma("unroll") for (int k = 0; k < 2; ++k) \
;         acc[ai][bj][m][n] = __builtin_amdgcn_mfma_f32_16x16x32_bf16(Bt[n][k], At[m][k], acc[ai][bj][m][n], 0, 0, 0); __builtin_amdgcn_s_setprio(0); } while (0)
; #define PG8_WAIT_V(n) asm volatile("s_waitcnt vmcnt(" #n ")" ::: "memory")
; #define PG8_WAIT_L(n) asm volatile("s_waitcnt lgkmcnt(" #n ")" ::: "memory")
; #define PG8_BAR __builtin_amdgcn_s_barrier()
; #define PG8_SCHED __builtin_amdgcn_sched_barrier(0)
; template <class Epi, class Sched, bool ALIGN_EPI = false, bool SP2 = false>
; __device__ __forceinline__ void gemm_phase(PG8_LAS unsigned char* lds, const Gemm g, const Sched& S, const Epi& E) {
;     ...
;             PG8_LDA(At, 1, 1); PG8_STAGE(PG8_SB(1, 0), b3, voffB); PG8_STAGE(PG8_SB(1, 1), b3 + hstep, voffB); PG8_STAGE(PG8_SA(1, 0), a3, voffA);
;             PG8_WAIT_V(8); PG8_WAIT_L(0); PG8_BAR; PG8_MMA(1, 0, At, B0); PG8_MMA(1, 1, At, B1); PG8_BAR; PG8_SCHED;
	s_add_i32 s39, s91, s92
	v_lshl_add_u64 v[144:145], v[174:175], 0, s[24:25]
	s_mov_b32 m0, s39
	ds_read_b128 v[170:173], v238 offset:49152
	ds_read_b128 v[188:191], v238 offset:50176
	ds_read_b128 v[192:195], v238 offset:51200
	ds_read_b128 v[196:199], v238 offset:52224
	ds_read_b128 v[200:203], v238 offset:53248
	ds_read_b128 v[204:207], v238 offset:54272
	ds_read_b128 v[242:245], v238 offset:55296
	ds_read_b128 v[246:249], v238 offset:56320
	global_load_lds_dwordx4 v[144:145], off
	v_lshl_add_u64 v[144:145], v[208:209], 0, s[24:25]
	s_add_i32 m0, s39, 0x2000
	s_add_i32 s38, s38, s92
	global_load_lds_dwordx4 v[144:145], off
	v_lshl_add_u64 v[144:145], v[216:217], 0, s[24:25]
	s_mov_b32 m0, s38
	s_nop 0
	global_load_lds_dwordx4 v[144:145], off
	v_lshl_add_u64 v[144:145], v[224:225], 0, s[24:25]
	s_add_i32 m0, s38, 0x2000
	s_nop 0
	global_load_lds_dwordx4 v[144:145], off
	v_lshl_add_u64 v[144:145], v[226:227], 0, s[24:25]
	s_mov_b32 m0, s10
	s_nop 0
	global_load_lds_dwordx4 v[144:145], off
	v_lshl_add_u64 v[144:145], v[228:229], 0, s[24:25]
	s_mov_b32 m0, s11
	s_nop 0
	global_load_lds_dwordx4 v[144:145], off
	s_waitcnt vmcnt(8)
	s_waitcnt lgkmcnt(0)
	s_barrier
	s_setprio 1
	s_waitcnt lgkmcnt(0)
	v_mfma_f32_16x16x32_bf16 v[92:95], v[120:123], v[170:173], v[92:95]
	v_mfma_f32_16x16x32_bf16 v[92:95], v[124:127], v[188:191], v[92:95]
	v_mfma_f32_16x16x32_bf16 v[84:87], v[120:123], v[192:195], v[84:87]
	v_mfma_f32_16x16x32_bf16 v[84:87], v[124:127], v[196:199], v[84:87]
	v_mfma_f32_16x16x32_bf16 v[76:79], v[120:123], v[200:203], v[76:79]
	v_mfma_f32_16x16x32_bf16 v[76:79], v[124:127], v[204:207], v[76:79]
	v_mfma_f32_16x16x32_bf16 v[108:111], v[120:123], v[242:245], v[108:111]
	v_mfma_f32_16x16x32_bf16 v[108:111], v[124:127], v[246:249], v[108:111]
	v_mfma_f32_16x16x32_bf16 v[44:47], v[128:131], v[242:245], v[44:47]
	v_mfma_f32_16x16x32_bf16 v[44:47], v[132:135], v[246:249], v[44:47]
	v_mfma_f32_16x16x32_bf16 v[12:15], v[128:131], v[200:203], v[12:15]
	v_mfma_f32_16x16x32_bf16 v[12:15], v[132:135], v[204:207], v[12:15]
	v_mfma_f32_16x16x32_bf16 v[20:23], v[128:131], v[192:195], v[20:23]
	v_mfma_f32_16x16x32_bf16 v[20:23], v[132:135], v[196:199], v[20:23]
	v_mfma_f32_16x16x32_bf16 v[28:31], v[128:131], v[170:173], v[28:31]
	v_mfma_f32_16x16x32_bf16 v[28:31], v[132:135], v[188:191], v[28:31]
	s_setprio 0
	s_setprio 1
	v_mfma_f32_16x16x32_bf16 v[88:91], v[136:139], v[170:173], v[88:91]
	v_mfma_f32_16x16x32_bf16 v[88:91], v[140:143], v[188:191], v[88:91]
	v_mfma_f32_16x16x32_bf16 v[80:83], v[136:139], v[192:195], v[80:83]
	v_mfma_f32_16x16x32_bf16 v[80:83], v[140:143], v[196:199], v[80:83]
	v_mfma_f32_16x16x32_bf16 v[72:75], v[136:139], v[200:203], v[72:75]
	v_mfma_f32_16x16x32_bf16 v[72:75], v[140:143], v[204:207], v[72:75]
	v_mfma_f32_16x16x32_bf16 v[104:107], v[136:139], v[242:245], v[104:107]
	v_mfma_f32_16x16x32_bf16 v[104:107], v[140:143], v[246:249], v[104:107]
	v_mfma_f32_16x16x32_bf16 v[40:43], v[162:165], v[242:245], v[40:43]
	v_mfma_f32_16x16x32_bf16 v[40:43], v[166:169], v[246:249], v[40:43]
	v_mfma_f32_16x16x32_bf16 v[8:11], v[162:165], v[200:203], v[8:11]
	v_mfma_f32_16x16x32_bf16 v[8:11], v[166:169], v[204:207], v[8:11]
	v_mfma_f32_16x16x32_bf16 v[16:19], v[162:165], v[192:195], v[16:19]
	v_mfma_f32_16x16x32_bf16 v[16:19], v[166:169], v[196:199], v[16:19]
	v_mfma_f32_16x16x32_bf16 v[24:27], v[162:165], v[170:173], v[24:27]
	v_mfma_f32_16x16x32_bf16 v[24:27], v[166:169], v[188:191], v[24:27]
	s_setprio 0
	s_barrier
	s_add_u32 s0, s0, 0x100
	s_addc_u32 s1, s1, 0
	s_add_u32 s72, s72, 0x100
	s_addc_u32 s73, s73, 0
	s_cmp_ge_u32 s88, s9
	s_mov_b32 s86, s88
	s_cbranch_scc0 .LBB0_365

; #define PG8_STAGE(bufoff, gbase, voff) do { _Pragma("unroll") for (int _i = 0; _i < 2; ++_i) \
;         __builtin_amdgcn_global_load_lds((const unsigned*)((const char*)(gbase) + (voff)[_i]), (PG8_LAS unsigned*)(lds + (bufoff) + ldsw + _i * 8192), 16, 0, 0); } while (0)
; #define PG8_LDA(dst, b, h) do { _Pragma("unroll") for (int m = 0; m < 4; ++m) _Pragma("unroll") for (int k = 0; k < 2; ++k) dst[m][k] = *(const PG8_LAS bf16x8*)(lds + PG8_SA(b, h) + aoff + m * 2048 + k * 1024); } while (0)
; #define PG8_LDB(dst, b, h) do { _Pragma("unroll") for (int n = 0; n < 2; ++n) _Pragma("unroll") for (int k = 0; k < 2; ++k) dst[n][k] = *(const PG8_LAS bf16x8*)(lds + PG8_SB(b, h) + boff + n * 2048 + k * 1024); } while (0)
; #define PG8_MMA(ai, bj, At, Bt) do { __builtin_amdgcn_s_setprio(1); _Pragma("unroll") for (int m = 0; m < 4; ++m) _Pragma("unroll") for (int n = 0; n < 2; ++n) _Pragma("unroll") for (int k = 0; k < 2; ++k) \
;         acc[ai][bj][m][n] = __builtin_amdgcn_mfma_f32_16x16x32_bf16(Bt[n][k], At[m][k], acc[ai][bj][m][n], 0, 0, 0); __builtin_amdgcn_s_setprio(0); } while (0)
; #define PG8_WAIT_V(n) asm volatile("s_waitcnt vmcnt(" #n ")" ::: "memory")
; #define PG8_WAIT_L(n) asm volatile("s_waitcnt lgkmcnt(" #n ")" ::: "memory")
; #define PG8_BAR __builtin_amdgcn_s_barrier()
; #define PG8_SCHED __builtin_amdgcn_sched_barrier(0)
; template <class Epi, class Sched, bool ALIGN_EPI = false, bool SP2 = false>
; __device__ __forceinline__ void gemm_phase(PG8_LAS unsigned char* lds, const Gemm g, const Sched& S, const Epi& E) {
;     ...
;             const bool last = (t == nt - 2);
;             const char* a1 = cA + (size_t)(t + 1) * kstep;
;             const char* a2 = last ? nA : cA + (size_t)(t + 2) * kstep; const char* b2 = last ? nB : cB + (size_t)(t + 2) * kstep;
;             const char* a3 = a2 + kstep; const char* b3 = b2 + kstep;
;             if (last && has_next) S.a_ready(nxt);
;             if constexpr (SP2) {
;             PG8_LDB(B0, 0, 0); PG8_LDB(B1, 0, 1); PG8_SCHED; PG8_LDA(At, 0, 0); PG8_STAGE(PG8_SA(1, 1), a1 + hstep, voffA);
;             PG8_WAIT_V(8); PG8_WAIT_L(0); PG8_BAR; PG8_MMA(0, 0, At, B0); PG8_MMA(0, 1, At, B1); PG8_BAR; PG8_SCHED;
;             PG8_LDA(At, 0, 1); PG8_STAGE(PG8_SB(0, 0), b2, voffB); PG8_STAGE(PG8_SB(0, 1), b2 + hstep, voffB); PG8_STAGE(PG8_SA(0, 0), a2, voffA);
.LBB0_468:
	s_add_i32 s78, s38, 2
	s_add_u32 s79, s0, 0x80
	s_addc_u32 s39, s1, 0
	s_cmp_eq_u32 s33, s38
	s_cselect_b32 s39, s7, s39
	s_cselect_b32 s38, s6, s79
	s_cselect_b32 s81, s23, s41
	s_cselect_b32 s80, s22, s40
	s_add_i32 s79, 0, 0x14000
	v_add_u32_e32 v148, s19, v162
	v_add_u32_e32 v171, s79, v162
	ds_read_b128 v[136:139], v148
	ds_read_b128 v[140:143], v148 offset:1024
	ds_read_b128 v[144:147], v148 offset:2048
	ds_read_b128 v[148:151], v148 offset:3072
	ds_read_b128 v[172:175], v171
	ds_read_b128 v[176:179], v171 offset:1024
	ds_read_b128 v[184:187], v171 offset:2048
	ds_read_b128 v[188:191], v171 offset:3072
	v_lshl_add_u64 v[180:181], s[0:1], 0, v[158:159]
	s_add_i32 m0, s46, 0xc000
	ds_read_b128 v[192:195], v167
	ds_read_b128 v[196:199], v167 offset:1024
	ds_read_b128 v[200:203], v167 offset:2048
	ds_read_b128 v[204:207], v167 offset:3072
	ds_read_b128 v[230:233], v167 offset:4096
	ds_read_b128 v[234:237], v167 offset:5120
	ds_read_b128 v[238:241], v167 offset:6144
	ds_read_b128 v[242:245], v167 offset:7168
	global_load_lds_dwordx4 v[180:181], off
	v_lshl_add_u64 v[180:181], s[0:1], 0, v[160:161]
	s_add_i32 m0, s46, 0xe000
	s_nop 0
	global_load_lds_dwordx4 v[180:181], off
	s_waitcnt vmcnt(8)
	s_waitcnt lgkmcnt(0)
	s_barrier
	s_setprio 1
	s_waitcnt lgkmcnt(0)
	v_mfma_f32_16x16x32_bf16 v[132:135], v[136:139], v[192:195], v[132:135]
	v_mfma_f32_16x16x32_bf16 v[132:135], v[140:143], v[196:199], v[132:135]
	v_mfma_f32_16x16x32_bf16 v[116:119], v[136:139], v[200:203], v[116:119]
	v_mfma_f32_16x16x32_bf16 v[116:119], v[140:143], v[204:207], v[116:119]
	v_mfma_f32_16x16x32_bf16 v[100:103], v[136:139], v[230:233], v[100:103]
	v_mfma_f32_16x16x32_bf16 v[100:103], v[140:143], v[234:237], v[100:103]
	v_mfma_f32_16x16x32_bf16 v[84:87], v[136:139], v[238:241], v[84:87]
	v_mfma_f32_16x16x32_bf16 v[84:87], v[140:143], v[242:245], v[84:87]
	v_mfma_f32_16x16x32_bf16 v[80:83], v[144:147], v[238:241], v[80:83]
	v_mfma_f32_16x16x32_bf16 v[80:83], v[148:151], v[242:245], v[80:83]
	v_mfma_f32_16x16x32_bf16 v[96:99], v[144:147], v[230:233], v[96:99]
	v_mfma_f32_16x16x32_bf16 v[96:99], v[148:151], v[234:237], v[96:99]
	v_mfma_f32_16x16x32_bf16 v[112:115], v[144:147], v[200:203], v[112:115]
	v_mfma_f32_16x16x32_bf16 v[112:115], v[148:151], v[204:207], v[112:115]
	v_mfma_f32_16x16x32_bf16 v[128:131], v[144:147], v[192:195], v[128:131]
	v_mfma_f32_16x16x32_bf16 v[128:131], v[148:151], v[196:199], v[128:131]
	s_setprio 0
	s_setprio 1
	v_mfma_f32_16x16x32_bf16 v[124:127], v[172:175], v[192:195], v[124:127]
	v_mfma_f32_16x16x32_bf16 v[124:127], v[176:179], v[196:199], v[124:127]
	v_mfma_f32_16x16x32_bf16 v[108:111], v[172:175], v[200:203], v[108:111]
	v_mfma_f32_16x16x32_bf16 v[108:111], v[176:179], v[204:207], v[108:111]
	v_mfma_f32_16x16x32_bf16 v[92:95], v[172:175], v[230:233], v[92:95]
	v_mfma_f32_16x16x32_bf16 v[92:95], v[176:179], v[234:237], v[92:95]
	v_mfma_f32_16x16x32_bf16 v[76:79], v[172:175], v[238:241], v[76:79]
	v_mfma_f32_16x16x32_bf16 v[76:79], v[176:179], v[242:245], v[76:79]
	v_mfma_f32_16x16x32_bf16 v[72:75], v[184:187], v[238:241], v[72:75]
	v_mfma_f32_16x16x32_bf16 v[72:75], v[188:191], v[242:245], v[72:75]
	v_mfma_f32_16x16x32_bf16 v[88:91], v[184:187], v[230:233], v[88:91]
	v_mfma_f32_16x16x32_bf16 v[88:91], v[188:191], v[234:237], v[88:91]
	v_mfma_f32_16x16x32_bf16 v[104:107], v[184:187], v[200:203], v[104:107]
	v_mfma_f32_16x16x32_bf16 v[104:107], v[188:191], v[204:207], v[104:107]
	v_mfma_f32_16x16x32_bf16 v[120:123], v[184:187], v[192:195], v[120:123]
	v_mfma_f32_16x16x32_bf16 v[120:123], v[188:191], v[196:199], v[120:123]
	s_setprio 0
	s_barrier
	s_add_i32 s82, s19, s42
	v_lshl_add_u64 v[180:181], s[80:81], 0, v[154:155]
	s_mov_b32 m0, s82
	ds_read_b128 v[192:195], v167 offset:16384
	ds_read_b128 v[196:199], v167 offset:17408
	ds_read_b128 v[200:203], v167 offset:18432
	ds_read_b128 v[204:207], v167 offset:19456
	ds_read_b128 v[230:233], v167 offset:20480
	ds_read_b128 v[234:237], v167 offset:21504
	ds_read_b128 v[238:241], v167 offset:22528
	ds_read_b128 v[242:245], v167 offset:23552
	global_load_lds_dwordx4 v[180:181], off
	s_add_i32 m0, s82, 0x2000
	v_lshl_add_u64 v[208:209], s[80:81], 0, v[2:3]
	s_add_u32 s80, s80, s48
	s_addc_u32 s81, s81, s49
	s_add_i32 s79, s79, s42
	global_load_lds_dwordx4 v[208:209], off
	v_lshl_add_u64 v[216:217], s[80:81], 0, v[154:155]
	s_mov_b32 m0, s79
	v_lshl_add_u64 v[224:225], s[80:81], 0, v[2:3]
	global_load_lds_dwordx4 v[216:217], off
	s_add_i32 m0, s79, 0x2000
	v_lshl_add_u64 v[226:227], s[38:39], 0, v[156:157]
	global_load_lds_dwordx4 v[224:225], off
	s_mov_b32 m0, s46
	v_lshl_add_u64 v[246:247], s[38:39], 0, v[152:153]
	global_load_lds_dwordx4 v[226:227], off
	s_mov_b32 m0, s47
	s_nop 0
	global_load_lds_dwordx4 v[246:247], off
	s_waitcnt vmcnt(8)
	s_waitcnt lgkmcnt(0)
	s_barrier
; #define PG8_STAGE(bufoff, gbase, voff) do { _Pragma("unroll") for (int _i = 0; _i < 2; ++_i) \
;         __builtin_amdgcn_global_load_lds((const unsigned*)((const char*)(gbase) + (voff)[_i]), (PG8_LAS unsigned*)(lds + (bufoff) + ldsw + _i * 8192), 16, 0, 0); } while (0)
; #define PG8_LDA(dst, b, h) do { _Pragma("unroll") for (int m = 0; m < 4; ++m) _Pragma("unroll") for (int k = 0; k < 2; ++k) dst[m][k] = *(const PG8_LAS bf16x8*)(lds + PG8_SA(b, h) + aoff + m * 2048 + k * 1024); } while (0)
; #define PG8_LDB(dst, b, h) do { _Pragma("unroll") for (int n = 0; n < 2; ++n) _Pragma("unroll") for (int k = 0; k < 2; ++k) dst[n][k] = *(const PG8_LAS bf16x8*)(lds + PG8_SB(b, h) + boff + n * 2048 + k * 1024); } while (0)
; #define PG8_MMA(ai, bj, At, Bt) do { __builtin_amdgcn_s_setprio(1); _Pragma("unroll") for (int m = 0; m < 4; ++m) _Pragma("unroll") for (int n = 0; n < 2; ++n) _Pragma("unroll") for (int k = 0; k < 2; ++k) \
;         acc[ai][bj][m][n] = __builtin_amdgcn_mfma_f32_16x16x32_bf16(Bt[n][k], At[m][k], acc[ai][bj][m][n], 0, 0, 0); __builtin_amdgcn_s_setprio(0); } while (0)
; #define PG8_WAIT_V(n) asm volatile("s_waitcnt vmcnt(" #n ")" ::: "memory")
; #define PG8_WAIT_L(n) asm volatile("s_waitcnt lgkmcnt(" #n ")" ::: "memory")
; #define PG8_BAR __builtin_amdgcn_s_barrier()
; #define PG8_SCHED __builtin_amdgcn_sched_barrier(0)
; template <class Epi, class Sched, bool ALIGN_EPI = false, bool SP2 = false>
; __device__ __forceinline__ void gemm_phase(PG8_LAS unsigned char* lds, const Gemm g, const Sched& S, const Epi& E) {
;     ...
;             PG8_WAIT_V(8); PG8_WAIT_L(0); PG8_BAR; PG8_MMA(1, 0, At, B0); PG8_MMA(1, 1, At, B1); PG8_BAR; PG8_SCHED;
;             PG8_LDB(B0, 1, 0); PG8_LDB(B1, 1, 1); PG8_SCHED; PG8_LDA(At, 1, 0); PG8_STAGE(PG8_SA(0, 1), a2 + hstep, voffA);
;             PG8_WAIT_V(8); PG8_WAIT_L(0); PG8_BAR; PG8_MMA(0, 0, At, B0); PG8_MMA(0, 1, At, B1); PG8_BAR; PG8_SCHED;
	s_setprio 1
	s_waitcnt lgkmcnt(0)
	v_mfma_f32_16x16x32_bf16 v[68:71], v[136:139], v[192:195], v[68:71]
	v_mfma_f32_16x16x32_bf16 v[68:71], v[140:143], v[196:199], v[68:71]
	v_mfma_f32_16x16x32_bf16 v[52:55], v[136:139], v[200:203], v[52:55]
	v_mfma_f32_16x16x32_bf16 v[52:55], v[140:143], v[204:207], v[52:55]
	v_mfma_f32_16x16x32_bf16 v[36:39], v[136:139], v[230:233], v[36:39]
	v_mfma_f32_16x16x32_bf16 v[36:39], v[140:143], v[234:237], v[36:39]
	v_mfma_f32_16x16x32_bf16 v[20:23], v[136:139], v[238:241], v[20:23]
	v_mfma_f32_16x16x32_bf16 v[20:23], v[140:143], v[242:245], v[20:23]
	v_mfma_f32_16x16x32_bf16 v[16:19], v[144:147], v[238:241], v[16:19]
	v_mfma_f32_16x16x32_bf16 v[16:19], v[148:151], v[242:245], v[16:19]
	v_mfma_f32_16x16x32_bf16 v[32:35], v[144:147], v[230:233], v[32:35]
	v_mfma_f32_16x16x32_bf16 v[32:35], v[148:151], v[234:237], v[32:35]
	v_mfma_f32_16x16x32_bf16 v[48:51], v[144:147], v[200:203], v[48:51]
	v_mfma_f32_16x16x32_bf16 v[48:51], v[148:151], v[204:207], v[48:51]
	v_mfma_f32_16x16x32_bf16 v[64:67], v[144:147], v[192:195], v[64:67]
	v_mfma_f32_16x16x32_bf16 v[64:67], v[148:151], v[196:199], v[64:67]
	s_setprio 0
	s_setprio 1
	v_mfma_f32_16x16x32_bf16 v[60:63], v[172:175], v[192:195], v[60:63]
	v_mfma_f32_16x16x32_bf16 v[60:63], v[176:179], v[196:199], v[60:63]
	v_mfma_f32_16x16x32_bf16 v[44:47], v[172:175], v[200:203], v[44:47]
	v_mfma_f32_16x16x32_bf16 v[44:47], v[176:179], v[204:207], v[44:47]
	v_mfma_f32_16x16x32_bf16 v[28:31], v[172:175], v[230:233], v[28:31]
	v_mfma_f32_16x16x32_bf16 v[28:31], v[176:179], v[234:237], v[28:31]
	v_mfma_f32_16x16x32_bf16 v[12:15], v[172:175], v[238:241], v[12:15]
	v_mfma_f32_16x16x32_bf16 v[12:15], v[176:179], v[242:245], v[12:15]
	v_mfma_f32_16x16x32_bf16 v[8:11], v[184:187], v[238:241], v[8:11]
	v_mfma_f32_16x16x32_bf16 v[8:11], v[188:191], v[242:245], v[8:11]
	v_mfma_f32_16x16x32_bf16 v[24:27], v[184:187], v[230:233], v[24:27]
	v_mfma_f32_16x16x32_bf16 v[24:27], v[188:191], v[234:237], v[24:27]
	v_mfma_f32_16x16x32_bf16 v[40:43], v[184:187], v[200:203], v[40:43]
	v_mfma_f32_16x16x32_bf16 v[40:43], v[188:191], v[204:207], v[40:43]
	v_mfma_f32_16x16x32_bf16 v[56:59], v[184:187], v[192:195], v[56:59]
	v_mfma_f32_16x16x32_bf16 v[56:59], v[188:191], v[196:199], v[56:59]
	s_setprio 0
	s_barrier
	s_add_i32 s79, 0, 0x1c000
	v_add_u32_e32 v148, s91, v162
	v_add_u32_e32 v171, s79, v162
	ds_read_b128 v[136:139], v148
	ds_read_b128 v[140:143], v148 offset:1024
	ds_read_b128 v[144:147], v148 offset:2048
	ds_read_b128 v[148:151], v148 offset:3072
	ds_read_b128 v[172:175], v171
	ds_read_b128 v[176:179], v171 offset:1024
	ds_read_b128 v[184:187], v171 offset:2048
	ds_read_b128 v[188:191], v171 offset:3072
	s_add_u32 s38, s38, s48
	s_addc_u32 s39, s39, s49
	s_mov_b32 m0, s52
	v_lshl_add_u64 v[248:249], s[38:39], 0, v[156:157]
	ds_read_b128 v[192:195], v167 offset:32768
	ds_read_b128 v[196:199], v167 offset:33792
	ds_read_b128 v[200:203], v167 offset:34816
	ds_read_b128 v[204:207], v167 offset:35840
	ds_read_b128 v[230:233], v167 offset:36864
	ds_read_b128 v[234:237], v167 offset:37888
	ds_read_b128 v[238:241], v167 offset:38912
	ds_read_b128 v[242:245], v167 offset:39936
	global_load_lds_dwordx4 v[248:249], off
	v_lshl_add_u64 v[248:249], s[38:39], 0, v[152:153]
	s_mov_b32 m0, s53
	s_nop 0
	global_load_lds_dwordx4 v[248:249], off
	s_waitcnt vmcnt(8)
	s_waitcnt lgkmcnt(0)
	s_barrier
	s_setprio 1
	s_waitcnt lgkmcnt(0)
	v_mfma_f32_16x16x32_bf16 v[132:135], v[136:139], v[192:195], v[132:135]
	v_mfma_f32_16x16x32_bf16 v[132:135], v[140:143], v[196:199], v[132:135]
	v_mfma_f32_16x16x32_bf16 v[116:119], v[136:139], v[200:203], v[116:119]
	v_mfma_f32_16x16x32_bf16 v[116:119], v[140:143], v[204:207], v[116:119]
	v_mfma_f32_16x16x32_bf16 v[100:103], v[136:139], v[230:233], v[100:103]
	v_mfma_f32_16x16x32_bf16 v[100:103], v[140:143], v[234:237], v[100:103]
	v_mfma_f32_16x16x32_bf16 v[84:87], v[136:139], v[238:241], v[84:87]
	v_mfma_f32_16x16x32_bf16 v[84:87], v[140:143], v[242:245], v[84:87]
	v_mfma_f32_16x16x32_bf16 v[80:83], v[144:147], v[238:241], v[80:83]
	v_mfma_f32_16x16x32_bf16 v[80:83], v[148:151], v[242:245], v[80:83]
	v_mfma_f32_16x16x32_bf16 v[96:99], v[144:147], v[230:233], v[96:99]
	v_mfma_f32_16x16x32_bf16 v[96:99], v[148:151], v[234:237], v[96:99]
	v_mfma_f32_16x16x32_bf16 v[112:115], v[144:147], v[200:203], v[112:115]
	v_mfma_f32_16x16x32_bf16 v[112:115], v[148:151], v[204:207], v[112:115]
	v_mfma_f32_16x16x32_bf16 v[128:131], v[144:147], v[192:195], v[128:131]
	v_mfma_f32_16x16x32_bf16 v[128:131], v[148:151], v[196:199], v[128:131]
	s_setprio 0
	s_setprio 1
	v_mfma_f32_16x16x32_bf16 v[124:127], v[172:175], v[192:195], v[124:127]
	v_mfma_f32_16x16x32_bf16 v[124:127], v[176:179], v[196:199], v[124:127]
	v_mfma_f32_16x16x32_bf16 v[108:111], v[172:175], v[200:203], v[108:111]
	v_mfma_f32_16x16x32_bf16 v[108:111], v[176:179], v[204:207], v[108:111]
	v_mfma_f32_16x16x32_bf16 v[92:95], v[172:175], v[230:233], v[92:95]
	v_mfma_f32_16x16x32_bf16 v[92:95], v[176:179], v[234:237], v[92:95]
	v_mfma_f32_16x16x32_bf16 v[76:79], v[172:175], v[238:241], v[76:79]
	v_mfma_f32_16x16x32_bf16 v[76:79], v[176:179], v[242:245], v[76:79]
	v_mfma_f32_16x16x32_bf16 v[72:75], v[184:187], v[238:241], v[72:75]
	v_mfma_f32_16x16x32_bf16 v[72:75], v[188:191], v[242:245], v[72:75]
	v_mfma_f32_16x16x32_bf16 v[88:91], v[184:187], v[230:233], v[88:91]
	v_mfma_f32_16x16x32_bf16 v[88:91], v[188:191], v[234:237], v[88:91]
	v_mfma_f32_16x16x32_bf16 v[104:107], v[184:187], v[200:203], v[104:107]
	v_mfma_f32_16x16x32_bf16 v[104:107], v[188:191], v[204:207], v[104:107]
	v_mfma_f32_16x16x32_bf16 v[120:123], v[184:187], v[192:195], v[120:123]
	v_mfma_f32_16x16x32_bf16 v[120:123], v[188:191], v[196:199], v[120:123]
	s_setprio 0
	s_barrier
; #define PG8_STAGE(bufoff, gbase, voff) do { _Pragma("unroll") for (int _i = 0; _i < 2; ++_i) \
;         __builtin_amdgcn_global_load_lds((const unsigned*)((const char*)(gbase) + (voff)[_i]), (PG8_LAS unsigned*)(lds + (bufoff) + ldsw + _i * 8192), 16, 0, 0); } while (0)
; #define PG8_LDA(dst, b, h) do { _Pragma("unroll") for (int m = 0; m < 4; ++m) _Pragma("unroll") for (int k = 0; k < 2; ++k) dst[m][k] = *(const PG8_LAS bf16x8*)(lds + PG8_SA(b, h) + aoff + m * 2048 + k * 1024); } while (0)
; #define PG8_MMA(ai, bj, At, Bt) do { __builtin_amdgcn_s_setprio(1); _Pragma("unroll") for (int m = 0; m < 4; ++m) _Pragma("unroll") for (int n = 0; n < 2; ++n) _Pragma("unroll") for (int k = 0; k < 2; ++k) \
;         acc[ai][bj][m][n] = __builtin_amdgcn_mfma_f32_16x16x32_bf16(Bt[n][k], At[m][k], acc[ai][bj][m][n], 0, 0, 0); __builtin_amdgcn_s_setprio(0); } while (0)
; #define PG8_WAIT_V(n) asm volatile("s_waitcnt vmcnt(" #n ")" ::: "memory")
; #define PG8_WAIT_L(n) asm volatile("s_waitcnt lgkmcnt(" #n ")" ::: "memory")
; #define PG8_BAR __builtin_amdgcn_s_barrier()
; #define PG8_SCHED __builtin_amdgcn_sched_barrier(0)
; template <class Epi, class Sched, bool ALIGN_EPI = false, bool SP2 = false>
; __device__ __forceinline__ void gemm_phase(PG8_LAS unsigned char* lds, const Gemm g, const Sched& S, const Epi& E) {
;     ...
;             PG8_LDA(At, 1, 1); PG8_STAGE(PG8_SB(1, 0), b3, voffB); PG8_STAGE(PG8_SB(1, 1), b3 + hstep, voffB); PG8_STAGE(PG8_SA(1, 0), a3, voffA);
;             PG8_WAIT_V(8); PG8_WAIT_L(0); PG8_BAR; PG8_MMA(1, 0, At, B0); PG8_MMA(1, 1, At, B1); PG8_BAR; PG8_SCHED;
	s_add_i32 s38, s91, s42
	v_lshl_add_u64 v[180:181], v[180:181], 0, s[24:25]
	s_mov_b32 m0, s38
	ds_read_b128 v[192:195], v167 offset:49152
	ds_read_b128 v[196:199], v167 offset:50176
	ds_read_b128 v[200:203], v167 offset:51200
	ds_read_b128 v[204:207], v167 offset:52224
	ds_read_b128 v[230:233], v167 offset:53248
	ds_read_b128 v[234:237], v167 offset:54272
	ds_read_b128 v[238:241], v167 offset:55296
	ds_read_b128 v[242:245], v167 offset:56320
	global_load_lds_dwordx4 v[180:181], off
	v_lshl_add_u64 v[180:181], v[208:209], 0, s[24:25]
	s_add_i32 m0, s38, 0x2000
	s_add_i32 s38, s79, s42
	global_load_lds_dwordx4 v[180:181], off
	v_lshl_add_u64 v[180:181], v[216:217], 0, s[24:25]
	s_mov_b32 m0, s38
	s_nop 0
	global_load_lds_dwordx4 v[180:181], off
	v_lshl_add_u64 v[180:181], v[224:225], 0, s[24:25]
	s_add_i32 m0, s38, 0x2000
	s_nop 0
	global_load_lds_dwordx4 v[180:181], off
	v_lshl_add_u64 v[180:181], v[226:227], 0, s[24:25]
	s_mov_b32 m0, s72
	s_nop 0
	global_load_lds_dwordx4 v[180:181], off
	v_lshl_add_u64 v[180:181], v[246:247], 0, s[24:25]
	s_mov_b32 m0, s73
	s_nop 0
	global_load_lds_dwordx4 v[180:181], off
	s_waitcnt vmcnt(8)
	s_waitcnt lgkmcnt(0)
	s_barrier
	s_setprio 1
	s_waitcnt lgkmcnt(0)
	v_mfma_f32_16x16x32_bf16 v[68:71], v[136:139], v[192:195], v[68:71]
	v_mfma_f32_16x16x32_bf16 v[68:71], v[140:143], v[196:199], v[68:71]
	v_mfma_f32_16x16x32_bf16 v[52:55], v[136:139], v[200:203], v[52:55]
	v_mfma_f32_16x16x32_bf16 v[52:55], v[140:143], v[204:207], v[52:55]
	v_mfma_f32_16x16x32_bf16 v[36:39], v[136:139], v[230:233], v[36:39]
	v_mfma_f32_16x16x32_bf16 v[36:39], v[140:143], v[234:237], v[36:39]
	v_mfma_f32_16x16x32_bf16 v[20:23], v[136:139], v[238:241], v[20:23]
	v_mfma_f32_16x16x32_bf16 v[20:23], v[140:143], v[242:245], v[20:23]
	v_mfma_f32_16x16x32_bf16 v[16:19], v[144:147], v[238:241], v[16:19]
	v_mfma_f32_16x16x32_bf16 v[16:19], v[148:151], v[242:245], v[16:19]
	v_mfma_f32_16x16x32_bf16 v[32:35], v[144:147], v[230:233], v[32:35]
	v_mfma_f32_16x16x32_bf16 v[32:35], v[148:151], v[234:237], v[32:35]
	v_mfma_f32_16x16x32_bf16 v[48:51], v[144:147], v[200:203], v[48:51]
	v_mfma_f32_16x16x32_bf16 v[48:51], v[148:151], v[204:207], v[48:51]
	v_mfma_f32_16x16x32_bf16 v[64:67], v[144:147], v[192:195], v[64:67]
	v_mfma_f32_16x16x32_bf16 v[64:67], v[148:151], v[196:199], v[64:67]
	s_setprio 0
	s_setprio 1
	v_mfma_f32_16x16x32_bf16 v[60:63], v[172:175], v[192:195], v[60:63]
	v_mfma_f32_16x16x32_bf16 v[60:63], v[176:179], v[196:199], v[60:63]
	v_mfma_f32_16x16x32_bf16 v[44:47], v[172:175], v[200:203], v[44:47]
	v_mfma_f32_16x16x32_bf16 v[44:47], v[176:179], v[204:207], v[44:47]
	v_mfma_f32_16x16x32_bf16 v[28:31], v[172:175], v[230:233], v[28:31]
	v_mfma_f32_16x16x32_bf16 v[28:31], v[176:179], v[234:237], v[28:31]
	v_mfma_f32_16x16x32_bf16 v[12:15], v[172:175], v[238:241], v[12:15]
	v_mfma_f32_16x16x32_bf16 v[12:15], v[176:179], v[242:245], v[12:15]
	v_mfma_f32_16x16x32_bf16 v[8:11], v[184:187], v[238:241], v[8:11]
	v_mfma_f32_16x16x32_bf16 v[8:11], v[188:191], v[242:245], v[8:11]
	v_mfma_f32_16x16x32_bf16 v[24:27], v[184:187], v[230:233], v[24:27]
	v_mfma_f32_16x16x32_bf16 v[24:27], v[188:191], v[234:237], v[24:27]
	v_mfma_f32_16x16x32_bf16 v[40:43], v[184:187], v[200:203], v[40:43]
	v_mfma_f32_16x16x32_bf16 v[40:43], v[188:191], v[204:207], v[40:43]
	v_mfma_f32_16x16x32_bf16 v[56:59], v[184:187], v[192:195], v[56:59]
	v_mfma_f32_16x16x32_bf16 v[56:59], v[188:191], v[196:199], v[56:59]
	s_setprio 0
	s_barrier
	s_add_u32 s0, s0, 0x100
	s_addc_u32 s1, s1, 0
	s_add_u32 s40, s40, 0x100
	s_addc_u32 s41, s41, 0
	s_cmp_ge_u32 s78, s9
	s_mov_b32 s38, s78
	s_cbranch_scc0 .LBB0_468

; #define PG8_STAGE(bufoff, gbase, voff) do { _Pragma("unroll") for (int _i = 0; _i < 2; ++_i) \
;         __builtin_amdgcn_global_load_lds((const unsigned*)((const char*)(gbase) + (voff)[_i]), (PG8_LAS unsigned*)(lds + (bufoff) + ldsw + _i * 8192), 16, 0, 0); } while (0)
; #define PG8_LDA(dst, b, h) do { _Pragma("unroll") for (int m = 0; m < 4; ++m) _Pragma("unroll") for (int k = 0; k < 2; ++k) dst[m][k] = *(const PG8_LAS bf16x8*)(lds + PG8_SA(b, h) + aoff + m * 2048 + k * 1024); } while (0)
; #define PG8_LDB(dst, b, h) do { _Pragma("unroll") for (int n = 0; n < 2; ++n) _Pragma("unroll") for (int k = 0; k < 2; ++k) dst[n][k] = *(const PG8_LAS bf16x8*)(lds + PG8_SB(b, h) + boff + n * 2048 + k * 1024); } while (0)
; #define PG8_MMA(ai, bj, At, Bt) do { __builtin_amdgcn_s_setprio(1); _Pragma("unroll") for (int m = 0; m < 4; ++m) _Pragma("unroll") for (int n = 0; n < 2; ++n) _Pragma("unroll") for (int k = 0; k < 2; ++k) \
;         acc[ai][bj][m][n] = __builtin_amdgcn_mfma_f32_16x16x32_bf16(Bt[n][k], At[m][k], acc[ai][bj][m][n], 0, 0, 0); __builtin_amdgcn_s_setprio(0); } while (0)
; #define PG8_WAIT_V(n) asm volatile("s_waitcnt vmcnt(" #n ")" ::: "memory")
; #define PG8_WAIT_L(n) asm volatile("s_waitcnt lgkmcnt(" #n ")" ::: "memory")
; #define PG8_BAR __builtin_amdgcn_s_barrier()
; #define PG8_SCHED __builtin_amdgcn_sched_barrier(0)
; template <class Epi, class Sched, bool ALIGN_EPI = false, bool SP2 = false>
; __device__ __forceinline__ void gemm_phase(PG8_LAS unsigned char* lds, const Gemm g, const Sched& S, const Epi& E) {
;     ...
;             const bool last = (t == nt - 2);
;             const char* a1 = cA + (size_t)(t + 1) * kstep;
;             const char* a2 = last ? nA : cA + (size_t)(t + 2) * kstep; const char* b2 = last ? nB : cB + (size_t)(t + 2) * kstep;
;             const char* a3 = a2 + kstep; const char* b3 = b2 + kstep;
;             if (last && has_next) S.a_ready(nxt);
;             if constexpr (SP2) {
;             PG8_LDB(B0, 0, 0); PG8_LDB(B1, 0, 1); PG8_SCHED; PG8_LDA(At, 0, 0); PG8_STAGE(PG8_SA(1, 1), a1 + hstep, voffA);
;             PG8_WAIT_V(8); PG8_WAIT_L(0); PG8_BAR; PG8_MMA(0, 0, At, B0); PG8_MMA(0, 1, At, B1); PG8_BAR; PG8_SCHED;
;             PG8_LDA(At, 0, 1); PG8_STAGE(PG8_SB(0, 0), b2, voffB); PG8_STAGE(PG8_SB(0, 1), b2 + hstep, voffB); PG8_STAGE(PG8_SA(0, 0), a2, voffA);
.LBB0_501:
	s_add_i32 s80, s4, 2
	s_add_u32 s81, s0, 0x80
	s_addc_u32 s5, s1, 0
	s_cmp_eq_u32 s33, s4
	s_cselect_b32 s5, s23, s5
	s_cselect_b32 s4, s22, s81
	s_cselect_b32 s83, s41, s43
	s_cselect_b32 s82, s40, s42
	s_add_i32 s81, 0, 0x14000
	v_add_u32_e32 v148, s19, v164
	v_add_u32_e32 v162, s81, v164
	ds_read_b128 v[136:139], v148
	ds_read_b128 v[140:143], v148 offset:1024
	ds_read_b128 v[144:147], v148 offset:2048
	ds_read_b128 v[148:151], v148 offset:3072
	ds_read_b128 v[174:177], v162
	ds_read_b128 v[178:181], v162 offset:1024
	ds_read_b128 v[184:187], v162 offset:2048
	ds_read_b128 v[188:191], v162 offset:3072
	v_lshl_add_u64 v[162:163], s[0:1], 0, v[158:159]
	s_add_i32 m0, s45, 0xc000
	ds_read_b128 v[192:195], v170
	ds_read_b128 v[196:199], v170 offset:1024
	ds_read_b128 v[200:203], v170 offset:2048
	ds_read_b128 v[204:207], v170 offset:3072
	ds_read_b128 v[230:233], v170 offset:4096
	ds_read_b128 v[234:237], v170 offset:5120
	ds_read_b128 v[238:241], v170 offset:6144
	ds_read_b128 v[242:245], v170 offset:7168
	global_load_lds_dwordx4 v[162:163], off
	v_lshl_add_u64 v[162:163], s[0:1], 0, v[160:161]
	s_add_i32 m0, s45, 0xe000
	s_nop 0
	global_load_lds_dwordx4 v[162:163], off
	s_waitcnt vmcnt(8)
	s_waitcnt lgkmcnt(0)
	s_barrier
	s_setprio 1
	s_waitcnt lgkmcnt(0)
	v_mfma_f32_16x16x32_bf16 v[132:135], v[136:139], v[192:195], v[132:135]
	v_mfma_f32_16x16x32_bf16 v[132:135], v[140:143], v[196:199], v[132:135]
	v_mfma_f32_16x16x32_bf16 v[116:119], v[136:139], v[200:203], v[116:119]
	v_mfma_f32_16x16x32_bf16 v[116:119], v[140:143], v[204:207], v[116:119]
	v_mfma_f32_16x16x32_bf16 v[100:103], v[136:139], v[230:233], v[100:103]
	v_mfma_f32_16x16x32_bf16 v[100:103], v[140:143], v[234:237], v[100:103]
	v_mfma_f32_16x16x32_bf16 v[84:87], v[136:139], v[238:241], v[84:87]
	v_mfma_f32_16x16x32_bf16 v[84:87], v[140:143], v[242:245], v[84:87]
	v_mfma_f32_16x16x32_bf16 v[80:83], v[144:147], v[238:241], v[80:83]
	v_mfma_f32_16x16x32_bf16 v[80:83], v[148:151], v[242:245], v[80:83]
	v_mfma_f32_16x16x32_bf16 v[96:99], v[144:147], v[230:233], v[96:99]
	v_mfma_f32_16x16x32_bf16 v[96:99], v[148:151], v[234:237], v[96:99]
	v_mfma_f32_16x16x32_bf16 v[112:115], v[144:147], v[200:203], v[112:115]
	v_mfma_f32_16x16x32_bf16 v[112:115], v[148:151], v[204:207], v[112:115]
	v_mfma_f32_16x16x32_bf16 v[128:131], v[144:147], v[192:195], v[128:131]
	v_mfma_f32_16x16x32_bf16 v[128:131], v[148:151], v[196:199], v[128:131]
	s_setprio 0
	s_setprio 1
	v_mfma_f32_16x16x32_bf16 v[124:127], v[174:177], v[192:195], v[124:127]
	v_mfma_f32_16x16x32_bf16 v[124:127], v[178:181], v[196:199], v[124:127]
	v_mfma_f32_16x16x32_bf16 v[108:111], v[174:177], v[200:203], v[108:111]
	v_mfma_f32_16x16x32_bf16 v[108:111], v[178:181], v[204:207], v[108:111]
	v_mfma_f32_16x16x32_bf16 v[92:95], v[174:177], v[230:233], v[92:95]
	v_mfma_f32_16x16x32_bf16 v[92:95], v[178:181], v[234:237], v[92:95]
	v_mfma_f32_16x16x32_bf16 v[76:79], v[174:177], v[238:241], v[76:79]
	v_mfma_f32_16x16x32_bf16 v[76:79], v[178:181], v[242:245], v[76:79]
	v_mfma_f32_16x16x32_bf16 v[72:75], v[184:187], v[238:241], v[72:75]
	v_mfma_f32_16x16x32_bf16 v[72:75], v[188:191], v[242:245], v[72:75]
	v_mfma_f32_16x16x32_bf16 v[88:91], v[184:187], v[230:233], v[88:91]
	v_mfma_f32_16x16x32_bf16 v[88:91], v[188:191], v[234:237], v[88:91]
	v_mfma_f32_16x16x32_bf16 v[104:107], v[184:187], v[200:203], v[104:107]
	v_mfma_f32_16x16x32_bf16 v[104:107], v[188:191], v[204:207], v[104:107]
	v_mfma_f32_16x16x32_bf16 v[120:123], v[184:187], v[192:195], v[120:123]
	v_mfma_f32_16x16x32_bf16 v[120:123], v[188:191], v[196:199], v[120:123]
	s_setprio 0
	s_barrier
	s_add_i32 s84, s19, s44
	v_lshl_add_u64 v[162:163], s[82:83], 0, v[152:153]
	s_mov_b32 m0, s84
	ds_read_b128 v[192:195], v170 offset:16384
	ds_read_b128 v[196:199], v170 offset:17408
	ds_read_b128 v[200:203], v170 offset:18432
	ds_read_b128 v[204:207], v170 offset:19456
	ds_read_b128 v[230:233], v170 offset:20480
	ds_read_b128 v[234:237], v170 offset:21504
	ds_read_b128 v[238:241], v170 offset:22528
	ds_read_b128 v[242:245], v170 offset:23552
	global_load_lds_dwordx4 v[162:163], off
	s_add_i32 m0, s84, 0x2000
	v_lshl_add_u64 v[208:209], s[82:83], 0, v[156:157]
	s_add_u32 s82, s82, s48
	s_addc_u32 s83, s83, s49
	s_add_i32 s81, s81, s44
	global_load_lds_dwordx4 v[208:209], off
	v_lshl_add_u64 v[246:247], s[82:83], 0, v[152:153]
	s_mov_b32 m0, s81
	v_lshl_add_u64 v[248:249], s[82:83], 0, v[156:157]
	global_load_lds_dwordx4 v[246:247], off
	s_add_i32 m0, s81, 0x2000
	v_lshl_add_u64 v[216:217], s[4:5], 0, v[2:3]
	global_load_lds_dwordx4 v[248:249], off
	s_mov_b32 m0, s45
	v_lshl_add_u64 v[224:225], s[4:5], 0, v[154:155]
	global_load_lds_dwordx4 v[216:217], off
	s_mov_b32 m0, s46
	s_nop 0
	global_load_lds_dwordx4 v[224:225], off
	s_waitcnt vmcnt(8)
	s_waitcnt lgkmcnt(0)
	s_barrier
; #define PG8_STAGE(bufoff, gbase, voff) do { _Pragma("unroll") for (int _i = 0; _i < 2; ++_i) \
;         __builtin_amdgcn_global_load_lds((const unsigned*)((const char*)(gbase) + (voff)[_i]), (PG8_LAS unsigned*)(lds + (bufoff) + ldsw + _i * 8192), 16, 0, 0); } while (0)
; #define PG8_LDA(dst, b, h) do { _Pragma("unroll") for (int m = 0; m < 4; ++m) _Pragma("unroll") for (int k = 0; k < 2; ++k) dst[m][k] = *(const PG8_LAS bf16x8*)(lds + PG8_SA(b, h) + aoff + m * 2048 + k * 1024); } while (0)
; #define PG8_LDB(dst, b, h) do { _Pragma("unroll") for (int n = 0; n < 2; ++n) _Pragma("unroll") for (int k = 0; k < 2; ++k) dst[n][k] = *(const PG8_LAS bf16x8*)(lds + PG8_SB(b, h) + boff + n * 2048 + k * 1024); } while (0)
; #define PG8_MMA(ai, bj, At, Bt) do { __builtin_amdgcn_s_setprio(1); _Pragma("unroll") for (int m = 0; m < 4; ++m) _Pragma("unroll") for (int n = 0; n < 2; ++n) _Pragma("unroll") for (int k = 0; k < 2; ++k) \
;         acc[ai][bj][m][n] = __builtin_amdgcn_mfma_f32_16x16x32_bf16(Bt[n][k], At[m][k], acc[ai][bj][m][n], 0, 0, 0); __builtin_amdgcn_s_setprio(0); } while (0)
; #define PG8_WAIT_V(n) asm volatile("s_waitcnt vmcnt(" #n ")" ::: "memory")
; #define PG8_WAIT_L(n) asm volatile("s_waitcnt lgkmcnt(" #n ")" ::: "memory")
; #define PG8_BAR __builtin_amdgcn_s_barrier()
; #define PG8_SCHED __builtin_amdgcn_sched_barrier(0)
; template <class Epi, class Sched, bool ALIGN_EPI = false, bool SP2 = false>
; __device__ __forceinline__ void gemm_phase(PG8_LAS unsigned char* lds, const Gemm g, const Sched& S, const Epi& E) {
;     ...
;             PG8_WAIT_V(8); PG8_WAIT_L(0); PG8_BAR; PG8_MMA(1, 0, At, B0); PG8_MMA(1, 1, At, B1); PG8_BAR; PG8_SCHED;
;             PG8_LDB(B0, 1, 0); PG8_LDB(B1, 1, 1); PG8_SCHED; PG8_LDA(At, 1, 0); PG8_STAGE(PG8_SA(0, 1), a2 + hstep, voffA);
;             PG8_WAIT_V(8); PG8_WAIT_L(0); PG8_BAR; PG8_MMA(0, 0, At, B0); PG8_MMA(0, 1, At, B1); PG8_BAR; PG8_SCHED;
	s_setprio 1
	s_waitcnt lgkmcnt(0)
	v_mfma_f32_16x16x32_bf16 v[68:71], v[136:139], v[192:195], v[68:71]
	v_mfma_f32_16x16x32_bf16 v[68:71], v[140:143], v[196:199], v[68:71]
	v_mfma_f32_16x16x32_bf16 v[52:55], v[136:139], v[200:203], v[52:55]
	v_mfma_f32_16x16x32_bf16 v[52:55], v[140:143], v[204:207], v[52:55]
	v_mfma_f32_16x16x32_bf16 v[36:39], v[136:139], v[230:233], v[36:39]
	v_mfma_f32_16x16x32_bf16 v[36:39], v[140:143], v[234:237], v[36:39]
	v_mfma_f32_16x16x32_bf16 v[20:23], v[136:139], v[238:241], v[20:23]
	v_mfma_f32_16x16x32_bf16 v[20:23], v[140:143], v[242:245], v[20:23]
	v_mfma_f32_16x16x32_bf16 v[16:19], v[144:147], v[238:241], v[16:19]
	v_mfma_f32_16x16x32_bf16 v[16:19], v[148:151], v[242:245], v[16:19]
	v_mfma_f32_16x16x32_bf16 v[32:35], v[144:147], v[230:233], v[32:35]
	v_mfma_f32_16x16x32_bf16 v[32:35], v[148:151], v[234:237], v[32:35]
	v_mfma_f32_16x16x32_bf16 v[48:51], v[144:147], v[200:203], v[48:51]
	v_mfma_f32_16x16x32_bf16 v[48:51], v[148:151], v[204:207], v[48:51]
	v_mfma_f32_16x16x32_bf16 v[64:67], v[144:147], v[192:195], v[64:67]
	v_mfma_f32_16x16x32_bf16 v[64:67], v[148:151], v[196:199], v[64:67]
	s_setprio 0
	s_setprio 1
	v_mfma_f32_16x16x32_bf16 v[60:63], v[174:177], v[192:195], v[60:63]
	v_mfma_f32_16x16x32_bf16 v[60:63], v[178:181], v[196:199], v[60:63]
	v_mfma_f32_16x16x32_bf16 v[44:47], v[174:177], v[200:203], v[44:47]
	v_mfma_f32_16x16x32_bf16 v[44:47], v[178:181], v[204:207], v[44:47]
	v_mfma_f32_16x16x32_bf16 v[28:31], v[174:177], v[230:233], v[28:31]
	v_mfma_f32_16x16x32_bf16 v[28:31], v[178:181], v[234:237], v[28:31]
	v_mfma_f32_16x16x32_bf16 v[12:15], v[174:177], v[238:241], v[12:15]
	v_mfma_f32_16x16x32_bf16 v[12:15], v[178:181], v[242:245], v[12:15]
	v_mfma_f32_16x16x32_bf16 v[8:11], v[184:187], v[238:241], v[8:11]
	v_mfma_f32_16x16x32_bf16 v[8:11], v[188:191], v[242:245], v[8:11]
	v_mfma_f32_16x16x32_bf16 v[24:27], v[184:187], v[230:233], v[24:27]
	v_mfma_f32_16x16x32_bf16 v[24:27], v[188:191], v[234:237], v[24:27]
	v_mfma_f32_16x16x32_bf16 v[40:43], v[184:187], v[200:203], v[40:43]
	v_mfma_f32_16x16x32_bf16 v[40:43], v[188:191], v[204:207], v[40:43]
	v_mfma_f32_16x16x32_bf16 v[56:59], v[184:187], v[192:195], v[56:59]
	v_mfma_f32_16x16x32_bf16 v[56:59], v[188:191], v[196:199], v[56:59]
	s_setprio 0
	s_barrier
	s_add_i32 s81, 0, 0x1c000
	v_add_u32_e32 v148, s91, v164
	v_add_u32_e32 v173, s81, v164
	ds_read_b128 v[136:139], v148
	ds_read_b128 v[140:143], v148 offset:1024
	ds_read_b128 v[144:147], v148 offset:2048
	ds_read_b128 v[148:151], v148 offset:3072
	ds_read_b128 v[174:177], v173
	ds_read_b128 v[178:181], v173 offset:1024
	ds_read_b128 v[184:187], v173 offset:2048
	ds_read_b128 v[188:191], v173 offset:3072
	s_add_u32 s4, s4, s48
	s_addc_u32 s5, s5, s49
	s_mov_b32 m0, s47
	v_lshl_add_u64 v[226:227], s[4:5], 0, v[2:3]
	ds_read_b128 v[192:195], v170 offset:32768
	ds_read_b128 v[196:199], v170 offset:33792
	ds_read_b128 v[200:203], v170 offset:34816
	ds_read_b128 v[204:207], v170 offset:35840
	ds_read_b128 v[230:233], v170 offset:36864
	ds_read_b128 v[234:237], v170 offset:37888
	ds_read_b128 v[238:241], v170 offset:38912
	ds_read_b128 v[242:245], v170 offset:39936
	global_load_lds_dwordx4 v[226:227], off
	v_lshl_add_u64 v[226:227], s[4:5], 0, v[154:155]
	s_mov_b32 m0, s52
	s_nop 0
	global_load_lds_dwordx4 v[226:227], off
	s_waitcnt vmcnt(8)
	s_waitcnt lgkmcnt(0)
	s_barrier
	s_setprio 1
	s_waitcnt lgkmcnt(0)
	v_mfma_f32_16x16x32_bf16 v[132:135], v[136:139], v[192:195], v[132:135]
	v_mfma_f32_16x16x32_bf16 v[132:135], v[140:143], v[196:199], v[132:135]
	v_mfma_f32_16x16x32_bf16 v[116:119], v[136:139], v[200:203], v[116:119]
	v_mfma_f32_16x16x32_bf16 v[116:119], v[140:143], v[204:207], v[116:119]
	v_mfma_f32_16x16x32_bf16 v[100:103], v[136:139], v[230:233], v[100:103]
	v_mfma_f32_16x16x32_bf16 v[100:103], v[140:143], v[234:237], v[100:103]
	v_mfma_f32_16x16x32_bf16 v[84:87], v[136:139], v[238:241], v[84:87]
	v_mfma_f32_16x16x32_bf16 v[84:87], v[140:143], v[242:245], v[84:87]
	v_mfma_f32_16x16x32_bf16 v[80:83], v[144:147], v[238:241], v[80:83]
	v_mfma_f32_16x16x32_bf16 v[80:83], v[148:151], v[242:245], v[80:83]
	v_mfma_f32_16x16x32_bf16 v[96:99], v[144:147], v[230:233], v[96:99]
	v_mfma_f32_16x16x32_bf16 v[96:99], v[148:151], v[234:237], v[96:99]
	v_mfma_f32_16x16x32_bf16 v[112:115], v[144:147], v[200:203], v[112:115]
	v_mfma_f32_16x16x32_bf16 v[112:115], v[148:151], v[204:207], v[112:115]
	v_mfma_f32_16x16x32_bf16 v[128:131], v[144:147], v[192:195], v[128:131]
	v_mfma_f32_16x16x32_bf16 v[128:131], v[148:151], v[196:199], v[128:131]
	s_setprio 0
	s_setprio 1
	v_mfma_f32_16x16x32_bf16 v[124:127], v[174:177], v[192:195], v[124:127]
	v_mfma_f32_16x16x32_bf16 v[124:127], v[178:181], v[196:199], v[124:127]
	v_mfma_f32_16x16x32_bf16 v[108:111], v[174:177], v[200:203], v[108:111]
	v_mfma_f32_16x16x32_bf16 v[108:111], v[178:181], v[204:207], v[108:111]
	v_mfma_f32_16x16x32_bf16 v[92:95], v[174:177], v[230:233], v[92:95]
	v_mfma_f32_16x16x32_bf16 v[92:95], v[178:181], v[234:237], v[92:95]
	v_mfma_f32_16x16x32_bf16 v[76:79], v[174:177], v[238:241], v[76:79]
	v_mfma_f32_16x16x32_bf16 v[76:79], v[178:181], v[242:245], v[76:79]
	v_mfma_f32_16x16x32_bf16 v[72:75], v[184:187], v[238:241], v[72:75]
	v_mfma_f32_16x16x32_bf16 v[72:75], v[188:191], v[242:245], v[72:75]
	v_mfma_f32_16x16x32_bf16 v[88:91], v[184:187], v[230:233], v[88:91]
	v_mfma_f32_16x16x32_bf16 v[88:91], v[188:191], v[234:237], v[88:91]
	v_mfma_f32_16x16x32_bf16 v[104:107], v[184:187], v[200:203], v[104:107]
	v_mfma_f32_16x16x32_bf16 v[104:107], v[188:191], v[204:207], v[104:107]
	v_mfma_f32_16x16x32_bf16 v[120:123], v[184:187], v[192:195], v[120:123]
	v_mfma_f32_16x16x32_bf16 v[120:123], v[188:191], v[196:199], v[120:123]
	s_setprio 0
	s_barrier
; #define PG8_STAGE(bufoff, gbase, voff) do { _Pragma("unroll") for (int _i = 0; _i < 2; ++_i) \
;         __builtin_amdgcn_global_load_lds((const unsigned*)((const char*)(gbase) + (voff)[_i]), (PG8_LAS unsigned*)(lds + (bufoff) + ldsw + _i * 8192), 16, 0, 0); } while (0)
; #define PG8_LDA(dst, b, h) do { _Pragma("unroll") for (int m = 0; m < 4; ++m) _Pragma("unroll") for (int k = 0; k < 2; ++k) dst[m][k] = *(const PG8_LAS bf16x8*)(lds + PG8_SA(b, h) + aoff + m * 2048 + k * 1024); } while (0)
; #define PG8_MMA(ai, bj, At, Bt) do { __builtin_amdgcn_s_setprio(1); _Pragma("unroll") for (int m = 0; m < 4; ++m) _Pragma("unroll") for (int n = 0; n < 2; ++n) _Pragma("unroll") for (int k = 0; k < 2; ++k) \
;         acc[ai][bj][m][n] = __builtin_amdgcn_mfma_f32_16x16x32_bf16(Bt[n][k], At[m][k], acc[ai][bj][m][n], 0, 0, 0); __builtin_amdgcn_s_setprio(0); } while (0)
; #define PG8_WAIT_V(n) asm volatile("s_waitcnt vmcnt(" #n ")" ::: "memory")
; #define PG8_WAIT_L(n) asm volatile("s_waitcnt lgkmcnt(" #n ")" ::: "memory")
; #define PG8_BAR __builtin_amdgcn_s_barrier()
; #define PG8_SCHED __builtin_amdgcn_sched_barrier(0)
; template <class Epi, class Sched, bool ALIGN_EPI = false, bool SP2 = false>
; __device__ __forceinline__ void gemm_phase(PG8_LAS unsigned char* lds, const Gemm g, const Sched& S, const Epi& E) {
;     ...
;             PG8_LDA(At, 1, 1); PG8_STAGE(PG8_SB(1, 0), b3, voffB); PG8_STAGE(PG8_SB(1, 1), b3 + hstep, voffB); PG8_STAGE(PG8_SA(1, 0), a3, voffA);
;             PG8_WAIT_V(8); PG8_WAIT_L(0); PG8_BAR; PG8_MMA(1, 0, At, B0); PG8_MMA(1, 1, At, B1); PG8_BAR; PG8_SCHED;
	s_add_i32 s4, s91, s44
	v_lshl_add_u64 v[162:163], v[162:163], 0, s[24:25]
	s_mov_b32 m0, s4
	ds_read_b128 v[192:195], v170 offset:49152
	ds_read_b128 v[196:199], v170 offset:50176
	ds_read_b128 v[200:203], v170 offset:51200
	ds_read_b128 v[204:207], v170 offset:52224
	ds_read_b128 v[230:233], v170 offset:53248
	ds_read_b128 v[234:237], v170 offset:54272
	ds_read_b128 v[238:241], v170 offset:55296
	ds_read_b128 v[242:245], v170 offset:56320
	global_load_lds_dwordx4 v[162:163], off
	v_lshl_add_u64 v[162:163], v[208:209], 0, s[24:25]
	s_add_i32 m0, s4, 0x2000
	s_add_i32 s4, s81, s44
	global_load_lds_dwordx4 v[162:163], off
	v_lshl_add_u64 v[162:163], v[246:247], 0, s[24:25]
	s_mov_b32 m0, s4
	s_nop 0
	global_load_lds_dwordx4 v[162:163], off
	v_lshl_add_u64 v[162:163], v[248:249], 0, s[24:25]
	s_add_i32 m0, s4, 0x2000
	s_nop 0
	global_load_lds_dwordx4 v[162:163], off
	v_lshl_add_u64 v[162:163], v[216:217], 0, s[24:25]
	s_mov_b32 m0, s53
	s_nop 0
	global_load_lds_dwordx4 v[162:163], off
	v_lshl_add_u64 v[162:163], v[224:225], 0, s[24:25]
	s_mov_b32 m0, s72
	s_nop 0
	global_load_lds_dwordx4 v[162:163], off
	s_waitcnt vmcnt(8)
	s_waitcnt lgkmcnt(0)
	s_barrier
	s_setprio 1
	s_waitcnt lgkmcnt(0)
	v_mfma_f32_16x16x32_bf16 v[68:71], v[136:139], v[192:195], v[68:71]
	v_mfma_f32_16x16x32_bf16 v[68:71], v[140:143], v[196:199], v[68:71]
	v_mfma_f32_16x16x32_bf16 v[52:55], v[136:139], v[200:203], v[52:55]
	v_mfma_f32_16x16x32_bf16 v[52:55], v[140:143], v[204:207], v[52:55]
	v_mfma_f32_16x16x32_bf16 v[36:39], v[136:139], v[230:233], v[36:39]
	v_mfma_f32_16x16x32_bf16 v[36:39], v[140:143], v[234:237], v[36:39]
	v_mfma_f32_16x16x32_bf16 v[20:23], v[136:139], v[238:241], v[20:23]
	v_mfma_f32_16x16x32_bf16 v[20:23], v[140:143], v[242:245], v[20:23]
	v_mfma_f32_16x16x32_bf16 v[16:19], v[144:147], v[238:241], v[16:19]
	v_mfma_f32_16x16x32_bf16 v[16:19], v[148:151], v[242:245], v[16:19]
	v_mfma_f32_16x16x32_bf16 v[32:35], v[144:147], v[230:233], v[32:35]
	v_mfma_f32_16x16x32_bf16 v[32:35], v[148:151], v[234:237], v[32:35]
	v_mfma_f32_16x16x32_bf16 v[48:51], v[144:147], v[200:203], v[48:51]
	v_mfma_f32_16x16x32_bf16 v[48:51], v[148:151], v[204:207], v[48:51]
	v_mfma_f32_16x16x32_bf16 v[64:67], v[144:147], v[192:195], v[64:67]
	v_mfma_f32_16x16x32_bf16 v[64:67], v[148:151], v[196:199], v[64:67]
	s_setprio 0
	s_setprio 1
	v_mfma_f32_16x16x32_bf16 v[60:63], v[174:177], v[192:195], v[60:63]
	v_mfma_f32_16x16x32_bf16 v[60:63], v[178:181], v[196:199], v[60:63]
	v_mfma_f32_16x16x32_bf16 v[44:47], v[174:177], v[200:203], v[44:47]
	v_mfma_f32_16x16x32_bf16 v[44:47], v[178:181], v[204:207], v[44:47]
	v_mfma_f32_16x16x32_bf16 v[28:31], v[174:177], v[230:233], v[28:31]
	v_mfma_f32_16x16x32_bf16 v[28:31], v[178:181], v[234:237], v[28:31]
	v_mfma_f32_16x16x32_bf16 v[12:15], v[174:177], v[238:241], v[12:15]
	v_mfma_f32_16x16x32_bf16 v[12:15], v[178:181], v[242:245], v[12:15]
	v_mfma_f32_16x16x32_bf16 v[8:11], v[184:187], v[238:241], v[8:11]
	v_mfma_f32_16x16x32_bf16 v[8:11], v[188:191], v[242:245], v[8:11]
	v_mfma_f32_16x16x32_bf16 v[24:27], v[184:187], v[230:233], v[24:27]
	v_mfma_f32_16x16x32_bf16 v[24:27], v[188:191], v[234:237], v[24:27]
	v_mfma_f32_16x16x32_bf16 v[40:43], v[184:187], v[200:203], v[40:43]
	v_mfma_f32_16x16x32_bf16 v[40:43], v[188:191], v[204:207], v[40:43]
	v_mfma_f32_16x16x32_bf16 v[56:59], v[184:187], v[192:195], v[56:59]
	v_mfma_f32_16x16x32_bf16 v[56:59], v[188:191], v[196:199], v[56:59]
	s_setprio 0
	s_barrier
	s_add_u32 s0, s0, 0x100
	s_addc_u32 s1, s1, 0
	s_add_u32 s42, s42, 0x100
	s_addc_u32 s43, s43, 0
	s_cmp_ge_u32 s80, s9
	s_mov_b32 s4, s80
	s_cbranch_scc0 .LBB0_501
